# attention loop rewritten by hand: single-chain QK accumulate (16 fewer VALU per tile), QK(j+1) overlapped with softmax(j), unroll x2, staggered wave halves with 3-deep V ring
# speedup vs baseline: 1.0162x; 1.0162x over previous
; __device__ __forceinline__ int v_rd_base(int lane) { return ((lane & 3) << 3) | (((lane >> 2) & 3) << 6) | (((lane >> 4) & 1) << 5) | (((lane >> 5) & 1) << 8); }
; #define RAWBAR() do { asm volatile("s_waitcnt lgkmcnt(0)" ::: "memory"); __builtin_amdgcn_s_barrier(); asm volatile("" ::: "memory"); } while (0)
; #define RAWBAR() do { asm volatile("s_waitcnt lgkmcnt(0)" ::: "memory"); __builtin_amdgcn_s_barrier(); asm volatile("" ::: "memory"); } while (0)
; #define RAWBAR() do { asm volatile("s_waitcnt lgkmcnt(0)" ::: "memory"); __builtin_amdgcn_s_barrier(); asm volatile("" ::: "memory"); } while (0)
; #define RAWBAR() do { asm volatile("s_waitcnt lgkmcnt(0)" ::: "memory"); __builtin_amdgcn_s_barrier(); asm volatile("" ::: "memory"); } while (0)
; #define RAWBAR() do { asm volatile("s_waitcnt lgkmcnt(0)" ::: "memory"); __builtin_amdgcn_s_barrier(); asm volatile("" ::: "memory"); } while (0)
; #define RAWBAR() do { asm volatile("s_waitcnt lgkmcnt(0)" ::: "memory"); __builtin_amdgcn_s_barrier(); asm volatile("" ::: "memory"); } while (0)
; template <int MODE> ...
;     ...
;   int tid_ = threadIdx.x; asm volatile("" : "+v"(tid_));
;   const int tid = tid_, wid = tid >> 6, lane = tid & 63, r32 = lane & 31, hi = lane >> 5, g = wid >> 1, kh = wid & 1;
;   char* K_lds = lds; char* V_lds = lds + 32768; float* L_lds = (float*)(lds + 131072);
;   constexpr float C = SCALE * 1.4426950408889634f;
;   f32x16 o[8] = {}; bf16x8 qr[8]; float lsum = 0.f;
;   const bf16* Qw = Qb + (long)(g * 32 + r32) * 128 + hi * 8;
; #pragma unroll
;   for (int d0 = 0; d0 < 8; ++d0) qr[d0] = St::ld8(Qw + d0 * 16);
;   const int vb0 = (int)(uintptr_t)V_lds + v_rd_base(lane) + 2 * kh * 4096;
;   const int krow = 32 * kh + r32;
;   typedef __attribute__((address_space(3))) unsigned lds_u32;
;   const int wu = __builtin_amdgcn_readfirstlane(wid);
;   long gk[2], gv[2];
; #pragma unroll
;   for (int c = 0; c < 2; ++c) { const int q = wu + 8 * c;
;     const int r = 4 * q + (lane >> 4), pch = lane & 15; gk[c] = (long)r * 128 + ((pch ^ (r & 7)) * 8);
;     const int st = 2 * q + (lane >> 5), kk = (st >> 2) * 8 + ((lane >> 2) & 7), k = (kk & ~0xC) | ((kk & 4) << 1) | ((kk & 8) >> 1), cc = (st & 3) * 32 + (lane & 3) * 8;
;     gv[c] = (long)k * 256 + cc; }
;     ...
;   const int NT = seq / KVBLK;
;   STAGE(0, 0); asm volatile("s_waitcnt vmcnt(0)" ::: "memory"); RAWBAR();
.LBB0_1017:
	s_mov_b64 s[24:25], -1
	s_and_b64 vcc, exec, s[22:23]
	s_cbranch_vccz .LBB0_1010
	s_ashr_i32 s29, s28, 31
	s_mul_i32 s2, s40, 0x8200
	s_lshl_b64 s[22:23], s[28:29], 7
	v_mov_b32_e32 v197, v224
	s_mul_hi_i32 s3, s40, 0x8200
	s_add_u32 s2, s2, s22
	s_addc_u32 s3, s3, s23
	v_ashrrev_i32_e32 v213, 7, v197
	v_and_b32_e32 v206, 31, v197
	v_lshlrev_b32_e32 v196, 5, v213
	s_lshl_b64 s[2:3], s[2:3], 8
	v_or_b32_e32 v0, v196, v206
	s_add_u32 s34, s52, s2
	v_ashrrev_i32_e32 v1, 31, v0
	s_addc_u32 s35, s53, s3
	s_mul_i32 s26, s40, 0x820000
	v_bfe_u32 v207, v197, 5, 1
	v_lshlrev_b64 v[0:1], 8, v[0:1]
	s_mul_hi_i32 s27, s40, 0x820000
	s_add_u32 s36, s47, s26
	v_lshl_add_u64 v[0:1], s[34:35], 0, v[0:1]
	v_lshlrev_b32_e32 v194, 4, v207
	s_addc_u32 s37, s48, s27
	v_lshl_add_u64 v[0:1], v[0:1], 0, v[194:195]
	v_ashrrev_i32_e32 v8, 6, v197
	s_add_u32 s30, s49, s26
	global_load_dwordx4 v[188:191], v[0:1], off
	global_load_dwordx4 v[184:187], v[0:1], off offset:32
	global_load_dwordx4 v[180:183], v[0:1], off offset:64
	global_load_dwordx4 v[176:179], v[0:1], off offset:96
	global_load_dwordx4 v[172:175], v[0:1], off offset:128
	global_load_dwordx4 v[168:171], v[0:1], off offset:160
	global_load_dwordx4 v[164:167], v[0:1], off offset:192
	global_load_dwordx4 v[160:163], v[0:1], off offset:224
	v_readfirstlane_b32 s2, v8
	v_bfe_u32 v0, v197, 2, 2
	v_lshrrev_b32_e32 v1, 1, v197
	s_addc_u32 s31, s50, s27
	v_bfe_u32 v4, v197, 4, 2
	v_and_or_b32 v7, v1, 8, v0
	v_lshlrev_b32_e32 v0, 3, v197
	s_lshl_b32 s3, s2, 2
	s_lshl_b32 s24, s2, 1
	v_and_b32_e32 v13, 24, v0
	v_or_b32_e32 v0, s3, v4
	s_and_b32 s3, s3, -16
	s_and_b32 s25, s24, 4
	v_and_b32_e32 v2, 63, v197
	s_or_b32 s3, s3, s25
	v_lshlrev_b32_e32 v9, 3, v2
	v_lshlrev_b32_e32 v212, 4, v2
	v_or_b32_e32 v2, s3, v7
	s_add_i32 s3, s2, 8
	v_and_or_b32 v14, s24, 2, v207
	s_lshl_b32 s24, s3, 2
	s_lshl_b32 s25, s3, 1
	v_or_b32_e32 v4, s24, v4
	s_and_b32 s24, s24, -16
	s_and_b32 s33, s25, 4
	v_and_b32_e32 v6, 15, v197
	v_ashrrev_i32_e32 v1, 31, v0
	s_or_b32 s24, s24, s33
	v_and_b32_e32 v12, 0x100, v9
	v_bitop3_b32 v11, v0, v6, 7 bitop3:0x6c
	v_ashrrev_i32_e32 v5, 31, v4
	v_bitop3_b32 v15, v4, v6, 7 bitop3:0x6c
	v_or_b32_e32 v6, s24, v7
	v_and_b32_e32 v211, 1, v8
	v_and_b32_e32 v17, 24, v9
	v_lshlrev_b64 v[8:9], 8, v[0:1]
	s_lshl_b32 s24, s2, 10
	v_lshlrev_b32_e32 v10, 1, v197
	v_and_or_b32 v16, s25, 2, v207
	v_lshl_or_b32 v8, v11, 4, v8
	s_add_i32 s25, s24, 0
	v_lshlrev_b64 v[4:5], 8, v[4:5]
	v_lshlrev_b32_e32 v15, 4, v15
	v_ashrrev_i32_e32 v3, 31, v2
	v_and_b32_e32 v19, 32, v10
	v_lshl_add_u64 v[10:11], s[36:37], 0, v[8:9]
	s_mov_b32 m0, s25
	v_or_b32_e32 v4, v4, v15
	v_ashrrev_i32_e32 v7, 31, v6
	global_load_lds_dwordx4 v[10:11], off
	v_lshl_add_u64 v[128:129], v[10:11], 0, s[18:19]
	v_lshl_add_u64 v[4:5], s[36:37], 0, v[4:5]
	v_lshl_add_u64 v[130:131], v[4:5], 0, s[18:19]
	s_add_i32 m0, s25, 0x2000
	v_lshlrev_b32_e32 v1, 6, v14
	v_lshlrev_b32_e32 v10, 1, v13
	v_lshlrev_b64 v[2:3], 9, v[2:3]
	global_load_lds_dwordx4 v[4:5], off
	s_add_i32 m0, s25, 0x4000
	s_nop 0
	global_load_lds_dwordx4 v[128:129], off
	s_add_i32 m0, s25, 0x6000
	s_nop 0
	global_load_lds_dwordx4 v[130:131], off
	v_or3_b32 v4, v1, v10, v2
	v_mov_b32_e32 v5, v3
	v_lshlrev_b32_e32 v1, 6, v16
	v_lshlrev_b64 v[6:7], 9, v[6:7]
	v_lshl_add_u64 v[4:5], s[30:31], 0, v[4:5]
	s_add_i32 m0, s25, 0x8000
	v_or3_b32 v10, v1, v10, v6
	v_mov_b32_e32 v11, v7
	global_load_lds_dwordx4 v[4:5], off
	v_lshl_add_u64 v[10:11], s[30:31], 0, v[10:11]
	s_add_i32 m0, s25, 0xa000
	v_lshl_add_u64 v[4:5], v[4:5], 0, s[10:11]
	global_load_lds_dwordx4 v[10:11], off
	s_add_i32 m0, s25, 0xc000
	s_add_i32 s33, 0, 0x8000
	global_load_lds_dwordx4 v[4:5], off
	v_lshl_add_u64 v[4:5], v[10:11], 0, s[10:11]
	s_add_i32 m0, s25, 0xe000
	v_lshlrev_b32_e32 v20, 13, v211
	global_load_lds_dwordx4 v[4:5], off
	s_cmp_lg_u32 s33, -1
	v_lshl_or_b32 v1, v206, 8, v20
	s_cselect_b32 s41, s33, 0
	s_and_b32 s2, s2, 1
	v_lshlrev_b32_e32 v4, 4, v197
	v_add_u32_e32 v216, 0, v1
	s_lshl_b32 s2, s2, 6
	v_and_b32_e32 v1, 32, v197
	v_and_b32_e32 v5, 0x70, v4
	v_bitop3_b32 v225, v194, v4, s58 bitop3:0x78
	v_or3_b32 v4, s2, v1, v13
	s_and_b32 s2, s3, 1
	s_lshl_b32 s2, s2, 6
	v_or3_b32 v1, s2, v1, v13
	v_add_u32_e32 v0, 32, v0
	v_and_b32_e32 v18, 0xc0, v212
	s_waitcnt vmcnt(0)
	v_lshl_or_b32 v6, v1, 1, v6
	v_ashrrev_i32_e32 v1, 31, v0
	s_waitcnt lgkmcnt(0)
	s_barrier
; __device__ __forceinline__ int v_rd_base(int lane) { return ((lane & 3) << 3) | (((lane >> 2) & 3) << 6) | (((lane >> 4) & 1) << 5) | (((lane >> 5) & 1) << 8); }
; #define RAWBAR() do { asm volatile("s_waitcnt lgkmcnt(0)" ::: "memory"); __builtin_amdgcn_s_barrier(); asm volatile("" ::: "memory"); } while (0)
; #define RAWBAR() do { asm volatile("s_waitcnt lgkmcnt(0)" ::: "memory"); __builtin_amdgcn_s_barrier(); asm volatile("" ::: "memory"); } while (0)
; #define RAWBAR() do { asm volatile("s_waitcnt lgkmcnt(0)" ::: "memory"); __builtin_amdgcn_s_barrier(); asm volatile("" ::: "memory"); } while (0)
; template <int MODE> ...
;     ...
;   f32x16 o[8] = {}; bf16x8 qr[8]; float lsum = 0.f;
;   const bf16* Qw = Qb + (long)(g * 32 + r32) * 128 + hi * 8;
; #pragma unroll
;   for (int d0 = 0; d0 < 8; ++d0) qr[d0] = St::ld8(Qw + d0 * 16);
;   const int vb0 = (int)(uintptr_t)V_lds + v_rd_base(lane) + 2 * kh * 4096;
;   const int krow = 32 * kh + r32;
;   typedef __attribute__((address_space(3))) unsigned lds_u32;
;   const int wu = __builtin_amdgcn_readfirstlane(wid);
;   long gk[2], gv[2];
; #pragma unroll
;   for (int c = 0; c < 2; ++c) { const int q = wu + 8 * c;
;     const int r = 4 * q + (lane >> 4), pch = lane & 15; gk[c] = (long)r * 128 + ((pch ^ (r & 7)) * 8);
;     const int st = 2 * q + (lane >> 5), kk = (st >> 2) * 8 + ((lane >> 2) & 7), k = (kk & ~0xC) | ((kk & 4) << 1) | ((kk & 8) >> 1), cc = (st & 3) * 32 + (lane & 3) * 8;
;     gv[c] = (long)k * 256 + cc; }
;     ...
;   const int NT = seq / KVBLK;
;   STAGE(0, 0); asm volatile("s_waitcnt vmcnt(0)" ::: "memory"); RAWBAR();
;   if (false) __builtin_amdgcn_s_setprio(1);
;   for (int j = 0; j < NT; ++j) {
;     const int buf = j & 1;
;     if (j + 1 < NT) { STAGE((j + 1) * KVBLK, buf ^ 1); }
;     const char* Kb = K_lds + buf * 16384;
;     f32x16 pe = {}, po = {};
; #pragma unroll
;     for (int d0 = 0; d0 < 8; d0 += 2) {
;       const bf16x8 k0 = *reinterpret_cast<const bf16x8*>(Kb + KSWZ(krow, (d0 * 16 + hi * 8) * 2));
;       const bf16x8 k1 = *reinterpret_cast<const bf16x8*>(Kb + KSWZ(krow, ((d0 + 1) * 16 + hi * 8) * 2));
;       pe = __builtin_amdgcn_mfma_f32_32x32x16_bf16(k0, qr[d0], pe, 0, 0, 0);
;       po = __builtin_amdgcn_mfma_f32_32x32x16_bf16(k1, qr[d0 + 1], po, 0, 0, 0); }
	v_add_u32_e32 v10, s41, v18
	v_readlane_b32 s84, v251, 28
	v_lshlrev_b64 v[0:1], 8, v[0:1]
	v_add3_u32 v10, v10, v17, v19
	v_lshl_or_b32 v2, v4, 1, v2
	v_readlane_b32 s85, v251, 29
	v_or_b32_e32 v0, v0, v15
	v_mov_b32_e32 v215, 0
	s_mov_b32 s25, 0
	v_add3_u32 v214, v10, v12, v20
	v_bitop3_b32 v223, v194, v5, 32 bitop3:0x36
	v_bitop3_b32 v222, v194, v5, 64 bitop3:0x36
	v_bitop3_b32 v221, v194, v5, s43 bitop3:0x36
	v_bitop3_b32 v220, v194, v5, s59 bitop3:0x36
	v_bitop3_b32 v219, v194, v5, s60 bitop3:0x36
	v_bitop3_b32 v218, v194, v5, s56 bitop3:0x36
	v_bitop3_b32 v217, v194, v5, s61 bitop3:0x36
	v_lshl_add_u64 v[198:199], s[84:85], 0, v[2:3]
	v_lshl_add_u64 v[200:201], s[84:85], 0, v[6:7]
	v_lshl_add_u64 v[202:203], s[6:7], 0, v[8:9]
	v_lshl_add_u64 v[204:205], s[6:7], 0, v[0:1]
	v_mov_b32_e32 v0, 0
	v_mov_b32_e32 v1, v215
	v_mov_b32_e32 v2, v215
	v_mov_b32_e32 v3, v215
	v_mov_b32_e32 v4, v215
	v_mov_b32_e32 v5, v215
	v_mov_b32_e32 v6, v215
	v_mov_b32_e32 v7, v215
	v_mov_b32_e32 v8, v215
	v_mov_b32_e32 v9, v215
	v_mov_b32_e32 v10, v215
	v_mov_b32_e32 v11, v215
	v_mov_b32_e32 v12, v215
	v_mov_b32_e32 v13, v215
	v_mov_b32_e32 v14, v215
	v_mov_b32_e32 v15, v215
	v_mov_b32_e32 v16, 0
	v_mov_b32_e32 v17, v215
	v_mov_b32_e32 v18, v215
	v_mov_b32_e32 v19, v215
	v_mov_b32_e32 v20, v215
	v_mov_b32_e32 v21, v215
	v_mov_b32_e32 v22, v215
	v_mov_b32_e32 v23, v215
	v_mov_b32_e32 v24, v215
	v_mov_b32_e32 v25, v215
	v_mov_b32_e32 v26, v215
	v_mov_b32_e32 v27, v215
	v_mov_b32_e32 v28, v215
	v_mov_b32_e32 v29, v215
	v_mov_b32_e32 v30, v215
	v_mov_b32_e32 v31, v215
	v_mov_b32_e32 v32, 0
	v_mov_b32_e32 v33, v215
	v_mov_b32_e32 v34, v215
	v_mov_b32_e32 v35, v215
	v_mov_b32_e32 v36, v215
	v_mov_b32_e32 v37, v215
	v_mov_b32_e32 v38, v215
	v_mov_b32_e32 v39, v215
	v_mov_b32_e32 v40, v215
	v_mov_b32_e32 v41, v215
	v_mov_b32_e32 v42, v215
	v_mov_b32_e32 v43, v215
	v_mov_b32_e32 v44, v215
	v_mov_b32_e32 v45, v215
	v_mov_b32_e32 v46, v215
	v_mov_b32_e32 v47, v215
	v_mov_b32_e32 v48, 0
	v_mov_b32_e32 v49, v215
	v_mov_b32_e32 v50, v215
	v_mov_b32_e32 v51, v215
	v_mov_b32_e32 v52, v215
	v_mov_b32_e32 v53, v215
	v_mov_b32_e32 v54, v215
	v_mov_b32_e32 v55, v215
	v_mov_b32_e32 v56, v215
	v_mov_b32_e32 v57, v215
	v_mov_b32_e32 v58, v215
	v_mov_b32_e32 v59, v215
	v_mov_b32_e32 v60, v215
	v_mov_b32_e32 v61, v215
	v_mov_b32_e32 v62, v215
	v_mov_b32_e32 v63, v215
	v_mov_b32_e32 v64, 0
	v_mov_b32_e32 v65, v215
	v_mov_b32_e32 v66, v215
	v_mov_b32_e32 v67, v215
	v_mov_b32_e32 v68, v215
	v_mov_b32_e32 v69, v215
	v_mov_b32_e32 v70, v215
	v_mov_b32_e32 v71, v215
	v_mov_b32_e32 v72, v215
	v_mov_b32_e32 v73, v215
	v_mov_b32_e32 v74, v215
	v_mov_b32_e32 v75, v215
	v_mov_b32_e32 v76, v215
	v_mov_b32_e32 v77, v215
	v_mov_b32_e32 v78, v215
	v_mov_b32_e32 v79, v215
	v_mov_b32_e32 v80, 0
	v_mov_b32_e32 v81, v215
	v_mov_b32_e32 v82, v215
	v_mov_b32_e32 v83, v215
	v_mov_b32_e32 v84, v215
	v_mov_b32_e32 v85, v215
	v_mov_b32_e32 v86, v215
	v_mov_b32_e32 v87, v215
	v_mov_b32_e32 v88, v215
	v_mov_b32_e32 v89, v215
	v_mov_b32_e32 v90, v215
	v_mov_b32_e32 v91, v215
	v_mov_b32_e32 v92, v215
	v_mov_b32_e32 v93, v215
	v_mov_b32_e32 v94, v215
	v_mov_b32_e32 v95, v215
	v_mov_b32_e32 v96, 0
	v_mov_b32_e32 v97, v215
	v_mov_b32_e32 v98, v215
	v_mov_b32_e32 v99, v215
	v_mov_b32_e32 v100, v215
	v_mov_b32_e32 v101, v215
	v_mov_b32_e32 v102, v215
	v_mov_b32_e32 v103, v215
	v_mov_b32_e32 v104, v215
	v_mov_b32_e32 v105, v215
	v_mov_b32_e32 v106, v215
	v_mov_b32_e32 v107, v215
	v_mov_b32_e32 v108, v215
	v_mov_b32_e32 v109, v215
	v_mov_b32_e32 v110, v215
	v_mov_b32_e32 v111, v215
	v_mov_b32_e32 v112, 0
	v_mov_b32_e32 v113, v215
	v_mov_b32_e32 v114, v215
	v_mov_b32_e32 v115, v215
	v_mov_b32_e32 v116, v215
	v_mov_b32_e32 v117, v215
	v_mov_b32_e32 v118, v215
	v_mov_b32_e32 v119, v215
	v_mov_b32_e32 v120, v215
	v_mov_b32_e32 v121, v215
	v_mov_b32_e32 v122, v215
	v_mov_b32_e32 v123, v215
	v_mov_b32_e32 v124, v215
	v_mov_b32_e32 v125, v215
	v_mov_b32_e32 v126, v215
	v_mov_b32_e32 v127, v215
	v_readlane_b32 s86, v251, 30
	v_readlane_b32 s87, v251, 31
	s_waitcnt vmcnt(0)
	v_lshl_add_u64 v[202:203], v[202:203], 0, s[18:19]
	v_lshl_add_u64 v[204:205], v[204:205], 0, s[18:19]
	v_add_u32_e32 v243, v216, v225
	v_add_u32_e32 v244, v216, v223
	ds_read_b128 v[226:229], v243
	ds_read_b128 v[230:233], v244
	s_waitcnt lgkmcnt(0)
	v_mfma_f32_32x32x16_bf16 v[144:159], v[226:229], v[188:191], 0
	v_mfma_f32_32x32x16_bf16 v[144:159], v[230:233], v[184:187], v[144:159]
	v_add_u32_e32 v243, v216, v222
	v_add_u32_e32 v244, v216, v221
	ds_read_b128 v[226:229], v243
	ds_read_b128 v[230:233], v244
	s_waitcnt lgkmcnt(0)
	v_mfma_f32_32x32x16_bf16 v[144:159], v[226:229], v[180:183], v[144:159]
	v_mfma_f32_32x32x16_bf16 v[144:159], v[230:233], v[176:179], v[144:159]
	v_add_u32_e32 v243, v216, v220
	v_add_u32_e32 v244, v216, v219
	ds_read_b128 v[226:229], v243
	ds_read_b128 v[230:233], v244
	s_waitcnt lgkmcnt(0)
	v_mfma_f32_32x32x16_bf16 v[144:159], v[226:229], v[172:175], v[144:159]
	v_mfma_f32_32x32x16_bf16 v[144:159], v[230:233], v[168:171], v[144:159]
	v_add_u32_e32 v243, v216, v218
	v_add_u32_e32 v244, v216, v217
	ds_read_b128 v[226:229], v243
	ds_read_b128 v[230:233], v244
	s_waitcnt lgkmcnt(0)
	v_mfma_f32_32x32x16_bf16 v[144:159], v[226:229], v[164:167], v[144:159]
	v_mfma_f32_32x32x16_bf16 v[144:159], v[230:233], v[160:163], v[144:159]
	s_mov_b32 s84, 0
	s_mov_b32 s85, 0x8000
	s_mov_b32 s86, 0x10000
	s_barrier
	s_cmp_lt_u32 s24, 0x1000
	s_cbranch_scc0 .LattnBpre_m0
; #define SBAR() __builtin_amdgcn_sched_barrier(0)
; #define PVR(S, DA, DB, vbase) do { S[0] = tr_read<v_rd_off(DA, 0, 0)>(vbase); S[1] = tr_read<v_rd_off(DA, 0, 1)>(vbase); S[2] = tr_read<v_rd_off(DB, 0, 0)>(vbase); S[3] = tr_read<v_rd_off(DB, 0, 1)>(vbase); \
;     S[4] = tr_read<v_rd_off(DA, 1, 0)>(vbase); S[5] = tr_read<v_rd_off(DA, 1, 1)>(vbase); S[6] = tr_read<v_rd_off(DB, 1, 0)>(vbase); S[7] = tr_read<v_rd_off(DB, 1, 1)>(vbase); } while (0)
; #define RAWBAR() do { asm volatile("s_waitcnt lgkmcnt(0)" ::: "memory"); __builtin_amdgcn_s_barrier(); asm volatile("" ::: "memory"); } while (0)
; #define RAWBAR() do { asm volatile("s_waitcnt lgkmcnt(0)" ::: "memory"); __builtin_amdgcn_s_barrier(); asm volatile("" ::: "memory"); } while (0)
; #define RAWBAR() do { asm volatile("s_waitcnt lgkmcnt(0)" ::: "memory"); __builtin_amdgcn_s_barrier(); asm volatile("" ::: "memory"); } while (0)
; #define RAWBAR() do { asm volatile("s_waitcnt lgkmcnt(0)" ::: "memory"); __builtin_amdgcn_s_barrier(); asm volatile("" ::: "memory"); } while (0)
; #define RAWBAR() do { asm volatile("s_waitcnt lgkmcnt(0)" ::: "memory"); __builtin_amdgcn_s_barrier(); asm volatile("" ::: "memory"); } while (0)
; template <int MODE> ...
;     ...
;   for (int j = 0; j < NT; ++j) {
;     const int buf = j & 1;
;     if (j + 1 < NT) { STAGE((j + 1) * KVBLK, buf ^ 1); }
;     const char* Kb = K_lds + buf * 16384;
;     f32x16 pe = {}, po = {};
; #pragma unroll
;     for (int d0 = 0; d0 < 8; d0 += 2) {
;       const bf16x8 k0 = *reinterpret_cast<const bf16x8*>(Kb + KSWZ(krow, (d0 * 16 + hi * 8) * 2));
;       const bf16x8 k1 = *reinterpret_cast<const bf16x8*>(Kb + KSWZ(krow, ((d0 + 1) * 16 + hi * 8) * 2));
;       pe = __builtin_amdgcn_mfma_f32_32x32x16_bf16(k0, qr[d0], pe, 0, 0, 0);
;       po = __builtin_amdgcn_mfma_f32_32x32x16_bf16(k1, qr[d0 + 1], po, 0, 0, 0); }
;     const int vo = vb0 + buf * 32768;
;     s16x4 R0_[8], R1_[8];
;     PVR(R0_, 0, 1, vo);
;     f32x16 p;
; #pragma unroll
;     for (int r = 0; r < 16; ++r) p[r] = __builtin_amdgcn_exp2f(fmaf(pe[r] + po[r], C, negMc));
;     float ps = 0.f;
; #pragma unroll
;     for (int r = 0; r < 16; ++r) ps += p[r];
;     lsum += ps;
;     const bf16x8 own0 = pk8(p, 0), own1 = pk8(p, 8);
;     SBAR();
;     PV_TAIL4(o, vo, vo + 16384, own0, own1);
;     asm volatile("s_waitcnt vmcnt(0)" ::: "memory");
;     RAWBAR();
;   }
.LBB0_1019:
	v_add_u32_e32 v242, 0x4000, v216
	v_add_u32_e32 v243, v242, v225
	v_add_u32_e32 v244, v242, v223
	ds_read_b128 v[226:229], v243
	ds_read_b128 v[230:233], v244
	v_add_u32_e32 v243, v242, v222
	v_add_u32_e32 v244, v242, v221
	ds_read_b128 v[234:237], v243
	ds_read_b128 v[238:241], v244
	v_lshl_add_u64 v[128:129], v[202:203], 0, s[26:27]
	s_mov_b32 m0, s24
	v_lshl_add_u64 v[130:131], v[204:205], 0, s[26:27]
	global_load_lds_dwordx4 v[128:129], off
	s_add_i32 m0, s24, 0x2000
	s_nop 0
	global_load_lds_dwordx4 v[130:131], off
	v_fmamk_f32 v144, v144, 0x3e0293ee, v208
	v_fmamk_f32 v145, v145, 0x3e0293ee, v208
	v_fmamk_f32 v146, v146, 0x3e0293ee, v208
	v_fmamk_f32 v147, v147, 0x3e0293ee, v208
	v_exp_f32_e32 v144, v144
	v_exp_f32_e32 v145, v145
	v_exp_f32_e32 v146, v146
	v_exp_f32_e32 v147, v147
	s_waitcnt lgkmcnt(2)
	v_mfma_f32_32x32x16_bf16 v[128:143], v[226:229], v[188:191], 0
	v_mfma_f32_32x32x16_bf16 v[128:143], v[230:233], v[184:187], v[128:143]
	v_add_u32_e32 v243, v242, v220
	v_add_u32_e32 v244, v242, v219
	ds_read_b128 v[226:229], v243
	ds_read_b128 v[230:233], v244
	v_fmamk_f32 v148, v148, 0x3e0293ee, v208
	v_fmamk_f32 v149, v149, 0x3e0293ee, v208
	v_fmamk_f32 v150, v150, 0x3e0293ee, v208
	v_fmamk_f32 v151, v151, 0x3e0293ee, v208
	v_exp_f32_e32 v148, v148
	v_exp_f32_e32 v149, v149
	v_exp_f32_e32 v150, v150
	v_exp_f32_e32 v151, v151
	v_add_f32_e32 v246, v144, v145
	v_add_f32_e32 v246, v146, v246
	v_add_f32_e32 v246, v147, v246
	s_waitcnt lgkmcnt(2)
	v_mfma_f32_32x32x16_bf16 v[128:143], v[234:237], v[180:183], v[128:143]
	v_mfma_f32_32x32x16_bf16 v[128:143], v[238:241], v[176:179], v[128:143]
	v_add_u32_e32 v243, v242, v218
	v_add_u32_e32 v244, v242, v217
	ds_read_b128 v[234:237], v243
	ds_read_b128 v[238:241], v244
	v_fmamk_f32 v152, v152, 0x3e0293ee, v208
	v_fmamk_f32 v153, v153, 0x3e0293ee, v208
	v_fmamk_f32 v154, v154, 0x3e0293ee, v208
	v_fmamk_f32 v155, v155, 0x3e0293ee, v208
	v_exp_f32_e32 v152, v152
	v_exp_f32_e32 v153, v153
	v_exp_f32_e32 v154, v154
	v_exp_f32_e32 v155, v155
	v_add_f32_e32 v246, v148, v246
	v_add_f32_e32 v246, v149, v246
	v_add_f32_e32 v246, v150, v246
	v_add_f32_e32 v246, v151, v246
	s_waitcnt lgkmcnt(2)
	v_mfma_f32_32x32x16_bf16 v[128:143], v[226:229], v[172:175], v[128:143]
	v_mfma_f32_32x32x16_bf16 v[128:143], v[230:233], v[168:171], v[128:143]
	v_fmamk_f32 v156, v156, 0x3e0293ee, v208
	v_fmamk_f32 v157, v157, 0x3e0293ee, v208
	v_fmamk_f32 v158, v158, 0x3e0293ee, v208
	v_fmamk_f32 v159, v159, 0x3e0293ee, v208
	v_exp_f32_e32 v156, v156
	v_exp_f32_e32 v157, v157
	v_exp_f32_e32 v158, v158
	v_exp_f32_e32 v159, v159
	v_add_f32_e32 v246, v152, v246
	v_add_f32_e32 v246, v153, v246
	v_add_f32_e32 v246, v154, v246
	v_add_f32_e32 v246, v155, v246
	v_cvt_pk_bf16_f32 v226, v144, v145
	v_cvt_pk_bf16_f32 v227, v146, v147
	v_cvt_pk_bf16_f32 v228, v148, v149
	v_cvt_pk_bf16_f32 v229, v150, v151
	s_waitcnt lgkmcnt(0)
	v_mfma_f32_32x32x16_bf16 v[128:143], v[234:237], v[164:167], v[128:143]
	v_mfma_f32_32x32x16_bf16 v[128:143], v[238:241], v[160:163], v[128:143]
	v_add_u32_e32 v245, s84, v214
	ds_read_b64_tr_b16 v[234:235], v245 offset:0
	ds_read_b64_tr_b16 v[236:237], v245 offset:2048
	ds_read_b64_tr_b16 v[238:239], v245 offset:512
	ds_read_b64_tr_b16 v[240:241], v245 offset:2560
	v_permlane32_swap_b32_e32 v226, v228
	v_permlane32_swap_b32_e32 v227, v229
	ds_read_b64_tr_b16 v[144:145], v245 offset:4096
	ds_read_b64_tr_b16 v[146:147], v245 offset:6144
	ds_read_b64_tr_b16 v[148:149], v245 offset:4608
	ds_read_b64_tr_b16 v[150:151], v245 offset:6656
	v_add_f32_e32 v246, v156, v246
	v_add_f32_e32 v246, v157, v246
	v_add_f32_e32 v246, v158, v246
	v_add_f32_e32 v246, v159, v246
	v_cvt_pk_bf16_f32 v230, v152, v153
	v_cvt_pk_bf16_f32 v231, v154, v155
	v_cvt_pk_bf16_f32 v232, v156, v157
	v_cvt_pk_bf16_f32 v233, v158, v159
	v_add_f32_e32 v215, v215, v246
	ds_read_b64_tr_b16 v[152:153], v245 offset:1024
	ds_read_b64_tr_b16 v[154:155], v245 offset:3072
	ds_read_b64_tr_b16 v[156:157], v245 offset:1536
	ds_read_b64_tr_b16 v[158:159], v245 offset:3584
	v_permlane32_swap_b32_e32 v230, v232
	v_permlane32_swap_b32_e32 v231, v233
	s_waitcnt lgkmcnt(8)
	v_mfma_f32_32x32x16_bf16 v[112:127], v[226:229], v[234:237], v[112:127]
	v_mfma_f32_32x32x16_bf16 v[96:111], v[226:229], v[238:241], v[96:111]
	ds_read_b64_tr_b16 v[234:235], v245 offset:5120
	ds_read_b64_tr_b16 v[236:237], v245 offset:7168
	ds_read_b64_tr_b16 v[238:239], v245 offset:5632
	ds_read_b64_tr_b16 v[240:241], v245 offset:7680
	v_lshl_add_u64 v[242:243], v[198:199], 0, s[26:27]
	s_add_i32 s41, s85, s24
	s_add_i32 m0, s41, 0x8000
	v_lshl_add_u64 v[242:243], v[242:243], 0, s[12:13]
	global_load_lds_dwordx4 v[242:243], off
	s_waitcnt lgkmcnt(8)
	v_mfma_f32_32x32x16_bf16 v[112:127], v[230:233], v[144:147], v[112:127]
	v_mfma_f32_32x32x16_bf16 v[96:111], v[230:233], v[148:151], v[96:111]
	ds_read_b64_tr_b16 v[144:145], v245 offset:16384
	ds_read_b64_tr_b16 v[146:147], v245 offset:18432
	ds_read_b64_tr_b16 v[148:149], v245 offset:16896
	ds_read_b64_tr_b16 v[150:151], v245 offset:18944
	v_lshl_add_u64 v[242:243], v[200:201], 0, s[26:27]
	s_add_i32 s41, s85, s24
	s_add_i32 m0, s41, 0xa000
	v_lshl_add_u64 v[242:243], v[242:243], 0, s[12:13]
	global_load_lds_dwordx4 v[242:243], off
	s_waitcnt lgkmcnt(8)
	v_mfma_f32_32x32x16_bf16 v[80:95], v[226:229], v[152:155], v[80:95]
	v_mfma_f32_32x32x16_bf16 v[64:79], v[226:229], v[156:159], v[64:79]
	ds_read_b64_tr_b16 v[152:153], v245 offset:20480
	ds_read_b64_tr_b16 v[154:155], v245 offset:22528
	ds_read_b64_tr_b16 v[156:157], v245 offset:20992
	ds_read_b64_tr_b16 v[158:159], v245 offset:23040
	v_lshl_add_u64 v[242:243], v[198:199], 0, s[26:27]
	s_add_i32 s41, s85, s24
	s_add_i32 m0, s41, 0xc000
	v_lshl_add_u64 v[242:243], v[242:243], 0, s[14:15]
	global_load_lds_dwordx4 v[242:243], off
	s_waitcnt lgkmcnt(8)
	v_mfma_f32_32x32x16_bf16 v[80:95], v[230:233], v[234:237], v[80:95]
	v_mfma_f32_32x32x16_bf16 v[64:79], v[230:233], v[238:241], v[64:79]
	ds_read_b64_tr_b16 v[234:235], v245 offset:17408
	ds_read_b64_tr_b16 v[236:237], v245 offset:19456
	ds_read_b64_tr_b16 v[238:239], v245 offset:17920
	ds_read_b64_tr_b16 v[240:241], v245 offset:19968
	v_lshl_add_u64 v[242:243], v[200:201], 0, s[26:27]
	s_add_i32 s41, s85, s24
	s_add_i32 m0, s41, 0xe000
	v_lshl_add_u64 v[242:243], v[242:243], 0, s[14:15]
	global_load_lds_dwordx4 v[242:243], off
	s_waitcnt lgkmcnt(8)
	v_mfma_f32_32x32x16_bf16 v[48:63], v[226:229], v[144:147], v[48:63]
	v_mfma_f32_32x32x16_bf16 v[32:47], v[226:229], v[148:151], v[32:47]
	ds_read_b64_tr_b16 v[144:145], v245 offset:21504
	ds_read_b64_tr_b16 v[146:147], v245 offset:23552
	ds_read_b64_tr_b16 v[148:149], v245 offset:22016
	ds_read_b64_tr_b16 v[150:151], v245 offset:24064
	s_waitcnt lgkmcnt(8)
	v_mfma_f32_32x32x16_bf16 v[48:63], v[230:233], v[152:155], v[48:63]
	v_mfma_f32_32x32x16_bf16 v[32:47], v[230:233], v[156:159], v[32:47]
	s_waitcnt lgkmcnt(0)
	v_mfma_f32_32x32x16_bf16 v[16:31], v[226:229], v[234:237], v[16:31]
	s_waitcnt vmcnt(0)
	s_barrier
; #define SBAR() __builtin_amdgcn_sched_barrier(0)
; #define PVR(S, DA, DB, vbase) do { S[0] = tr_read<v_rd_off(DA, 0, 0)>(vbase); S[1] = tr_read<v_rd_off(DA, 0, 1)>(vbase); S[2] = tr_read<v_rd_off(DB, 0, 0)>(vbase); S[3] = tr_read<v_rd_off(DB, 0, 1)>(vbase); \
;     S[4] = tr_read<v_rd_off(DA, 1, 0)>(vbase); S[5] = tr_read<v_rd_off(DA, 1, 1)>(vbase); S[6] = tr_read<v_rd_off(DB, 1, 0)>(vbase); S[7] = tr_read<v_rd_off(DB, 1, 1)>(vbase); } while (0)
; #define RAWBAR() do { asm volatile("s_waitcnt lgkmcnt(0)" ::: "memory"); __builtin_amdgcn_s_barrier(); asm volatile("" ::: "memory"); } while (0)
; #define RAWBAR() do { asm volatile("s_waitcnt lgkmcnt(0)" ::: "memory"); __builtin_amdgcn_s_barrier(); asm volatile("" ::: "memory"); } while (0)
; #define RAWBAR() do { asm volatile("s_waitcnt lgkmcnt(0)" ::: "memory"); __builtin_amdgcn_s_barrier(); asm volatile("" ::: "memory"); } while (0)
; #define RAWBAR() do { asm volatile("s_waitcnt lgkmcnt(0)" ::: "memory"); __builtin_amdgcn_s_barrier(); asm volatile("" ::: "memory"); } while (0)
; #define RAWBAR() do { asm volatile("s_waitcnt lgkmcnt(0)" ::: "memory"); __builtin_amdgcn_s_barrier(); asm volatile("" ::: "memory"); } while (0)
; template <int MODE> ...
;     ...
;   for (int j = 0; j < NT; ++j) {
;     const int buf = j & 1;
;     if (j + 1 < NT) { STAGE((j + 1) * KVBLK, buf ^ 1); }
;     const char* Kb = K_lds + buf * 16384;
;     f32x16 pe = {}, po = {};
; #pragma unroll
;     for (int d0 = 0; d0 < 8; d0 += 2) {
;       const bf16x8 k0 = *reinterpret_cast<const bf16x8*>(Kb + KSWZ(krow, (d0 * 16 + hi * 8) * 2));
;       const bf16x8 k1 = *reinterpret_cast<const bf16x8*>(Kb + KSWZ(krow, ((d0 + 1) * 16 + hi * 8) * 2));
;       pe = __builtin_amdgcn_mfma_f32_32x32x16_bf16(k0, qr[d0], pe, 0, 0, 0);
;       po = __builtin_amdgcn_mfma_f32_32x32x16_bf16(k1, qr[d0 + 1], po, 0, 0, 0); }
;     const int vo = vb0 + buf * 32768;
;     s16x4 R0_[8], R1_[8];
;     PVR(R0_, 0, 1, vo);
;     f32x16 p;
; #pragma unroll
;     for (int r = 0; r < 16; ++r) p[r] = __builtin_amdgcn_exp2f(fmaf(pe[r] + po[r], C, negMc));
;     float ps = 0.f;
; #pragma unroll
;     for (int r = 0; r < 16; ++r) ps += p[r];
;     lsum += ps;
;     const bf16x8 own0 = pk8(p, 0), own1 = pk8(p, 8);
;     SBAR();
;     PV_TAIL4(o, vo, vo + 16384, own0, own1);
;     asm volatile("s_waitcnt vmcnt(0)" ::: "memory");
;     RAWBAR();
;   }
	v_lshl_add_u64 v[198:199], v[198:199], 0, s[16:17]
	v_lshl_add_u64 v[200:201], v[200:201], 0, s[16:17]
	v_lshl_add_u64 v[202:203], v[202:203], 0, s[18:19]
	v_lshl_add_u64 v[204:205], v[204:205], 0, s[18:19]
	v_mfma_f32_32x32x16_bf16 v[0:15], v[226:229], v[238:241], v[0:15]
	v_mfma_f32_32x32x16_bf16 v[16:31], v[230:233], v[144:147], v[16:31]
	v_mfma_f32_32x32x16_bf16 v[0:15], v[230:233], v[148:151], v[0:15]
	s_mov_b32 s87, s84
	s_mov_b32 s84, s85
	s_mov_b32 s85, s86
	s_mov_b32 s86, s87
	v_add_u32_e32 v243, v216, v225
	v_add_u32_e32 v244, v216, v223
	ds_read_b128 v[226:229], v243
	ds_read_b128 v[230:233], v244
	v_add_u32_e32 v243, v216, v222
	v_add_u32_e32 v244, v216, v221
	ds_read_b128 v[234:237], v243
	ds_read_b128 v[238:241], v244
	v_lshl_add_u64 v[144:145], v[202:203], 0, s[26:27]
	s_add_i32 m0, s24, 0x4000
	v_lshl_add_u64 v[146:147], v[204:205], 0, s[26:27]
	global_load_lds_dwordx4 v[144:145], off
	s_add_i32 m0, s24, 0x6000
	s_nop 0
	global_load_lds_dwordx4 v[146:147], off
	v_fmamk_f32 v128, v128, 0x3e0293ee, v208
	v_fmamk_f32 v129, v129, 0x3e0293ee, v208
	v_fmamk_f32 v130, v130, 0x3e0293ee, v208
	v_fmamk_f32 v131, v131, 0x3e0293ee, v208
	v_exp_f32_e32 v128, v128
	v_exp_f32_e32 v129, v129
	v_exp_f32_e32 v130, v130
	v_exp_f32_e32 v131, v131
	s_waitcnt lgkmcnt(2)
	v_mfma_f32_32x32x16_bf16 v[144:159], v[226:229], v[188:191], 0
	v_mfma_f32_32x32x16_bf16 v[144:159], v[230:233], v[184:187], v[144:159]
	v_add_u32_e32 v243, v216, v220
	v_add_u32_e32 v244, v216, v219
	ds_read_b128 v[226:229], v243
	ds_read_b128 v[230:233], v244
	v_fmamk_f32 v132, v132, 0x3e0293ee, v208
	v_fmamk_f32 v133, v133, 0x3e0293ee, v208
	v_fmamk_f32 v134, v134, 0x3e0293ee, v208
	v_fmamk_f32 v135, v135, 0x3e0293ee, v208
	v_exp_f32_e32 v132, v132
	v_exp_f32_e32 v133, v133
	v_exp_f32_e32 v134, v134
	v_exp_f32_e32 v135, v135
	v_add_f32_e32 v246, v128, v129
	v_add_f32_e32 v246, v130, v246
	v_add_f32_e32 v246, v131, v246
	s_waitcnt lgkmcnt(2)
	v_mfma_f32_32x32x16_bf16 v[144:159], v[234:237], v[180:183], v[144:159]
	v_mfma_f32_32x32x16_bf16 v[144:159], v[238:241], v[176:179], v[144:159]
	v_add_u32_e32 v243, v216, v218
	v_add_u32_e32 v244, v216, v217
	ds_read_b128 v[234:237], v243
	ds_read_b128 v[238:241], v244
	v_fmamk_f32 v136, v136, 0x3e0293ee, v208
	v_fmamk_f32 v137, v137, 0x3e0293ee, v208
	v_fmamk_f32 v138, v138, 0x3e0293ee, v208
	v_fmamk_f32 v139, v139, 0x3e0293ee, v208
	v_exp_f32_e32 v136, v136
	v_exp_f32_e32 v137, v137
	v_exp_f32_e32 v138, v138
	v_exp_f32_e32 v139, v139
	v_add_f32_e32 v246, v132, v246
	v_add_f32_e32 v246, v133, v246
	v_add_f32_e32 v246, v134, v246
	v_add_f32_e32 v246, v135, v246
	s_waitcnt lgkmcnt(2)
	v_mfma_f32_32x32x16_bf16 v[144:159], v[226:229], v[172:175], v[144:159]
	v_mfma_f32_32x32x16_bf16 v[144:159], v[230:233], v[168:171], v[144:159]
	v_fmamk_f32 v140, v140, 0x3e0293ee, v208
	v_fmamk_f32 v141, v141, 0x3e0293ee, v208
	v_fmamk_f32 v142, v142, 0x3e0293ee, v208
	v_fmamk_f32 v143, v143, 0x3e0293ee, v208
	v_exp_f32_e32 v140, v140
	v_exp_f32_e32 v141, v141
	v_exp_f32_e32 v142, v142
	v_exp_f32_e32 v143, v143
	v_add_f32_e32 v246, v136, v246
	v_add_f32_e32 v246, v137, v246
	v_add_f32_e32 v246, v138, v246
	v_add_f32_e32 v246, v139, v246
	v_cvt_pk_bf16_f32 v226, v128, v129
	v_cvt_pk_bf16_f32 v227, v130, v131
	v_cvt_pk_bf16_f32 v228, v132, v133
	v_cvt_pk_bf16_f32 v229, v134, v135
	s_waitcnt lgkmcnt(0)
	v_mfma_f32_32x32x16_bf16 v[144:159], v[234:237], v[164:167], v[144:159]
	v_mfma_f32_32x32x16_bf16 v[144:159], v[238:241], v[160:163], v[144:159]
	v_add_u32_e32 v245, s84, v214
	ds_read_b64_tr_b16 v[234:235], v245 offset:0
	ds_read_b64_tr_b16 v[236:237], v245 offset:2048
	ds_read_b64_tr_b16 v[238:239], v245 offset:512
	ds_read_b64_tr_b16 v[240:241], v245 offset:2560
	v_permlane32_swap_b32_e32 v226, v228
	v_permlane32_swap_b32_e32 v227, v229
	ds_read_b64_tr_b16 v[128:129], v245 offset:4096
	ds_read_b64_tr_b16 v[130:131], v245 offset:6144
	ds_read_b64_tr_b16 v[132:133], v245 offset:4608
	ds_read_b64_tr_b16 v[134:135], v245 offset:6656
	v_add_f32_e32 v246, v140, v246
	v_add_f32_e32 v246, v141, v246
	v_add_f32_e32 v246, v142, v246
	v_add_f32_e32 v246, v143, v246
	v_cvt_pk_bf16_f32 v230, v136, v137
	v_cvt_pk_bf16_f32 v231, v138, v139
	v_cvt_pk_bf16_f32 v232, v140, v141
	v_cvt_pk_bf16_f32 v233, v142, v143
	v_add_f32_e32 v215, v215, v246
	ds_read_b64_tr_b16 v[136:137], v245 offset:1024
	ds_read_b64_tr_b16 v[138:139], v245 offset:3072
	ds_read_b64_tr_b16 v[140:141], v245 offset:1536
	ds_read_b64_tr_b16 v[142:143], v245 offset:3584
	v_permlane32_swap_b32_e32 v230, v232
	v_permlane32_swap_b32_e32 v231, v233
	s_waitcnt lgkmcnt(8)
	v_mfma_f32_32x32x16_bf16 v[112:127], v[226:229], v[234:237], v[112:127]
	v_mfma_f32_32x32x16_bf16 v[96:111], v[226:229], v[238:241], v[96:111]
	ds_read_b64_tr_b16 v[234:235], v245 offset:5120
	ds_read_b64_tr_b16 v[236:237], v245 offset:7168
	ds_read_b64_tr_b16 v[238:239], v245 offset:5632
	ds_read_b64_tr_b16 v[240:241], v245 offset:7680
	v_lshl_add_u64 v[242:243], v[198:199], 0, s[26:27]
	s_add_i32 s41, s85, s24
	s_add_i32 m0, s41, 0x8000
	v_lshl_add_u64 v[242:243], v[242:243], 0, s[12:13]
	global_load_lds_dwordx4 v[242:243], off
	s_waitcnt lgkmcnt(8)
	v_mfma_f32_32x32x16_bf16 v[112:127], v[230:233], v[128:131], v[112:127]
	v_mfma_f32_32x32x16_bf16 v[96:111], v[230:233], v[132:135], v[96:111]
	ds_read_b64_tr_b16 v[128:129], v245 offset:16384
	ds_read_b64_tr_b16 v[130:131], v245 offset:18432
	ds_read_b64_tr_b16 v[132:133], v245 offset:16896
	ds_read_b64_tr_b16 v[134:135], v245 offset:18944
	v_lshl_add_u64 v[242:243], v[200:201], 0, s[26:27]
	s_add_i32 s41, s85, s24
	s_add_i32 m0, s41, 0xa000
	v_lshl_add_u64 v[242:243], v[242:243], 0, s[12:13]
	global_load_lds_dwordx4 v[242:243], off
	s_waitcnt lgkmcnt(8)
; #define SBAR() __builtin_amdgcn_sched_barrier(0)
; #define PVR(S, DA, DB, vbase) do { S[0] = tr_read<v_rd_off(DA, 0, 0)>(vbase); S[1] = tr_read<v_rd_off(DA, 0, 1)>(vbase); S[2] = tr_read<v_rd_off(DB, 0, 0)>(vbase); S[3] = tr_read<v_rd_off(DB, 0, 1)>(vbase); \
;     S[4] = tr_read<v_rd_off(DA, 1, 0)>(vbase); S[5] = tr_read<v_rd_off(DA, 1, 1)>(vbase); S[6] = tr_read<v_rd_off(DB, 1, 0)>(vbase); S[7] = tr_read<v_rd_off(DB, 1, 1)>(vbase); } while (0)
; #define RAWBAR() do { asm volatile("s_waitcnt lgkmcnt(0)" ::: "memory"); __builtin_amdgcn_s_barrier(); asm volatile("" ::: "memory"); } while (0)
; #define RAWBAR() do { asm volatile("s_waitcnt lgkmcnt(0)" ::: "memory"); __builtin_amdgcn_s_barrier(); asm volatile("" ::: "memory"); } while (0)
; #define RAWBAR() do { asm volatile("s_waitcnt lgkmcnt(0)" ::: "memory"); __builtin_amdgcn_s_barrier(); asm volatile("" ::: "memory"); } while (0)
; #define RAWBAR() do { asm volatile("s_waitcnt lgkmcnt(0)" ::: "memory"); __builtin_amdgcn_s_barrier(); asm volatile("" ::: "memory"); } while (0)
; #define RAWBAR() do { asm volatile("s_waitcnt lgkmcnt(0)" ::: "memory"); __builtin_amdgcn_s_barrier(); asm volatile("" ::: "memory"); } while (0)
; template <int MODE> ...
;     ...
;   for (int j = 0; j < NT; ++j) {
;     const int buf = j & 1;
;     if (j + 1 < NT) { STAGE((j + 1) * KVBLK, buf ^ 1); }
;     const char* Kb = K_lds + buf * 16384;
;     f32x16 pe = {}, po = {};
; #pragma unroll
;     for (int d0 = 0; d0 < 8; d0 += 2) {
;       const bf16x8 k0 = *reinterpret_cast<const bf16x8*>(Kb + KSWZ(krow, (d0 * 16 + hi * 8) * 2));
;       const bf16x8 k1 = *reinterpret_cast<const bf16x8*>(Kb + KSWZ(krow, ((d0 + 1) * 16 + hi * 8) * 2));
;       pe = __builtin_amdgcn_mfma_f32_32x32x16_bf16(k0, qr[d0], pe, 0, 0, 0);
;       po = __builtin_amdgcn_mfma_f32_32x32x16_bf16(k1, qr[d0 + 1], po, 0, 0, 0); }
;     const int vo = vb0 + buf * 32768;
;     s16x4 R0_[8], R1_[8];
;     PVR(R0_, 0, 1, vo);
;     f32x16 p;
; #pragma unroll
;     for (int r = 0; r < 16; ++r) p[r] = __builtin_amdgcn_exp2f(fmaf(pe[r] + po[r], C, negMc));
;     float ps = 0.f;
; #pragma unroll
;     for (int r = 0; r < 16; ++r) ps += p[r];
;     lsum += ps;
;     const bf16x8 own0 = pk8(p, 0), own1 = pk8(p, 8);
;     SBAR();
;     PV_TAIL4(o, vo, vo + 16384, own0, own1);
;     asm volatile("s_waitcnt vmcnt(0)" ::: "memory");
;     RAWBAR();
;   }
	v_mfma_f32_32x32x16_bf16 v[80:95], v[226:229], v[136:139], v[80:95]
	v_mfma_f32_32x32x16_bf16 v[64:79], v[226:229], v[140:143], v[64:79]
	ds_read_b64_tr_b16 v[136:137], v245 offset:20480
	ds_read_b64_tr_b16 v[138:139], v245 offset:22528
	ds_read_b64_tr_b16 v[140:141], v245 offset:20992
	ds_read_b64_tr_b16 v[142:143], v245 offset:23040
	v_lshl_add_u64 v[242:243], v[198:199], 0, s[26:27]
	s_add_i32 s41, s85, s24
	s_add_i32 m0, s41, 0xc000
	v_lshl_add_u64 v[242:243], v[242:243], 0, s[14:15]
	global_load_lds_dwordx4 v[242:243], off
	s_waitcnt lgkmcnt(8)
	v_mfma_f32_32x32x16_bf16 v[80:95], v[230:233], v[234:237], v[80:95]
	v_mfma_f32_32x32x16_bf16 v[64:79], v[230:233], v[238:241], v[64:79]
	ds_read_b64_tr_b16 v[234:235], v245 offset:17408
	ds_read_b64_tr_b16 v[236:237], v245 offset:19456
	ds_read_b64_tr_b16 v[238:239], v245 offset:17920
	ds_read_b64_tr_b16 v[240:241], v245 offset:19968
	v_lshl_add_u64 v[242:243], v[200:201], 0, s[26:27]
	s_add_i32 s41, s85, s24
	s_add_i32 m0, s41, 0xe000
	v_lshl_add_u64 v[242:243], v[242:243], 0, s[14:15]
	global_load_lds_dwordx4 v[242:243], off
	s_waitcnt lgkmcnt(8)
	v_mfma_f32_32x32x16_bf16 v[48:63], v[226:229], v[128:131], v[48:63]
	v_mfma_f32_32x32x16_bf16 v[32:47], v[226:229], v[132:135], v[32:47]
	ds_read_b64_tr_b16 v[128:129], v245 offset:21504
	ds_read_b64_tr_b16 v[130:131], v245 offset:23552
	ds_read_b64_tr_b16 v[132:133], v245 offset:22016
	ds_read_b64_tr_b16 v[134:135], v245 offset:24064
	s_waitcnt lgkmcnt(8)
	v_mfma_f32_32x32x16_bf16 v[48:63], v[230:233], v[136:139], v[48:63]
	v_mfma_f32_32x32x16_bf16 v[32:47], v[230:233], v[140:143], v[32:47]
	s_waitcnt lgkmcnt(0)
	v_mfma_f32_32x32x16_bf16 v[16:31], v[226:229], v[234:237], v[16:31]
	s_waitcnt vmcnt(0)
	s_barrier
	v_lshl_add_u64 v[198:199], v[198:199], 0, s[16:17]
	v_lshl_add_u64 v[200:201], v[200:201], 0, s[16:17]
	v_lshl_add_u64 v[202:203], v[202:203], 0, s[18:19]
	v_lshl_add_u64 v[204:205], v[204:205], 0, s[18:19]
	v_mfma_f32_32x32x16_bf16 v[0:15], v[226:229], v[238:241], v[0:15]
	v_mfma_f32_32x32x16_bf16 v[16:31], v[230:233], v[128:131], v[16:31]
	v_mfma_f32_32x32x16_bf16 v[0:15], v[230:233], v[132:135], v[0:15]
	s_mov_b32 s87, s84
	s_mov_b32 s84, s85
	s_mov_b32 s85, s86
	s_mov_b32 s86, s87
	s_add_i32 s25, s25, 1
	s_cmpk_eq_i32 s25, 0x82
	s_cbranch_scc0 .LBB0_1019
	s_barrier
	s_branch .Lattn_join_m0
.LattnBpre_m0:
	v_lshl_add_u64 v[128:129], v[202:203], 0, s[26:27]
	s_mov_b32 m0, s24
	v_lshl_add_u64 v[130:131], v[204:205], 0, s[26:27]
	global_load_lds_dwordx4 v[128:129], off
	s_add_i32 m0, s24, 0x2000
	s_nop 0
	global_load_lds_dwordx4 v[130:131], off
	v_lshl_add_u64 v[132:133], v[198:199], 0, s[26:27]
	s_add_i32 s41, s85, s24
	s_add_i32 m0, s41, 0x8000
	v_lshl_add_u64 v[132:133], v[132:133], 0, s[12:13]
	global_load_lds_dwordx4 v[132:133], off
	v_lshl_add_u64 v[132:133], v[200:201], 0, s[26:27]
	s_add_i32 s41, s85, s24
	s_add_i32 m0, s41, 0xa000
	v_lshl_add_u64 v[132:133], v[132:133], 0, s[12:13]
	global_load_lds_dwordx4 v[132:133], off
	v_lshl_add_u64 v[132:133], v[198:199], 0, s[26:27]
	s_add_i32 s41, s85, s24
	s_add_i32 m0, s41, 0xc000
	v_lshl_add_u64 v[132:133], v[132:133], 0, s[14:15]
	global_load_lds_dwordx4 v[132:133], off
	v_lshl_add_u64 v[132:133], v[200:201], 0, s[26:27]
	s_add_i32 s41, s85, s24
	s_add_i32 m0, s41, 0xe000
	v_lshl_add_u64 v[132:133], v[132:133], 0, s[14:15]
	global_load_lds_dwordx4 v[132:133], off
.LattnB_m0:
	v_add_u32_e32 v242, 0x4000, v216
	v_add_u32_e32 v243, v242, v225
	v_add_u32_e32 v244, v242, v223
	ds_read_b128 v[226:229], v243
	ds_read_b128 v[230:233], v244
	v_add_u32_e32 v243, v242, v222
	v_add_u32_e32 v244, v242, v221
	ds_read_b128 v[234:237], v243
	ds_read_b128 v[238:241], v244
	v_fmamk_f32 v144, v144, 0x3e0293ee, v208
	v_fmamk_f32 v145, v145, 0x3e0293ee, v208
	v_fmamk_f32 v146, v146, 0x3e0293ee, v208
	v_fmamk_f32 v147, v147, 0x3e0293ee, v208
	v_exp_f32_e32 v144, v144
	v_exp_f32_e32 v145, v145
	v_exp_f32_e32 v146, v146
	v_exp_f32_e32 v147, v147
	s_waitcnt lgkmcnt(2)
	v_mfma_f32_32x32x16_bf16 v[128:143], v[226:229], v[188:191], 0
	v_mfma_f32_32x32x16_bf16 v[128:143], v[230:233], v[184:187], v[128:143]
	v_add_u32_e32 v243, v242, v220
	v_add_u32_e32 v244, v242, v219
	ds_read_b128 v[226:229], v243
	ds_read_b128 v[230:233], v244
	v_fmamk_f32 v148, v148, 0x3e0293ee, v208
	v_fmamk_f32 v149, v149, 0x3e0293ee, v208
	v_fmamk_f32 v150, v150, 0x3e0293ee, v208
	v_fmamk_f32 v151, v151, 0x3e0293ee, v208
	v_exp_f32_e32 v148, v148
	v_exp_f32_e32 v149, v149
	v_exp_f32_e32 v150, v150
	v_exp_f32_e32 v151, v151
	v_add_f32_e32 v246, v144, v145
	v_add_f32_e32 v246, v146, v246
	v_add_f32_e32 v246, v147, v246
	s_waitcnt lgkmcnt(2)
	v_mfma_f32_32x32x16_bf16 v[128:143], v[234:237], v[180:183], v[128:143]
	v_mfma_f32_32x32x16_bf16 v[128:143], v[238:241], v[176:179], v[128:143]
	v_add_u32_e32 v243, v242, v218
	v_add_u32_e32 v244, v242, v217
	ds_read_b128 v[234:237], v243
	ds_read_b128 v[238:241], v244
	v_fmamk_f32 v152, v152, 0x3e0293ee, v208
	v_fmamk_f32 v153, v153, 0x3e0293ee, v208
	v_fmamk_f32 v154, v154, 0x3e0293ee, v208
	v_fmamk_f32 v155, v155, 0x3e0293ee, v208
	v_exp_f32_e32 v152, v152
	v_exp_f32_e32 v153, v153
	v_exp_f32_e32 v154, v154
	v_exp_f32_e32 v155, v155
	v_add_f32_e32 v246, v148, v246
	v_add_f32_e32 v246, v149, v246
	v_add_f32_e32 v246, v150, v246
	v_add_f32_e32 v246, v151, v246
	s_waitcnt lgkmcnt(2)
	v_mfma_f32_32x32x16_bf16 v[128:143], v[226:229], v[172:175], v[128:143]
	v_mfma_f32_32x32x16_bf16 v[128:143], v[230:233], v[168:171], v[128:143]
	v_fmamk_f32 v156, v156, 0x3e0293ee, v208
	v_fmamk_f32 v157, v157, 0x3e0293ee, v208
	v_fmamk_f32 v158, v158, 0x3e0293ee, v208
	v_fmamk_f32 v159, v159, 0x3e0293ee, v208
	v_exp_f32_e32 v156, v156
	v_exp_f32_e32 v157, v157
	v_exp_f32_e32 v158, v158
	v_exp_f32_e32 v159, v159
	v_add_f32_e32 v246, v152, v246
	v_add_f32_e32 v246, v153, v246
	v_add_f32_e32 v246, v154, v246
	v_add_f32_e32 v246, v155, v246
	v_cvt_pk_bf16_f32 v226, v144, v145
	v_cvt_pk_bf16_f32 v227, v146, v147
	v_cvt_pk_bf16_f32 v228, v148, v149
	v_cvt_pk_bf16_f32 v229, v150, v151
	s_waitcnt lgkmcnt(0)
	v_mfma_f32_32x32x16_bf16 v[128:143], v[234:237], v[164:167], v[128:143]
	v_mfma_f32_32x32x16_bf16 v[128:143], v[238:241], v[160:163], v[128:143]
	s_waitcnt vmcnt(0)
	s_barrier
; #define SBAR() __builtin_amdgcn_sched_barrier(0)
; #define PVR(S, DA, DB, vbase) do { S[0] = tr_read<v_rd_off(DA, 0, 0)>(vbase); S[1] = tr_read<v_rd_off(DA, 0, 1)>(vbase); S[2] = tr_read<v_rd_off(DB, 0, 0)>(vbase); S[3] = tr_read<v_rd_off(DB, 0, 1)>(vbase); \
;     S[4] = tr_read<v_rd_off(DA, 1, 0)>(vbase); S[5] = tr_read<v_rd_off(DA, 1, 1)>(vbase); S[6] = tr_read<v_rd_off(DB, 1, 0)>(vbase); S[7] = tr_read<v_rd_off(DB, 1, 1)>(vbase); } while (0)
; #define RAWBAR() do { asm volatile("s_waitcnt lgkmcnt(0)" ::: "memory"); __builtin_amdgcn_s_barrier(); asm volatile("" ::: "memory"); } while (0)
; #define RAWBAR() do { asm volatile("s_waitcnt lgkmcnt(0)" ::: "memory"); __builtin_amdgcn_s_barrier(); asm volatile("" ::: "memory"); } while (0)
; #define RAWBAR() do { asm volatile("s_waitcnt lgkmcnt(0)" ::: "memory"); __builtin_amdgcn_s_barrier(); asm volatile("" ::: "memory"); } while (0)
; #define RAWBAR() do { asm volatile("s_waitcnt lgkmcnt(0)" ::: "memory"); __builtin_amdgcn_s_barrier(); asm volatile("" ::: "memory"); } while (0)
; #define RAWBAR() do { asm volatile("s_waitcnt lgkmcnt(0)" ::: "memory"); __builtin_amdgcn_s_barrier(); asm volatile("" ::: "memory"); } while (0)
; template <int MODE> ...
;     ...
;   for (int j = 0; j < NT; ++j) {
;     const int buf = j & 1;
;     if (j + 1 < NT) { STAGE((j + 1) * KVBLK, buf ^ 1); }
;     const char* Kb = K_lds + buf * 16384;
;     f32x16 pe = {}, po = {};
; #pragma unroll
;     for (int d0 = 0; d0 < 8; d0 += 2) {
;       const bf16x8 k0 = *reinterpret_cast<const bf16x8*>(Kb + KSWZ(krow, (d0 * 16 + hi * 8) * 2));
;       const bf16x8 k1 = *reinterpret_cast<const bf16x8*>(Kb + KSWZ(krow, ((d0 + 1) * 16 + hi * 8) * 2));
;       pe = __builtin_amdgcn_mfma_f32_32x32x16_bf16(k0, qr[d0], pe, 0, 0, 0);
;       po = __builtin_amdgcn_mfma_f32_32x32x16_bf16(k1, qr[d0 + 1], po, 0, 0, 0); }
;     const int vo = vb0 + buf * 32768;
;     s16x4 R0_[8], R1_[8];
;     PVR(R0_, 0, 1, vo);
;     f32x16 p;
; #pragma unroll
;     for (int r = 0; r < 16; ++r) p[r] = __builtin_amdgcn_exp2f(fmaf(pe[r] + po[r], C, negMc));
;     float ps = 0.f;
; #pragma unroll
;     for (int r = 0; r < 16; ++r) ps += p[r];
;     lsum += ps;
;     const bf16x8 own0 = pk8(p, 0), own1 = pk8(p, 8);
;     SBAR();
;     PV_TAIL4(o, vo, vo + 16384, own0, own1);
;     asm volatile("s_waitcnt vmcnt(0)" ::: "memory");
;     RAWBAR();
;   }
	v_lshl_add_u64 v[198:199], v[198:199], 0, s[16:17]
	v_lshl_add_u64 v[200:201], v[200:201], 0, s[16:17]
	v_lshl_add_u64 v[202:203], v[202:203], 0, s[18:19]
	v_lshl_add_u64 v[204:205], v[204:205], 0, s[18:19]
	v_lshl_add_u64 v[144:145], v[202:203], 0, s[26:27]
	s_add_i32 m0, s24, 0x4000
	v_lshl_add_u64 v[146:147], v[204:205], 0, s[26:27]
	global_load_lds_dwordx4 v[144:145], off
	s_add_i32 m0, s24, 0x6000
	s_nop 0
	global_load_lds_dwordx4 v[146:147], off
	v_add_u32_e32 v245, s84, v214
	ds_read_b64_tr_b16 v[234:235], v245 offset:0
	ds_read_b64_tr_b16 v[236:237], v245 offset:2048
	ds_read_b64_tr_b16 v[238:239], v245 offset:512
	ds_read_b64_tr_b16 v[240:241], v245 offset:2560
	v_permlane32_swap_b32_e32 v226, v228
	v_permlane32_swap_b32_e32 v227, v229
	ds_read_b64_tr_b16 v[144:145], v245 offset:4096
	ds_read_b64_tr_b16 v[146:147], v245 offset:6144
	ds_read_b64_tr_b16 v[148:149], v245 offset:4608
	ds_read_b64_tr_b16 v[150:151], v245 offset:6656
	v_add_f32_e32 v246, v156, v246
	v_add_f32_e32 v246, v157, v246
	v_add_f32_e32 v246, v158, v246
	v_add_f32_e32 v246, v159, v246
	v_cvt_pk_bf16_f32 v230, v152, v153
	v_cvt_pk_bf16_f32 v231, v154, v155
	v_cvt_pk_bf16_f32 v232, v156, v157
	v_cvt_pk_bf16_f32 v233, v158, v159
	v_add_f32_e32 v215, v215, v246
	ds_read_b64_tr_b16 v[152:153], v245 offset:1024
	ds_read_b64_tr_b16 v[154:155], v245 offset:3072
	ds_read_b64_tr_b16 v[156:157], v245 offset:1536
	ds_read_b64_tr_b16 v[158:159], v245 offset:3584
	v_permlane32_swap_b32_e32 v230, v232
	v_permlane32_swap_b32_e32 v231, v233
	s_waitcnt lgkmcnt(8)
	v_mfma_f32_32x32x16_bf16 v[112:127], v[226:229], v[234:237], v[112:127]
	v_mfma_f32_32x32x16_bf16 v[96:111], v[226:229], v[238:241], v[96:111]
	ds_read_b64_tr_b16 v[234:235], v245 offset:5120
	ds_read_b64_tr_b16 v[236:237], v245 offset:7168
	ds_read_b64_tr_b16 v[238:239], v245 offset:5632
	ds_read_b64_tr_b16 v[240:241], v245 offset:7680
	v_lshl_add_u64 v[242:243], v[198:199], 0, s[26:27]
	s_add_i32 s41, s86, s24
	s_add_i32 m0, s41, 0x8000
	v_lshl_add_u64 v[242:243], v[242:243], 0, s[12:13]
	global_load_lds_dwordx4 v[242:243], off
	s_waitcnt lgkmcnt(8)
	v_mfma_f32_32x32x16_bf16 v[112:127], v[230:233], v[144:147], v[112:127]
	v_mfma_f32_32x32x16_bf16 v[96:111], v[230:233], v[148:151], v[96:111]
	ds_read_b64_tr_b16 v[144:145], v245 offset:16384
	ds_read_b64_tr_b16 v[146:147], v245 offset:18432
	ds_read_b64_tr_b16 v[148:149], v245 offset:16896
	ds_read_b64_tr_b16 v[150:151], v245 offset:18944
	v_lshl_add_u64 v[242:243], v[200:201], 0, s[26:27]
	s_add_i32 s41, s86, s24
	s_add_i32 m0, s41, 0xa000
	v_lshl_add_u64 v[242:243], v[242:243], 0, s[12:13]
	global_load_lds_dwordx4 v[242:243], off
	s_waitcnt lgkmcnt(8)
	v_mfma_f32_32x32x16_bf16 v[80:95], v[226:229], v[152:155], v[80:95]
	v_mfma_f32_32x32x16_bf16 v[64:79], v[226:229], v[156:159], v[64:79]
	ds_read_b64_tr_b16 v[152:153], v245 offset:20480
	ds_read_b64_tr_b16 v[154:155], v245 offset:22528
	ds_read_b64_tr_b16 v[156:157], v245 offset:20992
	ds_read_b64_tr_b16 v[158:159], v245 offset:23040
	v_lshl_add_u64 v[242:243], v[198:199], 0, s[26:27]
	s_add_i32 s41, s86, s24
	s_add_i32 m0, s41, 0xc000
	v_lshl_add_u64 v[242:243], v[242:243], 0, s[14:15]
	global_load_lds_dwordx4 v[242:243], off
	s_waitcnt lgkmcnt(8)
	v_mfma_f32_32x32x16_bf16 v[80:95], v[230:233], v[234:237], v[80:95]
	v_mfma_f32_32x32x16_bf16 v[64:79], v[230:233], v[238:241], v[64:79]
	ds_read_b64_tr_b16 v[234:235], v245 offset:17408
	ds_read_b64_tr_b16 v[236:237], v245 offset:19456
	ds_read_b64_tr_b16 v[238:239], v245 offset:17920
	ds_read_b64_tr_b16 v[240:241], v245 offset:19968
	v_lshl_add_u64 v[242:243], v[200:201], 0, s[26:27]
	s_add_i32 s41, s86, s24
	s_add_i32 m0, s41, 0xe000
	v_lshl_add_u64 v[242:243], v[242:243], 0, s[14:15]
	global_load_lds_dwordx4 v[242:243], off
	s_waitcnt lgkmcnt(8)
	v_mfma_f32_32x32x16_bf16 v[48:63], v[226:229], v[144:147], v[48:63]
	v_mfma_f32_32x32x16_bf16 v[32:47], v[226:229], v[148:151], v[32:47]
	ds_read_b64_tr_b16 v[144:145], v245 offset:21504
	ds_read_b64_tr_b16 v[146:147], v245 offset:23552
	ds_read_b64_tr_b16 v[148:149], v245 offset:22016
	ds_read_b64_tr_b16 v[150:151], v245 offset:24064
	s_waitcnt lgkmcnt(8)
	v_mfma_f32_32x32x16_bf16 v[48:63], v[230:233], v[152:155], v[48:63]
	v_mfma_f32_32x32x16_bf16 v[32:47], v[230:233], v[156:159], v[32:47]
	s_waitcnt lgkmcnt(0)
	v_mfma_f32_32x32x16_bf16 v[16:31], v[226:229], v[234:237], v[16:31]
	v_mfma_f32_32x32x16_bf16 v[0:15], v[226:229], v[238:241], v[0:15]
	v_mfma_f32_32x32x16_bf16 v[16:31], v[230:233], v[144:147], v[16:31]
	v_mfma_f32_32x32x16_bf16 v[0:15], v[230:233], v[148:151], v[0:15]
	s_mov_b32 s87, s84
	s_mov_b32 s84, s85
	s_mov_b32 s85, s86
	s_mov_b32 s86, s87
	v_add_u32_e32 v243, v216, v225
	v_add_u32_e32 v244, v216, v223
	ds_read_b128 v[226:229], v243
	ds_read_b128 v[230:233], v244
	v_add_u32_e32 v243, v216, v222
	v_add_u32_e32 v244, v216, v221
	ds_read_b128 v[234:237], v243
	ds_read_b128 v[238:241], v244
	v_fmamk_f32 v128, v128, 0x3e0293ee, v208
	v_fmamk_f32 v129, v129, 0x3e0293ee, v208
	v_fmamk_f32 v130, v130, 0x3e0293ee, v208
	v_fmamk_f32 v131, v131, 0x3e0293ee, v208
	v_exp_f32_e32 v128, v128
	v_exp_f32_e32 v129, v129
	v_exp_f32_e32 v130, v130
	v_exp_f32_e32 v131, v131
	s_waitcnt lgkmcnt(2)
	v_mfma_f32_32x32x16_bf16 v[144:159], v[226:229], v[188:191], 0
	v_mfma_f32_32x32x16_bf16 v[144:159], v[230:233], v[184:187], v[144:159]
	v_add_u32_e32 v243, v216, v220
	v_add_u32_e32 v244, v216, v219
	ds_read_b128 v[226:229], v243
	ds_read_b128 v[230:233], v244
	v_fmamk_f32 v132, v132, 0x3e0293ee, v208
	v_fmamk_f32 v133, v133, 0x3e0293ee, v208
	v_fmamk_f32 v134, v134, 0x3e0293ee, v208
	v_fmamk_f32 v135, v135, 0x3e0293ee, v208
	v_exp_f32_e32 v132, v132
	v_exp_f32_e32 v133, v133
	v_exp_f32_e32 v134, v134
	v_exp_f32_e32 v135, v135
	v_add_f32_e32 v246, v128, v129
	v_add_f32_e32 v246, v130, v246
	v_add_f32_e32 v246, v131, v246
	s_waitcnt lgkmcnt(2)
; #define SBAR() __builtin_amdgcn_sched_barrier(0)
; #define PVR(S, DA, DB, vbase) do { S[0] = tr_read<v_rd_off(DA, 0, 0)>(vbase); S[1] = tr_read<v_rd_off(DA, 0, 1)>(vbase); S[2] = tr_read<v_rd_off(DB, 0, 0)>(vbase); S[3] = tr_read<v_rd_off(DB, 0, 1)>(vbase); \
;     S[4] = tr_read<v_rd_off(DA, 1, 0)>(vbase); S[5] = tr_read<v_rd_off(DA, 1, 1)>(vbase); S[6] = tr_read<v_rd_off(DB, 1, 0)>(vbase); S[7] = tr_read<v_rd_off(DB, 1, 1)>(vbase); } while (0)
; #define RAWBAR() do { asm volatile("s_waitcnt lgkmcnt(0)" ::: "memory"); __builtin_amdgcn_s_barrier(); asm volatile("" ::: "memory"); } while (0)
; #define RAWBAR() do { asm volatile("s_waitcnt lgkmcnt(0)" ::: "memory"); __builtin_amdgcn_s_barrier(); asm volatile("" ::: "memory"); } while (0)
; #define RAWBAR() do { asm volatile("s_waitcnt lgkmcnt(0)" ::: "memory"); __builtin_amdgcn_s_barrier(); asm volatile("" ::: "memory"); } while (0)
; #define RAWBAR() do { asm volatile("s_waitcnt lgkmcnt(0)" ::: "memory"); __builtin_amdgcn_s_barrier(); asm volatile("" ::: "memory"); } while (0)
; #define RAWBAR() do { asm volatile("s_waitcnt lgkmcnt(0)" ::: "memory"); __builtin_amdgcn_s_barrier(); asm volatile("" ::: "memory"); } while (0)
; template <int MODE> ...
;     ...
;   for (int j = 0; j < NT; ++j) {
;     const int buf = j & 1;
;     if (j + 1 < NT) { STAGE((j + 1) * KVBLK, buf ^ 1); }
;     const char* Kb = K_lds + buf * 16384;
;     f32x16 pe = {}, po = {};
; #pragma unroll
;     for (int d0 = 0; d0 < 8; d0 += 2) {
;       const bf16x8 k0 = *reinterpret_cast<const bf16x8*>(Kb + KSWZ(krow, (d0 * 16 + hi * 8) * 2));
;       const bf16x8 k1 = *reinterpret_cast<const bf16x8*>(Kb + KSWZ(krow, ((d0 + 1) * 16 + hi * 8) * 2));
;       pe = __builtin_amdgcn_mfma_f32_32x32x16_bf16(k0, qr[d0], pe, 0, 0, 0);
;       po = __builtin_amdgcn_mfma_f32_32x32x16_bf16(k1, qr[d0 + 1], po, 0, 0, 0); }
;     const int vo = vb0 + buf * 32768;
;     s16x4 R0_[8], R1_[8];
;     PVR(R0_, 0, 1, vo);
;     f32x16 p;
; #pragma unroll
;     for (int r = 0; r < 16; ++r) p[r] = __builtin_amdgcn_exp2f(fmaf(pe[r] + po[r], C, negMc));
;     float ps = 0.f;
; #pragma unroll
;     for (int r = 0; r < 16; ++r) ps += p[r];
;     lsum += ps;
;     const bf16x8 own0 = pk8(p, 0), own1 = pk8(p, 8);
;     SBAR();
;     PV_TAIL4(o, vo, vo + 16384, own0, own1);
;     asm volatile("s_waitcnt vmcnt(0)" ::: "memory");
;     RAWBAR();
;   }
	v_mfma_f32_32x32x16_bf16 v[144:159], v[234:237], v[180:183], v[144:159]
	v_mfma_f32_32x32x16_bf16 v[144:159], v[238:241], v[176:179], v[144:159]
	v_add_u32_e32 v243, v216, v218
	v_add_u32_e32 v244, v216, v217
	ds_read_b128 v[234:237], v243
	ds_read_b128 v[238:241], v244
	v_fmamk_f32 v136, v136, 0x3e0293ee, v208
	v_fmamk_f32 v137, v137, 0x3e0293ee, v208
	v_fmamk_f32 v138, v138, 0x3e0293ee, v208
	v_fmamk_f32 v139, v139, 0x3e0293ee, v208
	v_exp_f32_e32 v136, v136
	v_exp_f32_e32 v137, v137
	v_exp_f32_e32 v138, v138
	v_exp_f32_e32 v139, v139
	v_add_f32_e32 v246, v132, v246
	v_add_f32_e32 v246, v133, v246
	v_add_f32_e32 v246, v134, v246
	v_add_f32_e32 v246, v135, v246
	s_waitcnt lgkmcnt(2)
	v_mfma_f32_32x32x16_bf16 v[144:159], v[226:229], v[172:175], v[144:159]
	v_mfma_f32_32x32x16_bf16 v[144:159], v[230:233], v[168:171], v[144:159]
	v_fmamk_f32 v140, v140, 0x3e0293ee, v208
	v_fmamk_f32 v141, v141, 0x3e0293ee, v208
	v_fmamk_f32 v142, v142, 0x3e0293ee, v208
	v_fmamk_f32 v143, v143, 0x3e0293ee, v208
	v_exp_f32_e32 v140, v140
	v_exp_f32_e32 v141, v141
	v_exp_f32_e32 v142, v142
	v_exp_f32_e32 v143, v143
	v_add_f32_e32 v246, v136, v246
	v_add_f32_e32 v246, v137, v246
	v_add_f32_e32 v246, v138, v246
	v_add_f32_e32 v246, v139, v246
	v_cvt_pk_bf16_f32 v226, v128, v129
	v_cvt_pk_bf16_f32 v227, v130, v131
	v_cvt_pk_bf16_f32 v228, v132, v133
	v_cvt_pk_bf16_f32 v229, v134, v135
	s_waitcnt lgkmcnt(0)
	v_mfma_f32_32x32x16_bf16 v[144:159], v[234:237], v[164:167], v[144:159]
	v_mfma_f32_32x32x16_bf16 v[144:159], v[238:241], v[160:163], v[144:159]
	s_waitcnt vmcnt(0)
	s_barrier
	v_lshl_add_u64 v[198:199], v[198:199], 0, s[16:17]
	v_lshl_add_u64 v[200:201], v[200:201], 0, s[16:17]
	v_lshl_add_u64 v[202:203], v[202:203], 0, s[18:19]
	v_lshl_add_u64 v[204:205], v[204:205], 0, s[18:19]
	v_lshl_add_u64 v[128:129], v[202:203], 0, s[26:27]
	s_mov_b32 m0, s24
	v_lshl_add_u64 v[130:131], v[204:205], 0, s[26:27]
	global_load_lds_dwordx4 v[128:129], off
	s_add_i32 m0, s24, 0x2000
	s_nop 0
	global_load_lds_dwordx4 v[130:131], off
	v_add_u32_e32 v245, s84, v214
	ds_read_b64_tr_b16 v[234:235], v245 offset:0
	ds_read_b64_tr_b16 v[236:237], v245 offset:2048
	ds_read_b64_tr_b16 v[238:239], v245 offset:512
	ds_read_b64_tr_b16 v[240:241], v245 offset:2560
	v_permlane32_swap_b32_e32 v226, v228
	v_permlane32_swap_b32_e32 v227, v229
	ds_read_b64_tr_b16 v[128:129], v245 offset:4096
	ds_read_b64_tr_b16 v[130:131], v245 offset:6144
	ds_read_b64_tr_b16 v[132:133], v245 offset:4608
	ds_read_b64_tr_b16 v[134:135], v245 offset:6656
	v_add_f32_e32 v246, v140, v246
	v_add_f32_e32 v246, v141, v246
	v_add_f32_e32 v246, v142, v246
	v_add_f32_e32 v246, v143, v246
	v_cvt_pk_bf16_f32 v230, v136, v137
	v_cvt_pk_bf16_f32 v231, v138, v139
	v_cvt_pk_bf16_f32 v232, v140, v141
	v_cvt_pk_bf16_f32 v233, v142, v143
	v_add_f32_e32 v215, v215, v246
	ds_read_b64_tr_b16 v[136:137], v245 offset:1024
	ds_read_b64_tr_b16 v[138:139], v245 offset:3072
	ds_read_b64_tr_b16 v[140:141], v245 offset:1536
	ds_read_b64_tr_b16 v[142:143], v245 offset:3584
	v_permlane32_swap_b32_e32 v230, v232
	v_permlane32_swap_b32_e32 v231, v233
	s_waitcnt lgkmcnt(8)
	v_mfma_f32_32x32x16_bf16 v[112:127], v[226:229], v[234:237], v[112:127]
	v_mfma_f32_32x32x16_bf16 v[96:111], v[226:229], v[238:241], v[96:111]
	ds_read_b64_tr_b16 v[234:235], v245 offset:5120
	ds_read_b64_tr_b16 v[236:237], v245 offset:7168
	ds_read_b64_tr_b16 v[238:239], v245 offset:5632
	ds_read_b64_tr_b16 v[240:241], v245 offset:7680
	v_lshl_add_u64 v[242:243], v[198:199], 0, s[26:27]
	s_add_i32 s41, s86, s24
	s_add_i32 m0, s41, 0x8000
	v_lshl_add_u64 v[242:243], v[242:243], 0, s[12:13]
	global_load_lds_dwordx4 v[242:243], off
	s_waitcnt lgkmcnt(8)
	v_mfma_f32_32x32x16_bf16 v[112:127], v[230:233], v[128:131], v[112:127]
	v_mfma_f32_32x32x16_bf16 v[96:111], v[230:233], v[132:135], v[96:111]
	ds_read_b64_tr_b16 v[128:129], v245 offset:16384
	ds_read_b64_tr_b16 v[130:131], v245 offset:18432
	ds_read_b64_tr_b16 v[132:133], v245 offset:16896
	ds_read_b64_tr_b16 v[134:135], v245 offset:18944
	v_lshl_add_u64 v[242:243], v[200:201], 0, s[26:27]
	s_add_i32 s41, s86, s24
	s_add_i32 m0, s41, 0xa000
	v_lshl_add_u64 v[242:243], v[242:243], 0, s[12:13]
	global_load_lds_dwordx4 v[242:243], off
	s_waitcnt lgkmcnt(8)
	v_mfma_f32_32x32x16_bf16 v[80:95], v[226:229], v[136:139], v[80:95]
	v_mfma_f32_32x32x16_bf16 v[64:79], v[226:229], v[140:143], v[64:79]
	ds_read_b64_tr_b16 v[136:137], v245 offset:20480
	ds_read_b64_tr_b16 v[138:139], v245 offset:22528
	ds_read_b64_tr_b16 v[140:141], v245 offset:20992
	ds_read_b64_tr_b16 v[142:143], v245 offset:23040
	v_lshl_add_u64 v[242:243], v[198:199], 0, s[26:27]
	s_add_i32 s41, s86, s24
	s_add_i32 m0, s41, 0xc000
	v_lshl_add_u64 v[242:243], v[242:243], 0, s[14:15]
	global_load_lds_dwordx4 v[242:243], off
	s_waitcnt lgkmcnt(8)
	v_mfma_f32_32x32x16_bf16 v[80:95], v[230:233], v[234:237], v[80:95]
	v_mfma_f32_32x32x16_bf16 v[64:79], v[230:233], v[238:241], v[64:79]
	ds_read_b64_tr_b16 v[234:235], v245 offset:17408
	ds_read_b64_tr_b16 v[236:237], v245 offset:19456
	ds_read_b64_tr_b16 v[238:239], v245 offset:17920
	ds_read_b64_tr_b16 v[240:241], v245 offset:19968
	v_lshl_add_u64 v[242:243], v[200:201], 0, s[26:27]
	s_add_i32 s41, s86, s24
	s_add_i32 m0, s41, 0xe000
	v_lshl_add_u64 v[242:243], v[242:243], 0, s[14:15]
	global_load_lds_dwordx4 v[242:243], off
	s_waitcnt lgkmcnt(8)
	v_mfma_f32_32x32x16_bf16 v[48:63], v[226:229], v[128:131], v[48:63]
	v_mfma_f32_32x32x16_bf16 v[32:47], v[226:229], v[132:135], v[32:47]
	ds_read_b64_tr_b16 v[128:129], v245 offset:21504
	ds_read_b64_tr_b16 v[130:131], v245 offset:23552
	ds_read_b64_tr_b16 v[132:133], v245 offset:22016
	ds_read_b64_tr_b16 v[134:135], v245 offset:24064
	s_waitcnt lgkmcnt(8)
	v_mfma_f32_32x32x16_bf16 v[48:63], v[230:233], v[136:139], v[48:63]
	v_mfma_f32_32x32x16_bf16 v[32:47], v[230:233], v[140:143], v[32:47]
	s_waitcnt lgkmcnt(0)
	v_mfma_f32_32x32x16_bf16 v[16:31], v[226:229], v[234:237], v[16:31]
	v_mfma_f32_32x32x16_bf16 v[0:15], v[226:229], v[238:241], v[0:15]
	v_mfma_f32_32x32x16_bf16 v[16:31], v[230:233], v[128:131], v[16:31]
	v_mfma_f32_32x32x16_bf16 v[0:15], v[230:233], v[132:135], v[0:15]
	s_mov_b32 s87, s84
	s_mov_b32 s84, s85
	s_mov_b32 s85, s86
	s_mov_b32 s86, s87
	s_add_i32 s25, s25, 1
	s_cmpk_eq_i32 s25, 0x82
	s_cbranch_scc0 .LattnB_m0
	s_waitcnt vmcnt(0)
	s_barrier
; #define XS_WRITE(OV, BASE) do { float* xs_ = (float*)(lds + (BASE)) + ((g * 4) * 64 + lane) * 16; \
;     _Pragma("unroll") for (int d0 = 0; d0 < 4; ++d0) { float* xp = xs_ + d0 * 64 * 16; \
;       _Pragma("unroll") for (int q4 = 0; q4 < 4; ++q4) *(f32x4v*)(xp + 4 * q4) = (f32x4v){OV[d0][4 * q4], OV[d0][4 * q4 + 1], OV[d0][4 * q4 + 2], OV[d0][4 * q4 + 3]}; } } while (0)
; #define XS_WRITE(OV, BASE) do { float* xs_ = (float*)(lds + (BASE)) + ((g * 4) * 64 + lane) * 16; \
;     _Pragma("unroll") for (int d0 = 0; d0 < 4; ++d0) { float* xp = xs_ + d0 * 64 * 16; \
;       _Pragma("unroll") for (int q4 = 0; q4 < 4; ++q4) *(f32x4v*)(xp + 4 * q4) = (f32x4v){OV[d0][4 * q4], OV[d0][4 * q4 + 1], OV[d0][4 * q4 + 2], OV[d0][4 * q4 + 3]}; } } while (0)
; template <int MODE> ...
;     ...
;   __builtin_amdgcn_s_setprio(0);
;   L_lds[(wid * 2 + hi) * 32 + r32] = lsum;
;     ...
;   f32x16* olo = o; f32x16* ohi = o + 4;
;   if (kh) { XS_WRITE(olo, 0); } else { XS_WRITE(ohi, 65536); }
;   __syncthreads();
;   if (kh) { XS_ADD(ohi, 65536);
; #pragma unroll
;     for (int d0 = 0; d0 < 4; ++d0) o[d0] = o[4 + d0]; }
;   else { XS_ADD(olo, 0); }
.Lattn_join_m0:
	v_mov_b32_e32 v172, v215
	s_setprio 0
	v_lshl_add_u32 v128, v197, 2, 0
	v_add_u32_e32 v128, 0x20000, v128
	v_mov_b32_e32 v129, s65
	v_cmp_eq_u32_e32 vcc, 0, v211
	ds_write_b32 v128, v172
	v_lshlrev_b32_e32 v128, 14, v213
	v_cndmask_b32_e32 v131, 0, v129, vcc
	v_lshlrev_b32_e32 v130, 2, v212
	v_cndmask_b32_e32 v147, v115, v51, vcc
	v_cndmask_b32_e32 v146, v114, v50, vcc
	v_cndmask_b32_e32 v145, v113, v49, vcc
	v_cndmask_b32_e32 v144, v112, v48, vcc
	v_add3_u32 v131, v131, v128, v130
	v_cndmask_b32_e32 v135, v127, v63, vcc
	v_cndmask_b32_e32 v134, v126, v62, vcc
	v_cndmask_b32_e32 v133, v125, v61, vcc
	v_cndmask_b32_e32 v132, v124, v60, vcc
	v_cndmask_b32_e32 v139, v123, v59, vcc
	v_cndmask_b32_e32 v138, v122, v58, vcc
	v_cndmask_b32_e32 v137, v121, v57, vcc
	v_cndmask_b32_e32 v136, v120, v56, vcc
	v_cndmask_b32_e32 v143, v119, v55, vcc
	v_cndmask_b32_e32 v142, v118, v54, vcc
	v_cndmask_b32_e32 v141, v117, v53, vcc
	v_cndmask_b32_e32 v140, v116, v52, vcc
	v_cndmask_b32_e32 v151, v111, v47, vcc
	v_cndmask_b32_e32 v150, v110, v46, vcc
	v_cndmask_b32_e32 v149, v109, v45, vcc
	v_cndmask_b32_e32 v148, v108, v44, vcc
	v_cndmask_b32_e32 v155, v107, v43, vcc
	v_cndmask_b32_e32 v154, v106, v42, vcc
	v_cndmask_b32_e32 v153, v105, v41, vcc
	v_cndmask_b32_e32 v152, v104, v40, vcc
	v_cndmask_b32_e32 v159, v103, v39, vcc
	v_cndmask_b32_e32 v158, v102, v38, vcc
	v_cndmask_b32_e32 v157, v101, v37, vcc
	v_cndmask_b32_e32 v156, v100, v36, vcc
	v_cndmask_b32_e32 v163, v99, v35, vcc
	v_cndmask_b32_e32 v162, v98, v34, vcc
	v_cndmask_b32_e32 v161, v97, v33, vcc
	v_cndmask_b32_e32 v160, v96, v32, vcc
	v_cndmask_b32_e32 v167, v95, v31, vcc
	v_cndmask_b32_e32 v166, v94, v30, vcc
	v_cndmask_b32_e32 v165, v93, v29, vcc
	v_cndmask_b32_e32 v164, v92, v28, vcc
	v_cndmask_b32_e32 v171, v91, v27, vcc
	v_cndmask_b32_e32 v170, v90, v26, vcc
	v_cndmask_b32_e32 v169, v89, v25, vcc
	v_cndmask_b32_e32 v168, v88, v24, vcc
	v_cndmask_b32_e32 v175, v87, v23, vcc
	v_cndmask_b32_e32 v174, v86, v22, vcc
	v_cndmask_b32_e32 v173, v85, v21, vcc
	v_cndmask_b32_e32 v172, v84, v20, vcc
	v_cndmask_b32_e32 v179, v83, v19, vcc
	v_cndmask_b32_e32 v178, v82, v18, vcc
	v_cndmask_b32_e32 v177, v81, v17, vcc
	v_cndmask_b32_e32 v176, v80, v16, vcc
	v_cndmask_b32_e32 v183, v79, v15, vcc
	v_cndmask_b32_e32 v182, v78, v14, vcc
	v_cndmask_b32_e32 v181, v77, v13, vcc
	v_cndmask_b32_e32 v180, v76, v12, vcc
	v_cndmask_b32_e32 v187, v75, v11, vcc
	v_cndmask_b32_e32 v186, v74, v10, vcc
	v_cndmask_b32_e32 v185, v73, v9, vcc
	v_cndmask_b32_e32 v184, v72, v8, vcc
	v_cndmask_b32_e32 v191, v71, v7, vcc
	v_cndmask_b32_e32 v190, v70, v6, vcc
	v_cndmask_b32_e32 v189, v69, v5, vcc
	v_cndmask_b32_e32 v188, v68, v4, vcc
	v_cndmask_b32_e32 v201, v67, v3, vcc
	v_cndmask_b32_e32 v200, v66, v2, vcc
	v_cndmask_b32_e32 v199, v65, v1, vcc
	v_cndmask_b32_e32 v198, v64, v0, vcc
	ds_write_b128 v131, v[144:147]
	ds_write_b128 v131, v[140:143] offset:16
	ds_write_b128 v131, v[136:139] offset:32
	ds_write_b128 v131, v[132:135] offset:48
	ds_write_b128 v131, v[160:163] offset:4096
	ds_write_b128 v131, v[156:159] offset:4112
	ds_write_b128 v131, v[152:155] offset:4128
	ds_write_b128 v131, v[148:151] offset:4144
	ds_write_b128 v131, v[176:179] offset:8192
	ds_write_b128 v131, v[172:175] offset:8208
	ds_write_b128 v131, v[168:171] offset:8224
	ds_write_b128 v131, v[164:167] offset:8240
	ds_write_b128 v131, v[198:201] offset:12288
	ds_write_b128 v131, v[188:191] offset:12304
	ds_write_b128 v131, v[184:187] offset:12320
	ds_write_b128 v131, v[180:183] offset:12336
	s_waitcnt vmcnt(0) lgkmcnt(0)
	s_barrier
	s_and_saveexec_b64 s[24:25], vcc
	s_cbranch_execz .LBB0_1022
	v_mov_b64_e32 v[48:49], v[112:113]
	v_mov_b64_e32 v[32:33], v[96:97]
	v_mov_b64_e32 v[16:17], v[80:81]
	v_mov_b64_e32 v[0:1], v[64:65]
	v_mov_b32_e32 v129, 0
	v_mov_b64_e32 v[50:51], v[114:115]
	v_mov_b64_e32 v[52:53], v[116:117]
	v_mov_b64_e32 v[54:55], v[118:119]
	v_mov_b64_e32 v[56:57], v[120:121]
	v_mov_b64_e32 v[58:59], v[122:123]
	v_mov_b64_e32 v[60:61], v[124:125]
	v_mov_b64_e32 v[62:63], v[126:127]
	v_mov_b64_e32 v[34:35], v[98:99]
	v_mov_b64_e32 v[36:37], v[100:101]
	v_mov_b64_e32 v[38:39], v[102:103]
	v_mov_b64_e32 v[40:41], v[104:105]
	v_mov_b64_e32 v[42:43], v[106:107]
	v_mov_b64_e32 v[44:45], v[108:109]
	v_mov_b64_e32 v[46:47], v[110:111]
	v_mov_b64_e32 v[18:19], v[82:83]
	v_mov_b64_e32 v[20:21], v[84:85]
	v_mov_b64_e32 v[22:23], v[86:87]
	v_mov_b64_e32 v[24:25], v[88:89]
	v_mov_b64_e32 v[26:27], v[90:91]
	v_mov_b64_e32 v[28:29], v[92:93]
	v_mov_b64_e32 v[30:31], v[94:95]
	v_mov_b64_e32 v[2:3], v[66:67]
	v_mov_b64_e32 v[4:5], v[68:69]
	v_mov_b64_e32 v[6:7], v[70:71]
	v_mov_b64_e32 v[8:9], v[72:73]
	v_mov_b64_e32 v[10:11], v[74:75]
	v_mov_b64_e32 v[12:13], v[76:77]
	v_mov_b64_e32 v[14:15], v[78:79]
; __device__ __forceinline__ int crow(int r, int hi) { return (r & 3) + 8 * (r >> 2) + 4 * hi; }
; template <int MODE> ...
;     ...
;   if (kh) { XS_ADD(ohi, 65536);
; #pragma unroll
;     for (int d0 = 0; d0 < 4; ++d0) o[d0] = o[4 + d0]; }
;   else { XS_ADD(olo, 0); }
;     ...
;   float rli[16];
; #pragma unroll
;   for (int r = 0; r < 16; ++r) { const int row = crow(r, hi); const float* lp = L_lds + (g * 4) * 32 + row; rli[r] = __builtin_amdgcn_rcpf((lp[0] + lp[32]) + (lp[64] + lp[96])); }
.LBB0_1022:
	s_or_b64 exec, exec, s[24:25]
	v_add3_u32 v80, v129, v128, v130
	ds_read_b128 v[64:67], v80
	ds_read_b128 v[68:71], v80 offset:16
	ds_read_b128 v[72:75], v80 offset:32
	ds_read_b128 v[76:79], v80 offset:48
	s_ashr_i32 s24, s40, 3
	s_ashr_i32 s25, s24, 31
	s_waitcnt lgkmcnt(2)
	v_add_f32_e32 v68, v52, v68
	v_add_f32_e32 v64, v48, v64
	v_add_f32_e32 v65, v49, v65
	v_add_f32_e32 v66, v50, v66
	v_add_f32_e32 v67, v51, v67
	ds_read_b128 v[48:51], v80 offset:4096
	v_add_f32_e32 v69, v53, v69
	v_add_f32_e32 v70, v54, v70
	v_add_f32_e32 v71, v55, v71
	ds_read_b128 v[52:55], v80 offset:4112
	s_waitcnt lgkmcnt(1)
	v_add_f32_e32 v48, v32, v48
	v_add_f32_e32 v49, v33, v49
	v_add_f32_e32 v50, v34, v50
	v_add_f32_e32 v51, v35, v51
	ds_read_b128 v[32:35], v80 offset:4128
	s_waitcnt lgkmcnt(1)
	v_add_f32_e32 v52, v36, v52
	v_add_f32_e32 v53, v37, v53
	v_add_f32_e32 v54, v38, v54
	v_add_f32_e32 v55, v39, v55
	ds_read_b128 v[36:39], v80 offset:4144
	s_waitcnt lgkmcnt(1)
	v_add_f32_e32 v40, v40, v32
	v_add_f32_e32 v41, v41, v33
	v_add_f32_e32 v42, v42, v34
	v_add_f32_e32 v43, v43, v35
	ds_read_b128 v[32:35], v80 offset:8192
	s_waitcnt lgkmcnt(1)
	v_add_f32_e32 v44, v44, v36
	v_add_f32_e32 v45, v45, v37
	v_add_f32_e32 v46, v46, v38
	v_add_f32_e32 v47, v47, v39
	ds_read_b128 v[36:39], v80 offset:8208
	s_waitcnt lgkmcnt(1)
	v_add_f32_e32 v32, v16, v32
	v_add_f32_e32 v33, v17, v33
	v_add_f32_e32 v34, v18, v34
	v_add_f32_e32 v35, v19, v35
	ds_read_b128 v[16:19], v80 offset:8224
	s_waitcnt lgkmcnt(1)
	v_add_f32_e32 v36, v20, v36
	v_add_f32_e32 v37, v21, v37
	v_add_f32_e32 v38, v22, v38
	v_add_f32_e32 v39, v23, v39
	ds_read_b128 v[20:23], v80 offset:8240
	v_add_f32_e32 v56, v56, v72
	v_add_f32_e32 v57, v57, v73
	v_add_f32_e32 v58, v58, v74
	v_add_f32_e32 v59, v59, v75
	s_waitcnt lgkmcnt(1)
	v_add_f32_e32 v72, v24, v16
	v_add_f32_e32 v73, v25, v17
	v_add_f32_e32 v74, v26, v18
	v_add_f32_e32 v75, v27, v19
	ds_read_b128 v[16:19], v80 offset:12288
	v_add_f32_e32 v60, v60, v76
	v_add_f32_e32 v61, v61, v77
	v_add_f32_e32 v62, v62, v78
	v_add_f32_e32 v63, v63, v79
	s_waitcnt lgkmcnt(1)
	v_add_f32_e32 v76, v28, v20
	v_add_f32_e32 v77, v29, v21
	v_add_f32_e32 v78, v30, v22
	v_add_f32_e32 v79, v31, v23
	ds_read_b128 v[20:23], v80 offset:12304
	s_lshl_b32 s2, s40, 8
	s_and_b32 s94, s2, 0x700
	s_lshl_b64 s[2:3], s[24:25], 27
	s_lshl_b64 s[28:29], s[28:29], 20
	s_waitcnt lgkmcnt(1)
	v_add_f32_e32 v81, v0, v16
	v_add_f32_e32 v82, v1, v17
	v_add_f32_e32 v83, v2, v18
	v_add_f32_e32 v84, v3, v19
	ds_read_b128 v[0:3], v80 offset:12320
	s_add_u32 s2, s38, s2
	s_addc_u32 s3, s39, s3
	s_add_u32 s2, s2, s28
	s_waitcnt lgkmcnt(1)
	v_add_f32_e32 v85, v4, v20
	v_add_f32_e32 v86, v5, v21
	v_add_f32_e32 v87, v6, v22
	v_add_f32_e32 v88, v7, v23
	ds_read_b128 v[4:7], v80 offset:12336
	s_addc_u32 s3, s3, s29
	s_lshl_b32 s25, s94, 2
	s_add_u32 s28, s2, s25
	s_waitcnt lgkmcnt(1)
	v_add_f32_e32 v80, v8, v0
	v_and_b32_e32 v0, 0x3fffff80, v197
	s_addc_u32 s29, s3, 0
	v_lshlrev_b32_e32 v0, 2, v0
	s_add_i32 s25, 0, 0x20000
	v_add3_u32 v96, s25, v0, v194
	v_add_f32_e32 v89, v9, v1
	v_add_f32_e32 v90, v10, v2
	v_add_f32_e32 v91, v11, v3
	s_waitcnt lgkmcnt(0)
	v_add_f32_e32 v92, v12, v4
	v_add_f32_e32 v93, v13, v5
	v_add_f32_e32 v94, v14, v6
	v_add_f32_e32 v95, v15, v7
	ds_read_b128 v[0:3], v96 offset:128
	ds_read_b128 v[4:7], v96
	ds_read_b128 v[8:11], v96 offset:32
	ds_read_b128 v[12:15], v96 offset:256
	ds_read_b128 v[16:19], v96 offset:384
	ds_read_b128 v[20:23], v96 offset:160
	s_waitcnt lgkmcnt(4)
	v_add_f32_e32 v0, v4, v0
	ds_read_b128 v[24:27], v96 offset:288
	ds_read_b128 v[28:31], v96 offset:416
	v_ashrrev_i32_e32 v197, 31, v196
	s_waitcnt lgkmcnt(3)
	v_add_f32_e32 v4, v12, v16
	v_add_f32_e32 v0, v0, v4
	v_rcp_f32_e32 v97, v0
	v_add_f32_e32 v0, v5, v1
	v_add_f32_e32 v1, v13, v17
	v_add_f32_e32 v0, v0, v1
	v_rcp_f32_e32 v98, v0
	v_add_f32_e32 v0, v6, v2
	v_add_f32_e32 v1, v14, v18
	v_add_f32_e32 v0, v0, v1
	v_rcp_f32_e32 v99, v0
	v_add_f32_e32 v0, v7, v3
	v_add_f32_e32 v1, v15, v19
	v_add_f32_e32 v0, v0, v1
	v_rcp_f32_e32 v100, v0
	s_waitcnt lgkmcnt(2)
	v_add_f32_e32 v0, v8, v20
	s_waitcnt lgkmcnt(0)
	v_add_f32_e32 v1, v24, v28
	v_add_f32_e32 v0, v0, v1
	v_rcp_f32_e32 v101, v0
	v_add_f32_e32 v0, v9, v21
	v_add_f32_e32 v1, v25, v29
	v_add_f32_e32 v0, v0, v1
	v_rcp_f32_e32 v102, v0
	v_add_f32_e32 v0, v10, v22
	v_add_f32_e32 v1, v26, v30
	v_add_f32_e32 v0, v0, v1
	v_rcp_f32_e32 v103, v0
	v_add_f32_e32 v0, v11, v23
	v_add_f32_e32 v1, v27, v31
	v_add_f32_e32 v0, v0, v1
	v_rcp_f32_e32 v104, v0
	ds_read_b128 v[0:3], v96 offset:64
	ds_read_b128 v[4:7], v96 offset:192
	ds_read_b128 v[8:11], v96 offset:320
	ds_read_b128 v[12:15], v96 offset:448
	ds_read_b128 v[16:19], v96 offset:96
	ds_read_b128 v[20:23], v96 offset:224
	s_waitcnt lgkmcnt(4)
	v_add_f32_e32 v0, v0, v4
	ds_read_b128 v[24:27], v96 offset:352
	ds_read_b128 v[28:31], v96 offset:480
	s_waitcnt lgkmcnt(4)
	v_add_f32_e32 v4, v8, v12
	v_add_f32_e32 v0, v0, v4
	v_rcp_f32_e32 v4, v0
	v_add_f32_e32 v0, v1, v5
	v_add_f32_e32 v1, v9, v13
	v_add_f32_e32 v0, v0, v1
	v_rcp_f32_e32 v5, v0
	v_add_f32_e32 v0, v2, v6
	v_add_f32_e32 v1, v10, v14
	v_add_f32_e32 v0, v0, v1
	v_rcp_f32_e32 v6, v0
	v_add_f32_e32 v0, v3, v7
	v_add_f32_e32 v1, v11, v15
	v_add_f32_e32 v0, v0, v1
	v_rcp_f32_e32 v7, v0
	s_waitcnt lgkmcnt(2)
	v_add_f32_e32 v0, v16, v20
	s_waitcnt lgkmcnt(0)
; __device__ __forceinline__ int crow(int r, int hi) { return (r & 3) + 8 * (r >> 2) + 4 * hi; }
; template <int MODE> ...
;     ...
;   for (int r = 0; r < 16; ++r) { const int row = crow(r, hi); const float* lp = L_lds + (g * 4) * 32 + row; rli[r] = __builtin_amdgcn_rcpf((lp[0] + lp[32]) + (lp[64] + lp[96])); }
;   float* Ow = Ob + (long)(g * 32) * LDO + kh * 128;
;   if (MODE == 0) {
; #pragma unroll
;     for (int r = 0; r < 16; ++r) { const int orow = crow(r, hi);
; #pragma unroll
;       for (int d0 = 0; d0 < 4; ++d0) Ow[(long)orow * LDO + d0 * 32 + r32] = o[d0][r] * rli[r]; }
;     asm volatile("s_waitcnt vmcnt(0)" ::: "memory"); __syncthreads();
	v_add_f32_e32 v1, v24, v28
	v_add_f32_e32 v0, v0, v1
	v_rcp_f32_e32 v8, v0
	v_add_f32_e32 v0, v17, v21
	v_add_f32_e32 v1, v25, v29
	v_add_f32_e32 v0, v0, v1
	v_rcp_f32_e32 v9, v0
	v_add_f32_e32 v0, v18, v22
	v_add_f32_e32 v1, v26, v30
	v_add_f32_e32 v0, v0, v1
	v_rcp_f32_e32 v10, v0
	v_add_f32_e32 v0, v19, v23
	v_add_f32_e32 v1, v27, v31
	v_add_f32_e32 v0, v0, v1
	v_rcp_f32_e32 v11, v0
	v_lshlrev_b64 v[0:1], 13, v[196:197]
	v_lshl_add_u64 v[0:1], s[28:29], 0, v[0:1]
	v_lshlrev_b32_e32 v194, 9, v211
	v_lshl_add_u64 v[0:1], v[0:1], 0, v[194:195]
	v_lshlrev_b32_e32 v194, 2, v206
	v_lshlrev_b32_e32 v2, 15, v207
	v_lshl_add_u64 v[0:1], v[0:1], 0, v[194:195]
	v_mov_b32_e32 v3, v195
	v_lshl_add_u64 v[0:1], v[0:1], 0, v[2:3]
	v_mul_f32_e32 v2, v64, v97
	global_store_dword v[0:1], v2, off
	v_mul_f32_e32 v2, v48, v97
	global_store_dword v[0:1], v2, off offset:128
	v_mul_f32_e32 v2, v32, v97
	global_store_dword v[0:1], v2, off offset:256
	v_mul_f32_e32 v2, v81, v97
	global_store_dword v[0:1], v2, off offset:384
	v_add_co_u32_e32 v2, vcc, s57, v0
	v_mul_f32_e32 v12, v65, v98
	s_nop 0
	v_addc_co_u32_e32 v3, vcc, 0, v1, vcc
	global_store_dword v[2:3], v12, off
	v_mul_f32_e32 v12, v49, v98
	global_store_dword v[2:3], v12, off offset:128
	v_mul_f32_e32 v12, v33, v98
	global_store_dword v[2:3], v12, off offset:256
	v_mul_f32_e32 v12, v82, v98
	global_store_dword v[2:3], v12, off offset:384
	v_add_co_u32_e32 v2, vcc, s62, v0
	v_mul_f32_e32 v12, v66, v99
	s_nop 0
	v_addc_co_u32_e32 v3, vcc, 0, v1, vcc
	global_store_dword v[2:3], v12, off
	v_mul_f32_e32 v12, v50, v99
	global_store_dword v[2:3], v12, off offset:128
	v_mul_f32_e32 v12, v34, v99
	global_store_dword v[2:3], v12, off offset:256
	v_mul_f32_e32 v12, v83, v99
	global_store_dword v[2:3], v12, off offset:384
	v_add_co_u32_e32 v2, vcc, s66, v0
	v_mul_f32_e32 v12, v67, v100
	s_nop 0
	v_addc_co_u32_e32 v3, vcc, 0, v1, vcc
	global_store_dword v[2:3], v12, off
	v_mul_f32_e32 v12, v51, v100
	global_store_dword v[2:3], v12, off offset:128
	v_mul_f32_e32 v12, v35, v100
	global_store_dword v[2:3], v12, off offset:256
	v_mul_f32_e32 v12, v84, v100
	global_store_dword v[2:3], v12, off offset:384
	v_add_co_u32_e32 v2, vcc, s64, v0
	v_mul_f32_e32 v12, v68, v101
	s_nop 0
	v_addc_co_u32_e32 v3, vcc, 0, v1, vcc
	global_store_dword v[2:3], v12, off
	v_mul_f32_e32 v12, v52, v101
	global_store_dword v[2:3], v12, off offset:128
	v_mul_f32_e32 v12, v36, v101
	global_store_dword v[2:3], v12, off offset:256
	v_mul_f32_e32 v12, v85, v101
	global_store_dword v[2:3], v12, off offset:384
	v_add_co_u32_e32 v2, vcc, s67, v0
	v_mul_f32_e32 v12, v69, v102
	s_nop 0
	v_addc_co_u32_e32 v3, vcc, 0, v1, vcc
	global_store_dword v[2:3], v12, off
	v_mul_f32_e32 v12, v53, v102
	global_store_dword v[2:3], v12, off offset:128
	v_mul_f32_e32 v12, v37, v102
	global_store_dword v[2:3], v12, off offset:256
	v_mul_f32_e32 v12, v86, v102
	global_store_dword v[2:3], v12, off offset:384
	v_add_co_u32_e32 v2, vcc, s68, v0
	v_mul_f32_e32 v12, v70, v103
	s_nop 0
	v_addc_co_u32_e32 v3, vcc, 0, v1, vcc
	global_store_dword v[2:3], v12, off
	v_mul_f32_e32 v12, v54, v103
	global_store_dword v[2:3], v12, off offset:128
	v_mul_f32_e32 v12, v38, v103
	global_store_dword v[2:3], v12, off offset:256
	v_mul_f32_e32 v12, v87, v103
	global_store_dword v[2:3], v12, off offset:384
	v_add_co_u32_e32 v2, vcc, s69, v0
	v_mul_f32_e32 v12, v71, v104
	s_nop 0
	v_addc_co_u32_e32 v3, vcc, 0, v1, vcc
	global_store_dword v[2:3], v12, off
	v_mul_f32_e32 v12, v55, v104
	global_store_dword v[2:3], v12, off offset:128
	v_mul_f32_e32 v12, v39, v104
	global_store_dword v[2:3], v12, off offset:256
	v_mul_f32_e32 v12, v88, v104
	global_store_dword v[2:3], v12, off offset:384
	v_add_co_u32_e32 v2, vcc, s63, v0
	v_mul_f32_e32 v12, v56, v4
	s_nop 0
	v_addc_co_u32_e32 v3, vcc, 0, v1, vcc
	global_store_dword v[2:3], v12, off
	v_mul_f32_e32 v12, v40, v4
	global_store_dword v[2:3], v12, off offset:128
	v_mul_f32_e32 v12, v72, v4
	v_mul_f32_e32 v4, v80, v4
	global_store_dword v[2:3], v12, off offset:256
	global_store_dword v[2:3], v4, off offset:384
	v_add_co_u32_e32 v2, vcc, s70, v0
	v_mul_f32_e32 v4, v57, v5
	s_nop 0
	v_addc_co_u32_e32 v3, vcc, 0, v1, vcc
	global_store_dword v[2:3], v4, off
	v_mul_f32_e32 v4, v41, v5
	global_store_dword v[2:3], v4, off offset:128
	v_mul_f32_e32 v4, v73, v5
	global_store_dword v[2:3], v4, off offset:256
	v_mul_f32_e32 v4, v89, v5
	global_store_dword v[2:3], v4, off offset:384
	v_add_co_u32_e32 v2, vcc, s71, v0
	v_mul_f32_e32 v4, v58, v6
	s_nop 0
	v_addc_co_u32_e32 v3, vcc, 0, v1, vcc
	global_store_dword v[2:3], v4, off
	v_mul_f32_e32 v4, v42, v6
	global_store_dword v[2:3], v4, off offset:128
	v_mul_f32_e32 v4, v74, v6
	global_store_dword v[2:3], v4, off offset:256
	v_mul_f32_e32 v4, v90, v6
	global_store_dword v[2:3], v4, off offset:384
	v_add_co_u32_e32 v2, vcc, s72, v0
	v_mul_f32_e32 v4, v59, v7
	s_nop 0
	v_addc_co_u32_e32 v3, vcc, 0, v1, vcc
	global_store_dword v[2:3], v4, off
	v_mul_f32_e32 v4, v43, v7
	global_store_dword v[2:3], v4, off offset:128
	v_mul_f32_e32 v4, v75, v7
	global_store_dword v[2:3], v4, off offset:256
	v_mul_f32_e32 v4, v91, v7
	global_store_dword v[2:3], v4, off offset:384
	v_add_co_u32_e32 v2, vcc, s73, v0
	v_mul_f32_e32 v4, v60, v8
	s_nop 0
	v_addc_co_u32_e32 v3, vcc, 0, v1, vcc
	global_store_dword v[2:3], v4, off
	v_mul_f32_e32 v4, v44, v8
	global_store_dword v[2:3], v4, off offset:128
	v_mul_f32_e32 v4, v76, v8
	global_store_dword v[2:3], v4, off offset:256
	v_mul_f32_e32 v4, v92, v8
	global_store_dword v[2:3], v4, off offset:384
	v_add_co_u32_e32 v2, vcc, s74, v0
	v_mul_f32_e32 v4, v61, v9
	s_nop 0
	v_addc_co_u32_e32 v3, vcc, 0, v1, vcc
	global_store_dword v[2:3], v4, off
	v_mul_f32_e32 v4, v45, v9
	global_store_dword v[2:3], v4, off offset:128
	v_mul_f32_e32 v4, v77, v9
	global_store_dword v[2:3], v4, off offset:256
	v_mul_f32_e32 v4, v93, v9
	global_store_dword v[2:3], v4, off offset:384
	v_add_co_u32_e32 v2, vcc, s75, v0
	v_mul_f32_e32 v4, v62, v10
	s_nop 0
	v_addc_co_u32_e32 v3, vcc, 0, v1, vcc
	global_store_dword v[2:3], v4, off
	v_mul_f32_e32 v4, v46, v10
	global_store_dword v[2:3], v4, off offset:128
	v_mul_f32_e32 v4, v78, v10
	global_store_dword v[2:3], v4, off offset:256
	v_mul_f32_e32 v4, v94, v10
	v_add_co_u32_e32 v0, vcc, s76, v0
	global_store_dword v[2:3], v4, off offset:384
	v_mul_f32_e32 v2, v63, v11
	v_addc_co_u32_e32 v1, vcc, 0, v1, vcc
	global_store_dword v[0:1], v2, off
	v_mul_f32_e32 v2, v47, v11
	global_store_dword v[0:1], v2, off offset:128
	v_mul_f32_e32 v2, v79, v11
	global_store_dword v[0:1], v2, off offset:256
	v_mul_f32_e32 v2, v95, v11
	global_store_dword v[0:1], v2, off offset:384
	v_mov_b32_e32 v194, v224
	s_waitcnt vmcnt(0)
	s_waitcnt vmcnt(63) expcnt(7) lgkmcnt(15)
	s_barrier
; __device__ __forceinline__ int v_rd_base(int lane) { return ((lane & 3) << 3) | (((lane >> 2) & 3) << 6) | (((lane >> 4) & 1) << 5) | (((lane >> 5) & 1) << 8); }
; #define RAWBAR() do { asm volatile("s_waitcnt lgkmcnt(0)" ::: "memory"); __builtin_amdgcn_s_barrier(); asm volatile("" ::: "memory"); } while (0)
; #define RAWBAR() do { asm volatile("s_waitcnt lgkmcnt(0)" ::: "memory"); __builtin_amdgcn_s_barrier(); asm volatile("" ::: "memory"); } while (0)
; #define RAWBAR() do { asm volatile("s_waitcnt lgkmcnt(0)" ::: "memory"); __builtin_amdgcn_s_barrier(); asm volatile("" ::: "memory"); } while (0)
; #define RAWBAR() do { asm volatile("s_waitcnt lgkmcnt(0)" ::: "memory"); __builtin_amdgcn_s_barrier(); asm volatile("" ::: "memory"); } while (0)
; #define RAWBAR() do { asm volatile("s_waitcnt lgkmcnt(0)" ::: "memory"); __builtin_amdgcn_s_barrier(); asm volatile("" ::: "memory"); } while (0)
; #define RAWBAR() do { asm volatile("s_waitcnt lgkmcnt(0)" ::: "memory"); __builtin_amdgcn_s_barrier(); asm volatile("" ::: "memory"); } while (0)
; template <int MODE> ...
;     ...
;   const bf16* Qw = Qb + (long)(g * 32 + r32) * 128 + hi * 8;
; #pragma unroll
;   for (int d0 = 0; d0 < 8; ++d0) qr[d0] = St::ld8(Qw + d0 * 16);
;   const int vb0 = (int)(uintptr_t)V_lds + v_rd_base(lane) + 2 * kh * 4096;
;   const int krow = 32 * kh + r32;
;   typedef __attribute__((address_space(3))) unsigned lds_u32;
;   const int wu = __builtin_amdgcn_readfirstlane(wid);
;   long gk[2], gv[2];
; #pragma unroll
;   for (int c = 0; c < 2; ++c) { const int q = wu + 8 * c;
;     const int r = 4 * q + (lane >> 4), pch = lane & 15; gk[c] = (long)r * 128 + ((pch ^ (r & 7)) * 8);
;     const int st = 2 * q + (lane >> 5), kk = (st >> 2) * 8 + ((lane >> 2) & 7), k = (kk & ~0xC) | ((kk & 4) << 1) | ((kk & 8) >> 1), cc = (st & 3) * 32 + (lane & 3) * 8;
;     gv[c] = (long)k * 256 + cc; }
;     ...
;   const int NT = seq / KVBLK;
;   STAGE(0, 0); asm volatile("s_waitcnt vmcnt(0)" ::: "memory"); RAWBAR();
	v_mov_b32_e32 v199, v195
	v_ashrrev_i32_e32 v217, 7, v194
	v_and_b32_e32 v214, 31, v194
	v_lshlrev_b32_e32 v196, 5, v217
	v_or_b32_e32 v0, v196, v214
	v_ashrrev_i32_e32 v1, 31, v0
	v_bfe_u32 v213, v194, 5, 1
	v_lshlrev_b64 v[0:1], 8, v[0:1]
	v_lshl_add_u64 v[0:1], s[34:35], 0, v[0:1]
	v_lshlrev_b32_e32 v198, 4, v213
	v_lshl_add_u64 v[0:1], v[0:1], 0, v[198:199]
	v_lshl_add_u64 v[2:3], v[0:1], 0, s[20:21]
	v_add_co_u32_e32 v0, vcc, s77, v0
	v_ashrrev_i32_e32 v215, 6, v194
	s_add_u32 s36, s36, 0x410000
	v_addc_co_u32_e32 v1, vcc, 0, v1, vcc
	v_readfirstlane_b32 s2, v215
	s_addc_u32 s37, s37, 0
	global_load_dwordx4 v[184:187], v[2:3], off offset:32
	global_load_dwordx4 v[180:183], v[2:3], off offset:64
	global_load_dwordx4 v[176:179], v[2:3], off offset:96
	global_load_dwordx4 v[172:175], v[2:3], off offset:128
	global_load_dwordx4 v[168:171], v[2:3], off offset:160
	global_load_dwordx4 v[164:167], v[2:3], off offset:192
	global_load_dwordx4 v[188:191], v[0:1], off
	global_load_dwordx4 v[160:163], v[2:3], off offset:224
	v_bfe_u32 v199, v194, 4, 2
	v_bfe_u32 v0, v194, 2, 2
	v_lshrrev_b32_e32 v1, 1, v194
	s_lshl_b32 s3, s2, 2
	s_lshl_b32 s34, s2, 1
	v_and_or_b32 v6, v1, 8, v0
	v_or_b32_e32 v0, s3, v199
	s_and_b32 s3, s3, -16
	s_and_b32 s35, s34, 4
	s_or_b32 s3, s3, s35
	v_or_b32_e32 v2, s3, v6
	s_add_i32 s3, s2, 8
	v_and_b32_e32 v4, 63, v194
	v_and_or_b32 v14, s34, 2, v213
	s_lshl_b32 s34, s3, 2
	s_lshl_b32 s35, s3, 1
	v_lshlrev_b32_e32 v8, 3, v4
	v_lshlrev_b32_e32 v197, 4, v4
	v_or_b32_e32 v4, s34, v199
	s_and_b32 s34, s34, -16
	s_and_b32 s41, s35, 4
	v_lshlrev_b32_e32 v9, 1, v194
	v_and_b32_e32 v211, 15, v194
	v_ashrrev_i32_e32 v1, 31, v0
	s_or_b32 s34, s34, s41
	v_and_b32_e32 v12, 0x100, v8
	v_bitop3_b32 v10, v0, v211, 7 bitop3:0x6c
	v_ashrrev_i32_e32 v5, 31, v4
	v_bitop3_b32 v15, v4, v211, 7 bitop3:0x6c
	v_or_b32_e32 v6, s34, v6
	v_and_b32_e32 v17, 24, v8
	v_and_b32_e32 v19, 32, v9
	v_lshlrev_b64 v[8:9], 8, v[0:1]
	s_lshl_b32 s34, s2, 10
	v_lshlrev_b32_e32 v212, 3, v194
	v_and_or_b32 v16, s35, 2, v213
	v_lshl_or_b32 v8, v10, 4, v8
	s_add_i32 s35, s34, 0
	v_lshlrev_b64 v[4:5], 8, v[4:5]
	v_lshlrev_b32_e32 v15, 4, v15
	v_and_b32_e32 v13, 24, v212
	v_ashrrev_i32_e32 v3, 31, v2
	v_lshl_add_u64 v[10:11], s[36:37], 0, v[8:9]
	s_mov_b32 m0, s35
	v_or_b32_e32 v4, v4, v15
	v_ashrrev_i32_e32 v7, 31, v6
	global_load_lds_dwordx4 v[10:11], off
	v_lshl_add_u64 v[128:129], v[10:11], 0, s[18:19]
	v_lshl_add_u64 v[4:5], s[36:37], 0, v[4:5]
	v_lshl_add_u64 v[130:131], v[4:5], 0, s[18:19]
	s_add_i32 m0, s35, 0x2000
	v_lshlrev_b32_e32 v1, 6, v14
	v_lshlrev_b32_e32 v10, 1, v13
	v_lshlrev_b64 v[2:3], 9, v[2:3]
	global_load_lds_dwordx4 v[4:5], off
	s_add_i32 m0, s35, 0x4000
	s_nop 0
	global_load_lds_dwordx4 v[128:129], off
	s_add_i32 m0, s35, 0x6000
	s_nop 0
	global_load_lds_dwordx4 v[130:131], off
	v_or3_b32 v4, v1, v10, v2
	v_mov_b32_e32 v5, v3
	v_lshlrev_b32_e32 v1, 6, v16
	v_lshlrev_b64 v[6:7], 9, v[6:7]
	v_lshl_add_u64 v[4:5], s[30:31], 0, v[4:5]
	s_add_i32 m0, s35, 0x8000
	v_or3_b32 v10, v1, v10, v6
	v_mov_b32_e32 v11, v7
	global_load_lds_dwordx4 v[4:5], off
	v_lshl_add_u64 v[10:11], s[30:31], 0, v[10:11]
	s_add_i32 m0, s35, 0xa000
	v_lshl_add_u64 v[4:5], v[4:5], 0, s[10:11]
	global_load_lds_dwordx4 v[10:11], off
	s_add_i32 m0, s35, 0xc000
	v_and_b32_e32 v216, 1, v215
	global_load_lds_dwordx4 v[4:5], off
	v_lshl_add_u64 v[4:5], v[10:11], 0, s[10:11]
	s_add_i32 m0, s35, 0xe000
	v_lshlrev_b32_e32 v20, 13, v216
	global_load_lds_dwordx4 v[4:5], off
	s_cmp_lg_u32 s33, -1
	v_lshl_or_b32 v1, v214, 8, v20
	s_cselect_b32 s30, s33, 0
	s_and_b32 s2, s2, 1
	v_lshlrev_b32_e32 v4, 4, v194
	v_add_u32_e32 v220, 0, v1
	s_lshl_b32 s2, s2, 6
	v_and_b32_e32 v1, 32, v194
	v_and_b32_e32 v5, 0x70, v4
	v_bitop3_b32 v229, v198, v4, s58 bitop3:0x78
	v_or3_b32 v4, s2, v1, v13
	s_and_b32 s2, s3, 1
	s_lshl_b32 s2, s2, 6
	v_or3_b32 v1, s2, v1, v13
	v_add_u32_e32 v0, 32, v0
	v_and_b32_e32 v18, 0xc0, v197
	s_waitcnt vmcnt(0)
	v_lshl_or_b32 v6, v1, 1, v6
	v_ashrrev_i32_e32 v1, 31, v0
	s_waitcnt lgkmcnt(0)
	s_barrier
	v_add_u32_e32 v10, s30, v18
	v_readlane_b32 s84, v251, 28
	v_lshlrev_b64 v[0:1], 8, v[0:1]
	v_add3_u32 v10, v10, v17, v19
	v_lshl_or_b32 v2, v4, 1, v2
	v_readlane_b32 s85, v251, 29
	v_or_b32_e32 v0, v0, v15
	v_mov_b32_e32 v219, 0
	s_mov_b32 s40, 0
	v_add3_u32 v218, v10, v12, v20
	v_bitop3_b32 v228, v198, v5, 32 bitop3:0x36
	v_bitop3_b32 v227, v198, v5, 64 bitop3:0x36
	v_bitop3_b32 v226, v198, v5, s43 bitop3:0x36
	v_bitop3_b32 v225, v198, v5, s59 bitop3:0x36
	v_bitop3_b32 v223, v198, v5, s60 bitop3:0x36
	v_bitop3_b32 v222, v198, v5, s56 bitop3:0x36
	v_bitop3_b32 v221, v198, v5, s61 bitop3:0x36
	v_lshl_add_u64 v[200:201], s[84:85], 0, v[2:3]
	v_lshl_add_u64 v[202:203], s[84:85], 0, v[6:7]
	v_lshl_add_u64 v[204:205], s[8:9], 0, v[8:9]
	v_lshl_add_u64 v[206:207], s[8:9], 0, v[0:1]
	v_mov_b32_e32 v0, 0
	v_mov_b32_e32 v1, v219
	v_mov_b32_e32 v2, v219
	v_mov_b32_e32 v3, v219
	v_mov_b32_e32 v4, v219
	v_mov_b32_e32 v5, v219
	v_mov_b32_e32 v6, v219
	v_mov_b32_e32 v7, v219
	v_mov_b32_e32 v8, v219
	v_mov_b32_e32 v9, v219
	v_mov_b32_e32 v10, v219
	v_mov_b32_e32 v11, v219
	v_mov_b32_e32 v12, v219
	v_mov_b32_e32 v13, v219
	v_mov_b32_e32 v14, v219
	v_mov_b32_e32 v15, v219
	v_mov_b32_e32 v48, 0
	v_mov_b32_e32 v49, v219
	v_mov_b32_e32 v50, v219
	v_mov_b32_e32 v51, v219
	v_mov_b32_e32 v52, v219
	v_mov_b32_e32 v53, v219
	v_mov_b32_e32 v54, v219
	v_mov_b32_e32 v55, v219
	v_mov_b32_e32 v56, v219
	v_mov_b32_e32 v57, v219
	v_mov_b32_e32 v58, v219
	v_mov_b32_e32 v59, v219
	v_mov_b32_e32 v60, v219
	v_mov_b32_e32 v61, v219
	v_mov_b32_e32 v62, v219
	v_mov_b32_e32 v63, v219
	v_mov_b32_e32 v16, 0
; #define SBAR() __builtin_amdgcn_sched_barrier(0)
; __device__ __forceinline__ int v_rd_base(int lane) { return ((lane & 3) << 3) | (((lane >> 2) & 3) << 6) | (((lane >> 4) & 1) << 5) | (((lane >> 5) & 1) << 8); }
; template <int MODE> ...
;     ...
;   f32x16 o[8] = {}; bf16x8 qr[8]; float lsum = 0.f;
;   const bf16* Qw = Qb + (long)(g * 32 + r32) * 128 + hi * 8;
; #pragma unroll
;   for (int d0 = 0; d0 < 8; ++d0) qr[d0] = St::ld8(Qw + d0 * 16);
;   const int vb0 = (int)(uintptr_t)V_lds + v_rd_base(lane) + 2 * kh * 4096;
;   const int krow = 32 * kh + r32;
;   typedef __attribute__((address_space(3))) unsigned lds_u32;
;   const int wu = __builtin_amdgcn_readfirstlane(wid);
;   long gk[2], gv[2];
; #pragma unroll
;   for (int c = 0; c < 2; ++c) { const int q = wu + 8 * c;
;     const int r = 4 * q + (lane >> 4), pch = lane & 15; gk[c] = (long)r * 128 + ((pch ^ (r & 7)) * 8);
;     const int st = 2 * q + (lane >> 5), kk = (st >> 2) * 8 + ((lane >> 2) & 7), k = (kk & ~0xC) | ((kk & 4) << 1) | ((kk & 8) >> 1), cc = (st & 3) * 32 + (lane & 3) * 8;
;     gv[c] = (long)k * 256 + cc; }
;     ...
;   const int NT = seq / KVBLK;
;   STAGE(0, 0); asm volatile("s_waitcnt vmcnt(0)" ::: "memory"); RAWBAR();
;   if (false) __builtin_amdgcn_s_setprio(1);
;   for (int j = 0; j < NT; ++j) {
;     const int buf = j & 1;
;     if (j + 1 < NT) { STAGE((j + 1) * KVBLK, buf ^ 1); }
;     const char* Kb = K_lds + buf * 16384;
;     f32x16 pe = {}, po = {};
; #pragma unroll
;     for (int d0 = 0; d0 < 8; d0 += 2) {
;       const bf16x8 k0 = *reinterpret_cast<const bf16x8*>(Kb + KSWZ(krow, (d0 * 16 + hi * 8) * 2));
;       const bf16x8 k1 = *reinterpret_cast<const bf16x8*>(Kb + KSWZ(krow, ((d0 + 1) * 16 + hi * 8) * 2));
;       pe = __builtin_amdgcn_mfma_f32_32x32x16_bf16(k0, qr[d0], pe, 0, 0, 0);
;       po = __builtin_amdgcn_mfma_f32_32x32x16_bf16(k1, qr[d0 + 1], po, 0, 0, 0); }
;     const int vo = vb0 + buf * 32768;
;     s16x4 R0_[8], R1_[8];
;     PVR(R0_, 0, 1, vo);
;     f32x16 p;
; #pragma unroll
;     for (int r = 0; r < 16; ++r) p[r] = __builtin_amdgcn_exp2f(fmaf(pe[r] + po[r], C, negMc));
;     float ps = 0.f;
; #pragma unroll
;     for (int r = 0; r < 16; ++r) ps += p[r];
;     lsum += ps;
;     const bf16x8 own0 = pk8(p, 0), own1 = pk8(p, 8);
;     SBAR();
;     PV_TAIL4(o, vo, vo + 16384, own0, own1);
;     asm volatile("s_waitcnt vmcnt(0)" ::: "memory");
;     RAWBAR();
;   }
	v_mov_b32_e32 v17, v219
	v_mov_b32_e32 v18, v219
	v_mov_b32_e32 v19, v219
	v_mov_b32_e32 v20, v219
	v_mov_b32_e32 v21, v219
	v_mov_b32_e32 v22, v219
	v_mov_b32_e32 v23, v219
	v_mov_b32_e32 v24, v219
	v_mov_b32_e32 v25, v219
	v_mov_b32_e32 v26, v219
	v_mov_b32_e32 v27, v219
	v_mov_b32_e32 v28, v219
	v_mov_b32_e32 v29, v219
	v_mov_b32_e32 v30, v219
	v_mov_b32_e32 v31, v219
	v_mov_b32_e32 v32, 0
	v_mov_b32_e32 v33, v219
	v_mov_b32_e32 v34, v219
	v_mov_b32_e32 v35, v219
	v_mov_b32_e32 v36, v219
	v_mov_b32_e32 v37, v219
	v_mov_b32_e32 v38, v219
	v_mov_b32_e32 v39, v219
	v_mov_b32_e32 v40, v219
	v_mov_b32_e32 v41, v219
	v_mov_b32_e32 v42, v219
	v_mov_b32_e32 v43, v219
	v_mov_b32_e32 v44, v219
	v_mov_b32_e32 v45, v219
	v_mov_b32_e32 v46, v219
	v_mov_b32_e32 v47, v219
	v_mov_b32_e32 v64, 0
	v_mov_b32_e32 v65, v219
	v_mov_b32_e32 v66, v219
	v_mov_b32_e32 v67, v219
	v_mov_b32_e32 v68, v219
	v_mov_b32_e32 v69, v219
	v_mov_b32_e32 v70, v219
	v_mov_b32_e32 v71, v219
	v_mov_b32_e32 v72, v219
	v_mov_b32_e32 v73, v219
	v_mov_b32_e32 v74, v219
	v_mov_b32_e32 v75, v219
	v_mov_b32_e32 v76, v219
	v_mov_b32_e32 v77, v219
	v_mov_b32_e32 v78, v219
	v_mov_b32_e32 v79, v219
	v_mov_b32_e32 v80, 0
	v_mov_b32_e32 v81, v219
	v_mov_b32_e32 v82, v219
	v_mov_b32_e32 v83, v219
	v_mov_b32_e32 v84, v219
	v_mov_b32_e32 v85, v219
	v_mov_b32_e32 v86, v219
	v_mov_b32_e32 v87, v219
	v_mov_b32_e32 v88, v219
	v_mov_b32_e32 v89, v219
	v_mov_b32_e32 v90, v219
	v_mov_b32_e32 v91, v219
	v_mov_b32_e32 v92, v219
	v_mov_b32_e32 v93, v219
	v_mov_b32_e32 v94, v219
	v_mov_b32_e32 v95, v219
	v_mov_b32_e32 v96, 0
	v_mov_b32_e32 v97, v219
	v_mov_b32_e32 v98, v219
	v_mov_b32_e32 v99, v219
	v_mov_b32_e32 v100, v219
	v_mov_b32_e32 v101, v219
	v_mov_b32_e32 v102, v219
	v_mov_b32_e32 v103, v219
	v_mov_b32_e32 v104, v219
	v_mov_b32_e32 v105, v219
	v_mov_b32_e32 v106, v219
	v_mov_b32_e32 v107, v219
	v_mov_b32_e32 v108, v219
	v_mov_b32_e32 v109, v219
	v_mov_b32_e32 v110, v219
	v_mov_b32_e32 v111, v219
	v_mov_b32_e32 v112, 0
	v_mov_b32_e32 v113, v219
	v_mov_b32_e32 v114, v219
	v_mov_b32_e32 v115, v219
	v_mov_b32_e32 v116, v219
	v_mov_b32_e32 v117, v219
	v_mov_b32_e32 v118, v219
	v_mov_b32_e32 v119, v219
	v_mov_b32_e32 v120, v219
	v_mov_b32_e32 v121, v219
	v_mov_b32_e32 v122, v219
	v_mov_b32_e32 v123, v219
	v_mov_b32_e32 v124, v219
	v_mov_b32_e32 v125, v219
	v_mov_b32_e32 v126, v219
	v_mov_b32_e32 v127, v219
	v_readlane_b32 s86, v251, 30
	v_readlane_b32 s87, v251, 31
	s_waitcnt vmcnt(0)
	v_lshl_add_u64 v[204:205], v[204:205], 0, s[18:19]
	v_lshl_add_u64 v[206:207], v[206:207], 0, s[18:19]
	v_add_u32_e32 v247, v220, v229
	v_add_u32_e32 v248, v220, v228
	ds_read_b128 v[230:233], v247
	ds_read_b128 v[234:237], v248
	s_waitcnt lgkmcnt(0)
	v_mfma_f32_32x32x16_bf16 v[144:159], v[230:233], v[188:191], 0
	v_mfma_f32_32x32x16_bf16 v[144:159], v[234:237], v[184:187], v[144:159]
	v_add_u32_e32 v247, v220, v227
	v_add_u32_e32 v248, v220, v226
	ds_read_b128 v[230:233], v247
	ds_read_b128 v[234:237], v248
	s_waitcnt lgkmcnt(0)
	v_mfma_f32_32x32x16_bf16 v[144:159], v[230:233], v[180:183], v[144:159]
	v_mfma_f32_32x32x16_bf16 v[144:159], v[234:237], v[176:179], v[144:159]
	v_add_u32_e32 v247, v220, v225
	v_add_u32_e32 v248, v220, v223
	ds_read_b128 v[230:233], v247
	ds_read_b128 v[234:237], v248
	s_waitcnt lgkmcnt(0)
	v_mfma_f32_32x32x16_bf16 v[144:159], v[230:233], v[172:175], v[144:159]
	v_mfma_f32_32x32x16_bf16 v[144:159], v[234:237], v[168:171], v[144:159]
	v_add_u32_e32 v247, v220, v222
	v_add_u32_e32 v248, v220, v221
	ds_read_b128 v[230:233], v247
	ds_read_b128 v[234:237], v248
	s_waitcnt lgkmcnt(0)
	v_mfma_f32_32x32x16_bf16 v[144:159], v[230:233], v[164:167], v[144:159]
	v_mfma_f32_32x32x16_bf16 v[144:159], v[234:237], v[160:163], v[144:159]
	s_mov_b32 s84, 0
	s_mov_b32 s85, 0x8000
	s_mov_b32 s86, 0x10000
	s_barrier
	s_cmp_lt_u32 s34, 0x1000
	s_cbranch_scc0 .LattnBpre_m1
.LBB0_1023:
	v_add_u32_e32 v246, 0x4000, v220
	v_add_u32_e32 v247, v246, v229
	v_add_u32_e32 v248, v246, v228
	ds_read_b128 v[230:233], v247
	ds_read_b128 v[234:237], v248
	v_add_u32_e32 v247, v246, v227
	v_add_u32_e32 v248, v246, v226
	ds_read_b128 v[238:241], v247
	ds_read_b128 v[242:245], v248
	v_lshl_add_u64 v[128:129], v[204:205], 0, s[26:27]
	s_mov_b32 m0, s34
	v_lshl_add_u64 v[130:131], v[206:207], 0, s[26:27]
	global_load_lds_dwordx4 v[128:129], off
	s_add_i32 m0, s34, 0x2000
	s_nop 0
	global_load_lds_dwordx4 v[130:131], off
	v_fmamk_f32 v144, v144, 0x3e0293ee, v208
	v_fmamk_f32 v145, v145, 0x3e0293ee, v208
	v_fmamk_f32 v146, v146, 0x3e0293ee, v208
	v_fmamk_f32 v147, v147, 0x3e0293ee, v208
	v_exp_f32_e32 v144, v144
	v_exp_f32_e32 v145, v145
	v_exp_f32_e32 v146, v146
	v_exp_f32_e32 v147, v147
	s_waitcnt lgkmcnt(2)
	v_mfma_f32_32x32x16_bf16 v[128:143], v[230:233], v[188:191], 0
	v_mfma_f32_32x32x16_bf16 v[128:143], v[234:237], v[184:187], v[128:143]
	v_add_u32_e32 v247, v246, v225
	v_add_u32_e32 v248, v246, v223
	ds_read_b128 v[230:233], v247
	ds_read_b128 v[234:237], v248
	v_fmamk_f32 v148, v148, 0x3e0293ee, v208
	v_fmamk_f32 v149, v149, 0x3e0293ee, v208
	v_fmamk_f32 v150, v150, 0x3e0293ee, v208
	v_fmamk_f32 v151, v151, 0x3e0293ee, v208
	v_exp_f32_e32 v148, v148
	v_exp_f32_e32 v149, v149
	v_exp_f32_e32 v150, v150
	v_exp_f32_e32 v151, v151
	v_add_f32_e32 v250, v144, v145
	v_add_f32_e32 v250, v146, v250
	v_add_f32_e32 v250, v147, v250
	s_waitcnt lgkmcnt(2)
; #define SBAR() __builtin_amdgcn_sched_barrier(0)
; #define PVR(S, DA, DB, vbase) do { S[0] = tr_read<v_rd_off(DA, 0, 0)>(vbase); S[1] = tr_read<v_rd_off(DA, 0, 1)>(vbase); S[2] = tr_read<v_rd_off(DB, 0, 0)>(vbase); S[3] = tr_read<v_rd_off(DB, 0, 1)>(vbase); \
;     S[4] = tr_read<v_rd_off(DA, 1, 0)>(vbase); S[5] = tr_read<v_rd_off(DA, 1, 1)>(vbase); S[6] = tr_read<v_rd_off(DB, 1, 0)>(vbase); S[7] = tr_read<v_rd_off(DB, 1, 1)>(vbase); } while (0)
; #define RAWBAR() do { asm volatile("s_waitcnt lgkmcnt(0)" ::: "memory"); __builtin_amdgcn_s_barrier(); asm volatile("" ::: "memory"); } while (0)
; #define RAWBAR() do { asm volatile("s_waitcnt lgkmcnt(0)" ::: "memory"); __builtin_amdgcn_s_barrier(); asm volatile("" ::: "memory"); } while (0)
; #define RAWBAR() do { asm volatile("s_waitcnt lgkmcnt(0)" ::: "memory"); __builtin_amdgcn_s_barrier(); asm volatile("" ::: "memory"); } while (0)
; #define RAWBAR() do { asm volatile("s_waitcnt lgkmcnt(0)" ::: "memory"); __builtin_amdgcn_s_barrier(); asm volatile("" ::: "memory"); } while (0)
; #define RAWBAR() do { asm volatile("s_waitcnt lgkmcnt(0)" ::: "memory"); __builtin_amdgcn_s_barrier(); asm volatile("" ::: "memory"); } while (0)
; template <int MODE> ...
;     ...
;   for (int j = 0; j < NT; ++j) {
;     const int buf = j & 1;
;     if (j + 1 < NT) { STAGE((j + 1) * KVBLK, buf ^ 1); }
;     const char* Kb = K_lds + buf * 16384;
;     f32x16 pe = {}, po = {};
; #pragma unroll
;     for (int d0 = 0; d0 < 8; d0 += 2) {
;       const bf16x8 k0 = *reinterpret_cast<const bf16x8*>(Kb + KSWZ(krow, (d0 * 16 + hi * 8) * 2));
;       const bf16x8 k1 = *reinterpret_cast<const bf16x8*>(Kb + KSWZ(krow, ((d0 + 1) * 16 + hi * 8) * 2));
;       pe = __builtin_amdgcn_mfma_f32_32x32x16_bf16(k0, qr[d0], pe, 0, 0, 0);
;       po = __builtin_amdgcn_mfma_f32_32x32x16_bf16(k1, qr[d0 + 1], po, 0, 0, 0); }
;     const int vo = vb0 + buf * 32768;
;     s16x4 R0_[8], R1_[8];
;     PVR(R0_, 0, 1, vo);
;     f32x16 p;
; #pragma unroll
;     for (int r = 0; r < 16; ++r) p[r] = __builtin_amdgcn_exp2f(fmaf(pe[r] + po[r], C, negMc));
;     float ps = 0.f;
; #pragma unroll
;     for (int r = 0; r < 16; ++r) ps += p[r];
;     lsum += ps;
;     const bf16x8 own0 = pk8(p, 0), own1 = pk8(p, 8);
;     SBAR();
;     PV_TAIL4(o, vo, vo + 16384, own0, own1);
;     asm volatile("s_waitcnt vmcnt(0)" ::: "memory");
;     RAWBAR();
;   }
	v_mfma_f32_32x32x16_bf16 v[128:143], v[238:241], v[180:183], v[128:143]
	v_mfma_f32_32x32x16_bf16 v[128:143], v[242:245], v[176:179], v[128:143]
	v_add_u32_e32 v247, v246, v222
	v_add_u32_e32 v248, v246, v221
	ds_read_b128 v[238:241], v247
	ds_read_b128 v[242:245], v248
	v_fmamk_f32 v152, v152, 0x3e0293ee, v208
	v_fmamk_f32 v153, v153, 0x3e0293ee, v208
	v_fmamk_f32 v154, v154, 0x3e0293ee, v208
	v_fmamk_f32 v155, v155, 0x3e0293ee, v208
	v_exp_f32_e32 v152, v152
	v_exp_f32_e32 v153, v153
	v_exp_f32_e32 v154, v154
	v_exp_f32_e32 v155, v155
	v_add_f32_e32 v250, v148, v250
	v_add_f32_e32 v250, v149, v250
	v_add_f32_e32 v250, v150, v250
	v_add_f32_e32 v250, v151, v250
	s_waitcnt lgkmcnt(2)
	v_mfma_f32_32x32x16_bf16 v[128:143], v[230:233], v[172:175], v[128:143]
	v_mfma_f32_32x32x16_bf16 v[128:143], v[234:237], v[168:171], v[128:143]
	v_fmamk_f32 v156, v156, 0x3e0293ee, v208
	v_fmamk_f32 v157, v157, 0x3e0293ee, v208
	v_fmamk_f32 v158, v158, 0x3e0293ee, v208
	v_fmamk_f32 v159, v159, 0x3e0293ee, v208
	v_exp_f32_e32 v156, v156
	v_exp_f32_e32 v157, v157
	v_exp_f32_e32 v158, v158
	v_exp_f32_e32 v159, v159
	v_add_f32_e32 v250, v152, v250
	v_add_f32_e32 v250, v153, v250
	v_add_f32_e32 v250, v154, v250
	v_add_f32_e32 v250, v155, v250
	v_cvt_pk_bf16_f32 v230, v144, v145
	v_cvt_pk_bf16_f32 v231, v146, v147
	v_cvt_pk_bf16_f32 v232, v148, v149
	v_cvt_pk_bf16_f32 v233, v150, v151
	s_waitcnt lgkmcnt(0)
	v_mfma_f32_32x32x16_bf16 v[128:143], v[238:241], v[164:167], v[128:143]
	v_mfma_f32_32x32x16_bf16 v[128:143], v[242:245], v[160:163], v[128:143]
	v_add_u32_e32 v249, s84, v218
	ds_read_b64_tr_b16 v[238:239], v249 offset:0
	ds_read_b64_tr_b16 v[240:241], v249 offset:2048
	ds_read_b64_tr_b16 v[242:243], v249 offset:512
	ds_read_b64_tr_b16 v[244:245], v249 offset:2560
	v_permlane32_swap_b32_e32 v230, v232
	v_permlane32_swap_b32_e32 v231, v233
	ds_read_b64_tr_b16 v[144:145], v249 offset:4096
	ds_read_b64_tr_b16 v[146:147], v249 offset:6144
	ds_read_b64_tr_b16 v[148:149], v249 offset:4608
	ds_read_b64_tr_b16 v[150:151], v249 offset:6656
	v_add_f32_e32 v250, v156, v250
	v_add_f32_e32 v250, v157, v250
	v_add_f32_e32 v250, v158, v250
	v_add_f32_e32 v250, v159, v250
	v_cvt_pk_bf16_f32 v234, v152, v153
	v_cvt_pk_bf16_f32 v235, v154, v155
	v_cvt_pk_bf16_f32 v236, v156, v157
	v_cvt_pk_bf16_f32 v237, v158, v159
	v_add_f32_e32 v219, v219, v250
	ds_read_b64_tr_b16 v[152:153], v249 offset:1024
	ds_read_b64_tr_b16 v[154:155], v249 offset:3072
	ds_read_b64_tr_b16 v[156:157], v249 offset:1536
	ds_read_b64_tr_b16 v[158:159], v249 offset:3584
	v_permlane32_swap_b32_e32 v234, v236
	v_permlane32_swap_b32_e32 v235, v237
	s_waitcnt lgkmcnt(8)
	v_mfma_f32_32x32x16_bf16 v[112:127], v[230:233], v[238:241], v[112:127]
	v_mfma_f32_32x32x16_bf16 v[96:111], v[230:233], v[242:245], v[96:111]
	ds_read_b64_tr_b16 v[238:239], v249 offset:5120
	ds_read_b64_tr_b16 v[240:241], v249 offset:7168
	ds_read_b64_tr_b16 v[242:243], v249 offset:5632
	ds_read_b64_tr_b16 v[244:245], v249 offset:7680
	v_lshl_add_u64 v[246:247], v[200:201], 0, s[26:27]
	s_add_i32 s30, s85, s34
	s_add_i32 m0, s30, 0x8000
	v_lshl_add_u64 v[246:247], v[246:247], 0, s[12:13]
	global_load_lds_dwordx4 v[246:247], off
	s_waitcnt lgkmcnt(8)
	v_mfma_f32_32x32x16_bf16 v[112:127], v[234:237], v[144:147], v[112:127]
	v_mfma_f32_32x32x16_bf16 v[96:111], v[234:237], v[148:151], v[96:111]
	ds_read_b64_tr_b16 v[144:145], v249 offset:16384
	ds_read_b64_tr_b16 v[146:147], v249 offset:18432
	ds_read_b64_tr_b16 v[148:149], v249 offset:16896
	ds_read_b64_tr_b16 v[150:151], v249 offset:18944
	v_lshl_add_u64 v[246:247], v[202:203], 0, s[26:27]
	s_add_i32 s30, s85, s34
	s_add_i32 m0, s30, 0xa000
	v_lshl_add_u64 v[246:247], v[246:247], 0, s[12:13]
	global_load_lds_dwordx4 v[246:247], off
	s_waitcnt lgkmcnt(8)
	v_mfma_f32_32x32x16_bf16 v[80:95], v[230:233], v[152:155], v[80:95]
	v_mfma_f32_32x32x16_bf16 v[64:79], v[230:233], v[156:159], v[64:79]
	ds_read_b64_tr_b16 v[152:153], v249 offset:20480
	ds_read_b64_tr_b16 v[154:155], v249 offset:22528
	ds_read_b64_tr_b16 v[156:157], v249 offset:20992
	ds_read_b64_tr_b16 v[158:159], v249 offset:23040
	v_lshl_add_u64 v[246:247], v[200:201], 0, s[26:27]
	s_add_i32 s30, s85, s34
	s_add_i32 m0, s30, 0xc000
	v_lshl_add_u64 v[246:247], v[246:247], 0, s[14:15]
	global_load_lds_dwordx4 v[246:247], off
	s_waitcnt lgkmcnt(8)
	v_mfma_f32_32x32x16_bf16 v[80:95], v[234:237], v[238:241], v[80:95]
	v_mfma_f32_32x32x16_bf16 v[64:79], v[234:237], v[242:245], v[64:79]
	ds_read_b64_tr_b16 v[238:239], v249 offset:17408
	ds_read_b64_tr_b16 v[240:241], v249 offset:19456
	ds_read_b64_tr_b16 v[242:243], v249 offset:17920
	ds_read_b64_tr_b16 v[244:245], v249 offset:19968
	v_lshl_add_u64 v[246:247], v[202:203], 0, s[26:27]
	s_add_i32 s30, s85, s34
	s_add_i32 m0, s30, 0xe000
	v_lshl_add_u64 v[246:247], v[246:247], 0, s[14:15]
	global_load_lds_dwordx4 v[246:247], off
	s_waitcnt lgkmcnt(8)
	v_mfma_f32_32x32x16_bf16 v[32:47], v[230:233], v[144:147], v[32:47]
	v_mfma_f32_32x32x16_bf16 v[16:31], v[230:233], v[148:151], v[16:31]
	ds_read_b64_tr_b16 v[144:145], v249 offset:21504
	ds_read_b64_tr_b16 v[146:147], v249 offset:23552
	ds_read_b64_tr_b16 v[148:149], v249 offset:22016
	ds_read_b64_tr_b16 v[150:151], v249 offset:24064
	s_waitcnt lgkmcnt(8)
	v_mfma_f32_32x32x16_bf16 v[32:47], v[234:237], v[152:155], v[32:47]
	v_mfma_f32_32x32x16_bf16 v[16:31], v[234:237], v[156:159], v[16:31]
	s_waitcnt lgkmcnt(0)
	v_mfma_f32_32x32x16_bf16 v[48:63], v[230:233], v[238:241], v[48:63]
	s_waitcnt vmcnt(0)
	s_barrier
; #define SBAR() __builtin_amdgcn_sched_barrier(0)
; #define PVR(S, DA, DB, vbase) do { S[0] = tr_read<v_rd_off(DA, 0, 0)>(vbase); S[1] = tr_read<v_rd_off(DA, 0, 1)>(vbase); S[2] = tr_read<v_rd_off(DB, 0, 0)>(vbase); S[3] = tr_read<v_rd_off(DB, 0, 1)>(vbase); \
;     S[4] = tr_read<v_rd_off(DA, 1, 0)>(vbase); S[5] = tr_read<v_rd_off(DA, 1, 1)>(vbase); S[6] = tr_read<v_rd_off(DB, 1, 0)>(vbase); S[7] = tr_read<v_rd_off(DB, 1, 1)>(vbase); } while (0)
; #define RAWBAR() do { asm volatile("s_waitcnt lgkmcnt(0)" ::: "memory"); __builtin_amdgcn_s_barrier(); asm volatile("" ::: "memory"); } while (0)
; #define RAWBAR() do { asm volatile("s_waitcnt lgkmcnt(0)" ::: "memory"); __builtin_amdgcn_s_barrier(); asm volatile("" ::: "memory"); } while (0)
; #define RAWBAR() do { asm volatile("s_waitcnt lgkmcnt(0)" ::: "memory"); __builtin_amdgcn_s_barrier(); asm volatile("" ::: "memory"); } while (0)
; #define RAWBAR() do { asm volatile("s_waitcnt lgkmcnt(0)" ::: "memory"); __builtin_amdgcn_s_barrier(); asm volatile("" ::: "memory"); } while (0)
; #define RAWBAR() do { asm volatile("s_waitcnt lgkmcnt(0)" ::: "memory"); __builtin_amdgcn_s_barrier(); asm volatile("" ::: "memory"); } while (0)
; template <int MODE> ...
;     ...
;   for (int j = 0; j < NT; ++j) {
;     const int buf = j & 1;
;     if (j + 1 < NT) { STAGE((j + 1) * KVBLK, buf ^ 1); }
;     const char* Kb = K_lds + buf * 16384;
;     f32x16 pe = {}, po = {};
; #pragma unroll
;     for (int d0 = 0; d0 < 8; d0 += 2) {
;       const bf16x8 k0 = *reinterpret_cast<const bf16x8*>(Kb + KSWZ(krow, (d0 * 16 + hi * 8) * 2));
;       const bf16x8 k1 = *reinterpret_cast<const bf16x8*>(Kb + KSWZ(krow, ((d0 + 1) * 16 + hi * 8) * 2));
;       pe = __builtin_amdgcn_mfma_f32_32x32x16_bf16(k0, qr[d0], pe, 0, 0, 0);
;       po = __builtin_amdgcn_mfma_f32_32x32x16_bf16(k1, qr[d0 + 1], po, 0, 0, 0); }
;     const int vo = vb0 + buf * 32768;
;     s16x4 R0_[8], R1_[8];
;     PVR(R0_, 0, 1, vo);
;     f32x16 p;
; #pragma unroll
;     for (int r = 0; r < 16; ++r) p[r] = __builtin_amdgcn_exp2f(fmaf(pe[r] + po[r], C, negMc));
;     float ps = 0.f;
; #pragma unroll
;     for (int r = 0; r < 16; ++r) ps += p[r];
;     lsum += ps;
;     const bf16x8 own0 = pk8(p, 0), own1 = pk8(p, 8);
;     SBAR();
;     PV_TAIL4(o, vo, vo + 16384, own0, own1);
;     asm volatile("s_waitcnt vmcnt(0)" ::: "memory");
;     RAWBAR();
;   }
	v_lshl_add_u64 v[200:201], v[200:201], 0, s[16:17]
	v_lshl_add_u64 v[202:203], v[202:203], 0, s[16:17]
	v_lshl_add_u64 v[204:205], v[204:205], 0, s[18:19]
	v_lshl_add_u64 v[206:207], v[206:207], 0, s[18:19]
	v_mfma_f32_32x32x16_bf16 v[0:15], v[230:233], v[242:245], v[0:15]
	v_mfma_f32_32x32x16_bf16 v[48:63], v[234:237], v[144:147], v[48:63]
	v_mfma_f32_32x32x16_bf16 v[0:15], v[234:237], v[148:151], v[0:15]
	s_mov_b32 s87, s84
	s_mov_b32 s84, s85
	s_mov_b32 s85, s86
	s_mov_b32 s86, s87
	v_add_u32_e32 v247, v220, v229
	v_add_u32_e32 v248, v220, v228
	ds_read_b128 v[230:233], v247
	ds_read_b128 v[234:237], v248
	v_add_u32_e32 v247, v220, v227
	v_add_u32_e32 v248, v220, v226
	ds_read_b128 v[238:241], v247
	ds_read_b128 v[242:245], v248
	v_lshl_add_u64 v[144:145], v[204:205], 0, s[26:27]
	s_add_i32 m0, s34, 0x4000
	v_lshl_add_u64 v[146:147], v[206:207], 0, s[26:27]
	global_load_lds_dwordx4 v[144:145], off
	s_add_i32 m0, s34, 0x6000
	s_nop 0
	global_load_lds_dwordx4 v[146:147], off
	v_fmamk_f32 v128, v128, 0x3e0293ee, v208
	v_fmamk_f32 v129, v129, 0x3e0293ee, v208
	v_fmamk_f32 v130, v130, 0x3e0293ee, v208
	v_fmamk_f32 v131, v131, 0x3e0293ee, v208
	v_exp_f32_e32 v128, v128
	v_exp_f32_e32 v129, v129
	v_exp_f32_e32 v130, v130
	v_exp_f32_e32 v131, v131
	s_waitcnt lgkmcnt(2)
	v_mfma_f32_32x32x16_bf16 v[144:159], v[230:233], v[188:191], 0
	v_mfma_f32_32x32x16_bf16 v[144:159], v[234:237], v[184:187], v[144:159]
	v_add_u32_e32 v247, v220, v225
	v_add_u32_e32 v248, v220, v223
	ds_read_b128 v[230:233], v247
	ds_read_b128 v[234:237], v248
	v_fmamk_f32 v132, v132, 0x3e0293ee, v208
	v_fmamk_f32 v133, v133, 0x3e0293ee, v208
	v_fmamk_f32 v134, v134, 0x3e0293ee, v208
	v_fmamk_f32 v135, v135, 0x3e0293ee, v208
	v_exp_f32_e32 v132, v132
	v_exp_f32_e32 v133, v133
	v_exp_f32_e32 v134, v134
	v_exp_f32_e32 v135, v135
	v_add_f32_e32 v250, v128, v129
	v_add_f32_e32 v250, v130, v250
	v_add_f32_e32 v250, v131, v250
	s_waitcnt lgkmcnt(2)
	v_mfma_f32_32x32x16_bf16 v[144:159], v[238:241], v[180:183], v[144:159]
	v_mfma_f32_32x32x16_bf16 v[144:159], v[242:245], v[176:179], v[144:159]
	v_add_u32_e32 v247, v220, v222
	v_add_u32_e32 v248, v220, v221
	ds_read_b128 v[238:241], v247
	ds_read_b128 v[242:245], v248
	v_fmamk_f32 v136, v136, 0x3e0293ee, v208
	v_fmamk_f32 v137, v137, 0x3e0293ee, v208
	v_fmamk_f32 v138, v138, 0x3e0293ee, v208
	v_fmamk_f32 v139, v139, 0x3e0293ee, v208
	v_exp_f32_e32 v136, v136
	v_exp_f32_e32 v137, v137
	v_exp_f32_e32 v138, v138
	v_exp_f32_e32 v139, v139
	v_add_f32_e32 v250, v132, v250
	v_add_f32_e32 v250, v133, v250
	v_add_f32_e32 v250, v134, v250
	v_add_f32_e32 v250, v135, v250
	s_waitcnt lgkmcnt(2)
	v_mfma_f32_32x32x16_bf16 v[144:159], v[230:233], v[172:175], v[144:159]
	v_mfma_f32_32x32x16_bf16 v[144:159], v[234:237], v[168:171], v[144:159]
	v_fmamk_f32 v140, v140, 0x3e0293ee, v208
	v_fmamk_f32 v141, v141, 0x3e0293ee, v208
	v_fmamk_f32 v142, v142, 0x3e0293ee, v208
	v_fmamk_f32 v143, v143, 0x3e0293ee, v208
	v_exp_f32_e32 v140, v140
	v_exp_f32_e32 v141, v141
	v_exp_f32_e32 v142, v142
	v_exp_f32_e32 v143, v143
	v_add_f32_e32 v250, v136, v250
	v_add_f32_e32 v250, v137, v250
	v_add_f32_e32 v250, v138, v250
	v_add_f32_e32 v250, v139, v250
	v_cvt_pk_bf16_f32 v230, v128, v129
	v_cvt_pk_bf16_f32 v231, v130, v131
	v_cvt_pk_bf16_f32 v232, v132, v133
	v_cvt_pk_bf16_f32 v233, v134, v135
	s_waitcnt lgkmcnt(0)
	v_mfma_f32_32x32x16_bf16 v[144:159], v[238:241], v[164:167], v[144:159]
	v_mfma_f32_32x32x16_bf16 v[144:159], v[242:245], v[160:163], v[144:159]
	v_add_u32_e32 v249, s84, v218
	ds_read_b64_tr_b16 v[238:239], v249 offset:0
	ds_read_b64_tr_b16 v[240:241], v249 offset:2048
	ds_read_b64_tr_b16 v[242:243], v249 offset:512
	ds_read_b64_tr_b16 v[244:245], v249 offset:2560
	v_permlane32_swap_b32_e32 v230, v232
	v_permlane32_swap_b32_e32 v231, v233
	ds_read_b64_tr_b16 v[128:129], v249 offset:4096
	ds_read_b64_tr_b16 v[130:131], v249 offset:6144
	ds_read_b64_tr_b16 v[132:133], v249 offset:4608
	ds_read_b64_tr_b16 v[134:135], v249 offset:6656
	v_add_f32_e32 v250, v140, v250
	v_add_f32_e32 v250, v141, v250
	v_add_f32_e32 v250, v142, v250
	v_add_f32_e32 v250, v143, v250
	v_cvt_pk_bf16_f32 v234, v136, v137
	v_cvt_pk_bf16_f32 v235, v138, v139
	v_cvt_pk_bf16_f32 v236, v140, v141
	v_cvt_pk_bf16_f32 v237, v142, v143
	v_add_f32_e32 v219, v219, v250
	ds_read_b64_tr_b16 v[136:137], v249 offset:1024
	ds_read_b64_tr_b16 v[138:139], v249 offset:3072
	ds_read_b64_tr_b16 v[140:141], v249 offset:1536
	ds_read_b64_tr_b16 v[142:143], v249 offset:3584
	v_permlane32_swap_b32_e32 v234, v236
	v_permlane32_swap_b32_e32 v235, v237
	s_waitcnt lgkmcnt(8)
	v_mfma_f32_32x32x16_bf16 v[112:127], v[230:233], v[238:241], v[112:127]
	v_mfma_f32_32x32x16_bf16 v[96:111], v[230:233], v[242:245], v[96:111]
	ds_read_b64_tr_b16 v[238:239], v249 offset:5120
	ds_read_b64_tr_b16 v[240:241], v249 offset:7168
	ds_read_b64_tr_b16 v[242:243], v249 offset:5632
	ds_read_b64_tr_b16 v[244:245], v249 offset:7680
	v_lshl_add_u64 v[246:247], v[200:201], 0, s[26:27]
	s_add_i32 s30, s85, s34
	s_add_i32 m0, s30, 0x8000
	v_lshl_add_u64 v[246:247], v[246:247], 0, s[12:13]
	global_load_lds_dwordx4 v[246:247], off
	s_waitcnt lgkmcnt(8)
	v_mfma_f32_32x32x16_bf16 v[112:127], v[234:237], v[128:131], v[112:127]
	v_mfma_f32_32x32x16_bf16 v[96:111], v[234:237], v[132:135], v[96:111]
	ds_read_b64_tr_b16 v[128:129], v249 offset:16384
	ds_read_b64_tr_b16 v[130:131], v249 offset:18432
	ds_read_b64_tr_b16 v[132:133], v249 offset:16896
	ds_read_b64_tr_b16 v[134:135], v249 offset:18944
	v_lshl_add_u64 v[246:247], v[202:203], 0, s[26:27]
	s_add_i32 s30, s85, s34
	s_add_i32 m0, s30, 0xa000
	v_lshl_add_u64 v[246:247], v[246:247], 0, s[12:13]
	global_load_lds_dwordx4 v[246:247], off
	s_waitcnt lgkmcnt(8)
; #define SBAR() __builtin_amdgcn_sched_barrier(0)
; #define PVR(S, DA, DB, vbase) do { S[0] = tr_read<v_rd_off(DA, 0, 0)>(vbase); S[1] = tr_read<v_rd_off(DA, 0, 1)>(vbase); S[2] = tr_read<v_rd_off(DB, 0, 0)>(vbase); S[3] = tr_read<v_rd_off(DB, 0, 1)>(vbase); \
;     S[4] = tr_read<v_rd_off(DA, 1, 0)>(vbase); S[5] = tr_read<v_rd_off(DA, 1, 1)>(vbase); S[6] = tr_read<v_rd_off(DB, 1, 0)>(vbase); S[7] = tr_read<v_rd_off(DB, 1, 1)>(vbase); } while (0)
; #define RAWBAR() do { asm volatile("s_waitcnt lgkmcnt(0)" ::: "memory"); __builtin_amdgcn_s_barrier(); asm volatile("" ::: "memory"); } while (0)
; #define RAWBAR() do { asm volatile("s_waitcnt lgkmcnt(0)" ::: "memory"); __builtin_amdgcn_s_barrier(); asm volatile("" ::: "memory"); } while (0)
; #define RAWBAR() do { asm volatile("s_waitcnt lgkmcnt(0)" ::: "memory"); __builtin_amdgcn_s_barrier(); asm volatile("" ::: "memory"); } while (0)
; #define RAWBAR() do { asm volatile("s_waitcnt lgkmcnt(0)" ::: "memory"); __builtin_amdgcn_s_barrier(); asm volatile("" ::: "memory"); } while (0)
; #define RAWBAR() do { asm volatile("s_waitcnt lgkmcnt(0)" ::: "memory"); __builtin_amdgcn_s_barrier(); asm volatile("" ::: "memory"); } while (0)
; template <int MODE> ...
;     ...
;   for (int j = 0; j < NT; ++j) {
;     const int buf = j & 1;
;     if (j + 1 < NT) { STAGE((j + 1) * KVBLK, buf ^ 1); }
;     const char* Kb = K_lds + buf * 16384;
;     f32x16 pe = {}, po = {};
; #pragma unroll
;     for (int d0 = 0; d0 < 8; d0 += 2) {
;       const bf16x8 k0 = *reinterpret_cast<const bf16x8*>(Kb + KSWZ(krow, (d0 * 16 + hi * 8) * 2));
;       const bf16x8 k1 = *reinterpret_cast<const bf16x8*>(Kb + KSWZ(krow, ((d0 + 1) * 16 + hi * 8) * 2));
;       pe = __builtin_amdgcn_mfma_f32_32x32x16_bf16(k0, qr[d0], pe, 0, 0, 0);
;       po = __builtin_amdgcn_mfma_f32_32x32x16_bf16(k1, qr[d0 + 1], po, 0, 0, 0); }
;     const int vo = vb0 + buf * 32768;
;     s16x4 R0_[8], R1_[8];
;     PVR(R0_, 0, 1, vo);
;     f32x16 p;
; #pragma unroll
;     for (int r = 0; r < 16; ++r) p[r] = __builtin_amdgcn_exp2f(fmaf(pe[r] + po[r], C, negMc));
;     float ps = 0.f;
; #pragma unroll
;     for (int r = 0; r < 16; ++r) ps += p[r];
;     lsum += ps;
;     const bf16x8 own0 = pk8(p, 0), own1 = pk8(p, 8);
;     SBAR();
;     PV_TAIL4(o, vo, vo + 16384, own0, own1);
;     asm volatile("s_waitcnt vmcnt(0)" ::: "memory");
;     RAWBAR();
;   }
	v_mfma_f32_32x32x16_bf16 v[80:95], v[230:233], v[136:139], v[80:95]
	v_mfma_f32_32x32x16_bf16 v[64:79], v[230:233], v[140:143], v[64:79]
	ds_read_b64_tr_b16 v[136:137], v249 offset:20480
	ds_read_b64_tr_b16 v[138:139], v249 offset:22528
	ds_read_b64_tr_b16 v[140:141], v249 offset:20992
	ds_read_b64_tr_b16 v[142:143], v249 offset:23040
	v_lshl_add_u64 v[246:247], v[200:201], 0, s[26:27]
	s_add_i32 s30, s85, s34
	s_add_i32 m0, s30, 0xc000
	v_lshl_add_u64 v[246:247], v[246:247], 0, s[14:15]
	global_load_lds_dwordx4 v[246:247], off
	s_waitcnt lgkmcnt(8)
	v_mfma_f32_32x32x16_bf16 v[80:95], v[234:237], v[238:241], v[80:95]
	v_mfma_f32_32x32x16_bf16 v[64:79], v[234:237], v[242:245], v[64:79]
	ds_read_b64_tr_b16 v[238:239], v249 offset:17408
	ds_read_b64_tr_b16 v[240:241], v249 offset:19456
	ds_read_b64_tr_b16 v[242:243], v249 offset:17920
	ds_read_b64_tr_b16 v[244:245], v249 offset:19968
	v_lshl_add_u64 v[246:247], v[202:203], 0, s[26:27]
	s_add_i32 s30, s85, s34
	s_add_i32 m0, s30, 0xe000
	v_lshl_add_u64 v[246:247], v[246:247], 0, s[14:15]
	global_load_lds_dwordx4 v[246:247], off
	s_waitcnt lgkmcnt(8)
	v_mfma_f32_32x32x16_bf16 v[32:47], v[230:233], v[128:131], v[32:47]
	v_mfma_f32_32x32x16_bf16 v[16:31], v[230:233], v[132:135], v[16:31]
	ds_read_b64_tr_b16 v[128:129], v249 offset:21504
	ds_read_b64_tr_b16 v[130:131], v249 offset:23552
	ds_read_b64_tr_b16 v[132:133], v249 offset:22016
	ds_read_b64_tr_b16 v[134:135], v249 offset:24064
	s_waitcnt lgkmcnt(8)
	v_mfma_f32_32x32x16_bf16 v[32:47], v[234:237], v[136:139], v[32:47]
	v_mfma_f32_32x32x16_bf16 v[16:31], v[234:237], v[140:143], v[16:31]
	s_waitcnt lgkmcnt(0)
	v_mfma_f32_32x32x16_bf16 v[48:63], v[230:233], v[238:241], v[48:63]
	s_waitcnt vmcnt(0)
	s_barrier
	v_lshl_add_u64 v[200:201], v[200:201], 0, s[16:17]
	v_lshl_add_u64 v[202:203], v[202:203], 0, s[16:17]
	v_lshl_add_u64 v[204:205], v[204:205], 0, s[18:19]
	v_lshl_add_u64 v[206:207], v[206:207], 0, s[18:19]
	v_mfma_f32_32x32x16_bf16 v[0:15], v[230:233], v[242:245], v[0:15]
	v_mfma_f32_32x32x16_bf16 v[48:63], v[234:237], v[128:131], v[48:63]
	v_mfma_f32_32x32x16_bf16 v[0:15], v[234:237], v[132:135], v[0:15]
	s_mov_b32 s87, s84
	s_mov_b32 s84, s85
	s_mov_b32 s85, s86
	s_mov_b32 s86, s87
	s_add_i32 s40, s40, 1
	s_cmpk_eq_i32 s40, 0x82
	s_cbranch_scc0 .LBB0_1023
	s_barrier
	s_branch .Lattn_join_m1
.LattnBpre_m1:
	v_lshl_add_u64 v[128:129], v[204:205], 0, s[26:27]
	s_mov_b32 m0, s34
	v_lshl_add_u64 v[130:131], v[206:207], 0, s[26:27]
	global_load_lds_dwordx4 v[128:129], off
	s_add_i32 m0, s34, 0x2000
	s_nop 0
	global_load_lds_dwordx4 v[130:131], off
	v_lshl_add_u64 v[132:133], v[200:201], 0, s[26:27]
	s_add_i32 s30, s85, s34
	s_add_i32 m0, s30, 0x8000
	v_lshl_add_u64 v[132:133], v[132:133], 0, s[12:13]
	global_load_lds_dwordx4 v[132:133], off
	v_lshl_add_u64 v[132:133], v[202:203], 0, s[26:27]
	s_add_i32 s30, s85, s34
	s_add_i32 m0, s30, 0xa000
	v_lshl_add_u64 v[132:133], v[132:133], 0, s[12:13]
	global_load_lds_dwordx4 v[132:133], off
	v_lshl_add_u64 v[132:133], v[200:201], 0, s[26:27]
	s_add_i32 s30, s85, s34
	s_add_i32 m0, s30, 0xc000
	v_lshl_add_u64 v[132:133], v[132:133], 0, s[14:15]
	global_load_lds_dwordx4 v[132:133], off
	v_lshl_add_u64 v[132:133], v[202:203], 0, s[26:27]
	s_add_i32 s30, s85, s34
	s_add_i32 m0, s30, 0xe000
	v_lshl_add_u64 v[132:133], v[132:133], 0, s[14:15]
	global_load_lds_dwordx4 v[132:133], off
.LattnB_m1:
	v_add_u32_e32 v246, 0x4000, v220
	v_add_u32_e32 v247, v246, v229
	v_add_u32_e32 v248, v246, v228
	ds_read_b128 v[230:233], v247
	ds_read_b128 v[234:237], v248
	v_add_u32_e32 v247, v246, v227
	v_add_u32_e32 v248, v246, v226
	ds_read_b128 v[238:241], v247
	ds_read_b128 v[242:245], v248
	v_fmamk_f32 v144, v144, 0x3e0293ee, v208
	v_fmamk_f32 v145, v145, 0x3e0293ee, v208
	v_fmamk_f32 v146, v146, 0x3e0293ee, v208
	v_fmamk_f32 v147, v147, 0x3e0293ee, v208
	v_exp_f32_e32 v144, v144
	v_exp_f32_e32 v145, v145
	v_exp_f32_e32 v146, v146
	v_exp_f32_e32 v147, v147
	s_waitcnt lgkmcnt(2)
	v_mfma_f32_32x32x16_bf16 v[128:143], v[230:233], v[188:191], 0
	v_mfma_f32_32x32x16_bf16 v[128:143], v[234:237], v[184:187], v[128:143]
	v_add_u32_e32 v247, v246, v225
	v_add_u32_e32 v248, v246, v223
	ds_read_b128 v[230:233], v247
	ds_read_b128 v[234:237], v248
	v_fmamk_f32 v148, v148, 0x3e0293ee, v208
	v_fmamk_f32 v149, v149, 0x3e0293ee, v208
	v_fmamk_f32 v150, v150, 0x3e0293ee, v208
	v_fmamk_f32 v151, v151, 0x3e0293ee, v208
	v_exp_f32_e32 v148, v148
	v_exp_f32_e32 v149, v149
	v_exp_f32_e32 v150, v150
	v_exp_f32_e32 v151, v151
	v_add_f32_e32 v250, v144, v145
	v_add_f32_e32 v250, v146, v250
	v_add_f32_e32 v250, v147, v250
	s_waitcnt lgkmcnt(2)
	v_mfma_f32_32x32x16_bf16 v[128:143], v[238:241], v[180:183], v[128:143]
	v_mfma_f32_32x32x16_bf16 v[128:143], v[242:245], v[176:179], v[128:143]
	v_add_u32_e32 v247, v246, v222
	v_add_u32_e32 v248, v246, v221
	ds_read_b128 v[238:241], v247
	ds_read_b128 v[242:245], v248
	v_fmamk_f32 v152, v152, 0x3e0293ee, v208
	v_fmamk_f32 v153, v153, 0x3e0293ee, v208
	v_fmamk_f32 v154, v154, 0x3e0293ee, v208
	v_fmamk_f32 v155, v155, 0x3e0293ee, v208
	v_exp_f32_e32 v152, v152
	v_exp_f32_e32 v153, v153
	v_exp_f32_e32 v154, v154
	v_exp_f32_e32 v155, v155
	v_add_f32_e32 v250, v148, v250
	v_add_f32_e32 v250, v149, v250
	v_add_f32_e32 v250, v150, v250
	v_add_f32_e32 v250, v151, v250
	s_waitcnt lgkmcnt(2)
	v_mfma_f32_32x32x16_bf16 v[128:143], v[230:233], v[172:175], v[128:143]
	v_mfma_f32_32x32x16_bf16 v[128:143], v[234:237], v[168:171], v[128:143]
	v_fmamk_f32 v156, v156, 0x3e0293ee, v208
	v_fmamk_f32 v157, v157, 0x3e0293ee, v208
	v_fmamk_f32 v158, v158, 0x3e0293ee, v208
	v_fmamk_f32 v159, v159, 0x3e0293ee, v208
	v_exp_f32_e32 v156, v156
	v_exp_f32_e32 v157, v157
	v_exp_f32_e32 v158, v158
	v_exp_f32_e32 v159, v159
	v_add_f32_e32 v250, v152, v250
	v_add_f32_e32 v250, v153, v250
	v_add_f32_e32 v250, v154, v250
	v_add_f32_e32 v250, v155, v250
	v_cvt_pk_bf16_f32 v230, v144, v145
	v_cvt_pk_bf16_f32 v231, v146, v147
	v_cvt_pk_bf16_f32 v232, v148, v149
	v_cvt_pk_bf16_f32 v233, v150, v151
	s_waitcnt lgkmcnt(0)
	v_mfma_f32_32x32x16_bf16 v[128:143], v[238:241], v[164:167], v[128:143]
	v_mfma_f32_32x32x16_bf16 v[128:143], v[242:245], v[160:163], v[128:143]
	s_waitcnt vmcnt(0)
	s_barrier
; #define SBAR() __builtin_amdgcn_sched_barrier(0)
; #define PVR(S, DA, DB, vbase) do { S[0] = tr_read<v_rd_off(DA, 0, 0)>(vbase); S[1] = tr_read<v_rd_off(DA, 0, 1)>(vbase); S[2] = tr_read<v_rd_off(DB, 0, 0)>(vbase); S[3] = tr_read<v_rd_off(DB, 0, 1)>(vbase); \
;     S[4] = tr_read<v_rd_off(DA, 1, 0)>(vbase); S[5] = tr_read<v_rd_off(DA, 1, 1)>(vbase); S[6] = tr_read<v_rd_off(DB, 1, 0)>(vbase); S[7] = tr_read<v_rd_off(DB, 1, 1)>(vbase); } while (0)
; #define RAWBAR() do { asm volatile("s_waitcnt lgkmcnt(0)" ::: "memory"); __builtin_amdgcn_s_barrier(); asm volatile("" ::: "memory"); } while (0)
; #define RAWBAR() do { asm volatile("s_waitcnt lgkmcnt(0)" ::: "memory"); __builtin_amdgcn_s_barrier(); asm volatile("" ::: "memory"); } while (0)
; #define RAWBAR() do { asm volatile("s_waitcnt lgkmcnt(0)" ::: "memory"); __builtin_amdgcn_s_barrier(); asm volatile("" ::: "memory"); } while (0)
; #define RAWBAR() do { asm volatile("s_waitcnt lgkmcnt(0)" ::: "memory"); __builtin_amdgcn_s_barrier(); asm volatile("" ::: "memory"); } while (0)
; #define RAWBAR() do { asm volatile("s_waitcnt lgkmcnt(0)" ::: "memory"); __builtin_amdgcn_s_barrier(); asm volatile("" ::: "memory"); } while (0)
; template <int MODE> ...
;     ...
;   for (int j = 0; j < NT; ++j) {
;     const int buf = j & 1;
;     if (j + 1 < NT) { STAGE((j + 1) * KVBLK, buf ^ 1); }
;     const char* Kb = K_lds + buf * 16384;
;     f32x16 pe = {}, po = {};
; #pragma unroll
;     for (int d0 = 0; d0 < 8; d0 += 2) {
;       const bf16x8 k0 = *reinterpret_cast<const bf16x8*>(Kb + KSWZ(krow, (d0 * 16 + hi * 8) * 2));
;       const bf16x8 k1 = *reinterpret_cast<const bf16x8*>(Kb + KSWZ(krow, ((d0 + 1) * 16 + hi * 8) * 2));
;       pe = __builtin_amdgcn_mfma_f32_32x32x16_bf16(k0, qr[d0], pe, 0, 0, 0);
;       po = __builtin_amdgcn_mfma_f32_32x32x16_bf16(k1, qr[d0 + 1], po, 0, 0, 0); }
;     const int vo = vb0 + buf * 32768;
;     s16x4 R0_[8], R1_[8];
;     PVR(R0_, 0, 1, vo);
;     f32x16 p;
; #pragma unroll
;     for (int r = 0; r < 16; ++r) p[r] = __builtin_amdgcn_exp2f(fmaf(pe[r] + po[r], C, negMc));
;     float ps = 0.f;
; #pragma unroll
;     for (int r = 0; r < 16; ++r) ps += p[r];
;     lsum += ps;
;     const bf16x8 own0 = pk8(p, 0), own1 = pk8(p, 8);
;     SBAR();
;     PV_TAIL4(o, vo, vo + 16384, own0, own1);
;     asm volatile("s_waitcnt vmcnt(0)" ::: "memory");
;     RAWBAR();
;   }
	v_lshl_add_u64 v[200:201], v[200:201], 0, s[16:17]
	v_lshl_add_u64 v[202:203], v[202:203], 0, s[16:17]
	v_lshl_add_u64 v[204:205], v[204:205], 0, s[18:19]
	v_lshl_add_u64 v[206:207], v[206:207], 0, s[18:19]
	v_lshl_add_u64 v[144:145], v[204:205], 0, s[26:27]
	s_add_i32 m0, s34, 0x4000
	v_lshl_add_u64 v[146:147], v[206:207], 0, s[26:27]
	global_load_lds_dwordx4 v[144:145], off
	s_add_i32 m0, s34, 0x6000
	s_nop 0
	global_load_lds_dwordx4 v[146:147], off
	v_add_u32_e32 v249, s84, v218
	ds_read_b64_tr_b16 v[238:239], v249 offset:0
	ds_read_b64_tr_b16 v[240:241], v249 offset:2048
	ds_read_b64_tr_b16 v[242:243], v249 offset:512
	ds_read_b64_tr_b16 v[244:245], v249 offset:2560
	v_permlane32_swap_b32_e32 v230, v232
	v_permlane32_swap_b32_e32 v231, v233
	ds_read_b64_tr_b16 v[144:145], v249 offset:4096
	ds_read_b64_tr_b16 v[146:147], v249 offset:6144
	ds_read_b64_tr_b16 v[148:149], v249 offset:4608
	ds_read_b64_tr_b16 v[150:151], v249 offset:6656
	v_add_f32_e32 v250, v156, v250
	v_add_f32_e32 v250, v157, v250
	v_add_f32_e32 v250, v158, v250
	v_add_f32_e32 v250, v159, v250
	v_cvt_pk_bf16_f32 v234, v152, v153
	v_cvt_pk_bf16_f32 v235, v154, v155
	v_cvt_pk_bf16_f32 v236, v156, v157
	v_cvt_pk_bf16_f32 v237, v158, v159
	v_add_f32_e32 v219, v219, v250
	ds_read_b64_tr_b16 v[152:153], v249 offset:1024
	ds_read_b64_tr_b16 v[154:155], v249 offset:3072
	ds_read_b64_tr_b16 v[156:157], v249 offset:1536
	ds_read_b64_tr_b16 v[158:159], v249 offset:3584
	v_permlane32_swap_b32_e32 v234, v236
	v_permlane32_swap_b32_e32 v235, v237
	s_waitcnt lgkmcnt(8)
	v_mfma_f32_32x32x16_bf16 v[112:127], v[230:233], v[238:241], v[112:127]
	v_mfma_f32_32x32x16_bf16 v[96:111], v[230:233], v[242:245], v[96:111]
	ds_read_b64_tr_b16 v[238:239], v249 offset:5120
	ds_read_b64_tr_b16 v[240:241], v249 offset:7168
	ds_read_b64_tr_b16 v[242:243], v249 offset:5632
	ds_read_b64_tr_b16 v[244:245], v249 offset:7680
	v_lshl_add_u64 v[246:247], v[200:201], 0, s[26:27]
	s_add_i32 s30, s86, s34
	s_add_i32 m0, s30, 0x8000
	v_lshl_add_u64 v[246:247], v[246:247], 0, s[12:13]
	global_load_lds_dwordx4 v[246:247], off
	s_waitcnt lgkmcnt(8)
	v_mfma_f32_32x32x16_bf16 v[112:127], v[234:237], v[144:147], v[112:127]
	v_mfma_f32_32x32x16_bf16 v[96:111], v[234:237], v[148:151], v[96:111]
	ds_read_b64_tr_b16 v[144:145], v249 offset:16384
	ds_read_b64_tr_b16 v[146:147], v249 offset:18432
	ds_read_b64_tr_b16 v[148:149], v249 offset:16896
	ds_read_b64_tr_b16 v[150:151], v249 offset:18944
	v_lshl_add_u64 v[246:247], v[202:203], 0, s[26:27]
	s_add_i32 s30, s86, s34
	s_add_i32 m0, s30, 0xa000
	v_lshl_add_u64 v[246:247], v[246:247], 0, s[12:13]
	global_load_lds_dwordx4 v[246:247], off
	s_waitcnt lgkmcnt(8)
	v_mfma_f32_32x32x16_bf16 v[80:95], v[230:233], v[152:155], v[80:95]
	v_mfma_f32_32x32x16_bf16 v[64:79], v[230:233], v[156:159], v[64:79]
	ds_read_b64_tr_b16 v[152:153], v249 offset:20480
	ds_read_b64_tr_b16 v[154:155], v249 offset:22528
	ds_read_b64_tr_b16 v[156:157], v249 offset:20992
	ds_read_b64_tr_b16 v[158:159], v249 offset:23040
	v_lshl_add_u64 v[246:247], v[200:201], 0, s[26:27]
	s_add_i32 s30, s86, s34
	s_add_i32 m0, s30, 0xc000
	v_lshl_add_u64 v[246:247], v[246:247], 0, s[14:15]
	global_load_lds_dwordx4 v[246:247], off
	s_waitcnt lgkmcnt(8)
	v_mfma_f32_32x32x16_bf16 v[80:95], v[234:237], v[238:241], v[80:95]
	v_mfma_f32_32x32x16_bf16 v[64:79], v[234:237], v[242:245], v[64:79]
	ds_read_b64_tr_b16 v[238:239], v249 offset:17408
	ds_read_b64_tr_b16 v[240:241], v249 offset:19456
	ds_read_b64_tr_b16 v[242:243], v249 offset:17920
	ds_read_b64_tr_b16 v[244:245], v249 offset:19968
	v_lshl_add_u64 v[246:247], v[202:203], 0, s[26:27]
	s_add_i32 s30, s86, s34
	s_add_i32 m0, s30, 0xe000
	v_lshl_add_u64 v[246:247], v[246:247], 0, s[14:15]
	global_load_lds_dwordx4 v[246:247], off
	s_waitcnt lgkmcnt(8)
	v_mfma_f32_32x32x16_bf16 v[32:47], v[230:233], v[144:147], v[32:47]
	v_mfma_f32_32x32x16_bf16 v[16:31], v[230:233], v[148:151], v[16:31]
	ds_read_b64_tr_b16 v[144:145], v249 offset:21504
	ds_read_b64_tr_b16 v[146:147], v249 offset:23552
	ds_read_b64_tr_b16 v[148:149], v249 offset:22016
	ds_read_b64_tr_b16 v[150:151], v249 offset:24064
	s_waitcnt lgkmcnt(8)
	v_mfma_f32_32x32x16_bf16 v[32:47], v[234:237], v[152:155], v[32:47]
	v_mfma_f32_32x32x16_bf16 v[16:31], v[234:237], v[156:159], v[16:31]
	s_waitcnt lgkmcnt(0)
	v_mfma_f32_32x32x16_bf16 v[48:63], v[230:233], v[238:241], v[48:63]
	v_mfma_f32_32x32x16_bf16 v[0:15], v[230:233], v[242:245], v[0:15]
	v_mfma_f32_32x32x16_bf16 v[48:63], v[234:237], v[144:147], v[48:63]
	v_mfma_f32_32x32x16_bf16 v[0:15], v[234:237], v[148:151], v[0:15]
	s_mov_b32 s87, s84
	s_mov_b32 s84, s85
	s_mov_b32 s85, s86
	s_mov_b32 s86, s87
	v_add_u32_e32 v247, v220, v229
	v_add_u32_e32 v248, v220, v228
	ds_read_b128 v[230:233], v247
	ds_read_b128 v[234:237], v248
	v_add_u32_e32 v247, v220, v227
	v_add_u32_e32 v248, v220, v226
	ds_read_b128 v[238:241], v247
	ds_read_b128 v[242:245], v248
	v_fmamk_f32 v128, v128, 0x3e0293ee, v208
	v_fmamk_f32 v129, v129, 0x3e0293ee, v208
	v_fmamk_f32 v130, v130, 0x3e0293ee, v208
	v_fmamk_f32 v131, v131, 0x3e0293ee, v208
	v_exp_f32_e32 v128, v128
	v_exp_f32_e32 v129, v129
	v_exp_f32_e32 v130, v130
	v_exp_f32_e32 v131, v131
	s_waitcnt lgkmcnt(2)
	v_mfma_f32_32x32x16_bf16 v[144:159], v[230:233], v[188:191], 0
	v_mfma_f32_32x32x16_bf16 v[144:159], v[234:237], v[184:187], v[144:159]
	v_add_u32_e32 v247, v220, v225
	v_add_u32_e32 v248, v220, v223
	ds_read_b128 v[230:233], v247
	ds_read_b128 v[234:237], v248
	v_fmamk_f32 v132, v132, 0x3e0293ee, v208
	v_fmamk_f32 v133, v133, 0x3e0293ee, v208
	v_fmamk_f32 v134, v134, 0x3e0293ee, v208
	v_fmamk_f32 v135, v135, 0x3e0293ee, v208
	v_exp_f32_e32 v132, v132
	v_exp_f32_e32 v133, v133
	v_exp_f32_e32 v134, v134
	v_exp_f32_e32 v135, v135
	v_add_f32_e32 v250, v128, v129
	v_add_f32_e32 v250, v130, v250
	v_add_f32_e32 v250, v131, v250
	s_waitcnt lgkmcnt(2)
; #define SBAR() __builtin_amdgcn_sched_barrier(0)
; #define PVR(S, DA, DB, vbase) do { S[0] = tr_read<v_rd_off(DA, 0, 0)>(vbase); S[1] = tr_read<v_rd_off(DA, 0, 1)>(vbase); S[2] = tr_read<v_rd_off(DB, 0, 0)>(vbase); S[3] = tr_read<v_rd_off(DB, 0, 1)>(vbase); \
;     S[4] = tr_read<v_rd_off(DA, 1, 0)>(vbase); S[5] = tr_read<v_rd_off(DA, 1, 1)>(vbase); S[6] = tr_read<v_rd_off(DB, 1, 0)>(vbase); S[7] = tr_read<v_rd_off(DB, 1, 1)>(vbase); } while (0)
; #define RAWBAR() do { asm volatile("s_waitcnt lgkmcnt(0)" ::: "memory"); __builtin_amdgcn_s_barrier(); asm volatile("" ::: "memory"); } while (0)
; #define RAWBAR() do { asm volatile("s_waitcnt lgkmcnt(0)" ::: "memory"); __builtin_amdgcn_s_barrier(); asm volatile("" ::: "memory"); } while (0)
; #define RAWBAR() do { asm volatile("s_waitcnt lgkmcnt(0)" ::: "memory"); __builtin_amdgcn_s_barrier(); asm volatile("" ::: "memory"); } while (0)
; #define RAWBAR() do { asm volatile("s_waitcnt lgkmcnt(0)" ::: "memory"); __builtin_amdgcn_s_barrier(); asm volatile("" ::: "memory"); } while (0)
; #define RAWBAR() do { asm volatile("s_waitcnt lgkmcnt(0)" ::: "memory"); __builtin_amdgcn_s_barrier(); asm volatile("" ::: "memory"); } while (0)
; template <int MODE> ...
;     ...
;   for (int j = 0; j < NT; ++j) {
;     const int buf = j & 1;
;     if (j + 1 < NT) { STAGE((j + 1) * KVBLK, buf ^ 1); }
;     const char* Kb = K_lds + buf * 16384;
;     f32x16 pe = {}, po = {};
; #pragma unroll
;     for (int d0 = 0; d0 < 8; d0 += 2) {
;       const bf16x8 k0 = *reinterpret_cast<const bf16x8*>(Kb + KSWZ(krow, (d0 * 16 + hi * 8) * 2));
;       const bf16x8 k1 = *reinterpret_cast<const bf16x8*>(Kb + KSWZ(krow, ((d0 + 1) * 16 + hi * 8) * 2));
;       pe = __builtin_amdgcn_mfma_f32_32x32x16_bf16(k0, qr[d0], pe, 0, 0, 0);
;       po = __builtin_amdgcn_mfma_f32_32x32x16_bf16(k1, qr[d0 + 1], po, 0, 0, 0); }
;     const int vo = vb0 + buf * 32768;
;     s16x4 R0_[8], R1_[8];
;     PVR(R0_, 0, 1, vo);
;     f32x16 p;
; #pragma unroll
;     for (int r = 0; r < 16; ++r) p[r] = __builtin_amdgcn_exp2f(fmaf(pe[r] + po[r], C, negMc));
;     float ps = 0.f;
; #pragma unroll
;     for (int r = 0; r < 16; ++r) ps += p[r];
;     lsum += ps;
;     const bf16x8 own0 = pk8(p, 0), own1 = pk8(p, 8);
;     SBAR();
;     PV_TAIL4(o, vo, vo + 16384, own0, own1);
;     asm volatile("s_waitcnt vmcnt(0)" ::: "memory");
;     RAWBAR();
;   }
	v_mfma_f32_32x32x16_bf16 v[144:159], v[238:241], v[180:183], v[144:159]
	v_mfma_f32_32x32x16_bf16 v[144:159], v[242:245], v[176:179], v[144:159]
	v_add_u32_e32 v247, v220, v222
	v_add_u32_e32 v248, v220, v221
	ds_read_b128 v[238:241], v247
	ds_read_b128 v[242:245], v248
	v_fmamk_f32 v136, v136, 0x3e0293ee, v208
	v_fmamk_f32 v137, v137, 0x3e0293ee, v208
	v_fmamk_f32 v138, v138, 0x3e0293ee, v208
	v_fmamk_f32 v139, v139, 0x3e0293ee, v208
	v_exp_f32_e32 v136, v136
	v_exp_f32_e32 v137, v137
	v_exp_f32_e32 v138, v138
	v_exp_f32_e32 v139, v139
	v_add_f32_e32 v250, v132, v250
	v_add_f32_e32 v250, v133, v250
	v_add_f32_e32 v250, v134, v250
	v_add_f32_e32 v250, v135, v250
	s_waitcnt lgkmcnt(2)
	v_mfma_f32_32x32x16_bf16 v[144:159], v[230:233], v[172:175], v[144:159]
	v_mfma_f32_32x32x16_bf16 v[144:159], v[234:237], v[168:171], v[144:159]
	v_fmamk_f32 v140, v140, 0x3e0293ee, v208
	v_fmamk_f32 v141, v141, 0x3e0293ee, v208
	v_fmamk_f32 v142, v142, 0x3e0293ee, v208
	v_fmamk_f32 v143, v143, 0x3e0293ee, v208
	v_exp_f32_e32 v140, v140
	v_exp_f32_e32 v141, v141
	v_exp_f32_e32 v142, v142
	v_exp_f32_e32 v143, v143
	v_add_f32_e32 v250, v136, v250
	v_add_f32_e32 v250, v137, v250
	v_add_f32_e32 v250, v138, v250
	v_add_f32_e32 v250, v139, v250
	v_cvt_pk_bf16_f32 v230, v128, v129
	v_cvt_pk_bf16_f32 v231, v130, v131
	v_cvt_pk_bf16_f32 v232, v132, v133
	v_cvt_pk_bf16_f32 v233, v134, v135
	s_waitcnt lgkmcnt(0)
	v_mfma_f32_32x32x16_bf16 v[144:159], v[238:241], v[164:167], v[144:159]
	v_mfma_f32_32x32x16_bf16 v[144:159], v[242:245], v[160:163], v[144:159]
	s_waitcnt vmcnt(0)
	s_barrier
	v_lshl_add_u64 v[200:201], v[200:201], 0, s[16:17]
	v_lshl_add_u64 v[202:203], v[202:203], 0, s[16:17]
	v_lshl_add_u64 v[204:205], v[204:205], 0, s[18:19]
	v_lshl_add_u64 v[206:207], v[206:207], 0, s[18:19]
	v_lshl_add_u64 v[128:129], v[204:205], 0, s[26:27]
	s_mov_b32 m0, s34
	v_lshl_add_u64 v[130:131], v[206:207], 0, s[26:27]
	global_load_lds_dwordx4 v[128:129], off
	s_add_i32 m0, s34, 0x2000
	s_nop 0
	global_load_lds_dwordx4 v[130:131], off
	v_add_u32_e32 v249, s84, v218
	ds_read_b64_tr_b16 v[238:239], v249 offset:0
	ds_read_b64_tr_b16 v[240:241], v249 offset:2048
	ds_read_b64_tr_b16 v[242:243], v249 offset:512
	ds_read_b64_tr_b16 v[244:245], v249 offset:2560
	v_permlane32_swap_b32_e32 v230, v232
	v_permlane32_swap_b32_e32 v231, v233
	ds_read_b64_tr_b16 v[128:129], v249 offset:4096
	ds_read_b64_tr_b16 v[130:131], v249 offset:6144
	ds_read_b64_tr_b16 v[132:133], v249 offset:4608
	ds_read_b64_tr_b16 v[134:135], v249 offset:6656
	v_add_f32_e32 v250, v140, v250
	v_add_f32_e32 v250, v141, v250
	v_add_f32_e32 v250, v142, v250
	v_add_f32_e32 v250, v143, v250
	v_cvt_pk_bf16_f32 v234, v136, v137
	v_cvt_pk_bf16_f32 v235, v138, v139
	v_cvt_pk_bf16_f32 v236, v140, v141
	v_cvt_pk_bf16_f32 v237, v142, v143
	v_add_f32_e32 v219, v219, v250
	ds_read_b64_tr_b16 v[136:137], v249 offset:1024
	ds_read_b64_tr_b16 v[138:139], v249 offset:3072
	ds_read_b64_tr_b16 v[140:141], v249 offset:1536
	ds_read_b64_tr_b16 v[142:143], v249 offset:3584
	v_permlane32_swap_b32_e32 v234, v236
	v_permlane32_swap_b32_e32 v235, v237
	s_waitcnt lgkmcnt(8)
	v_mfma_f32_32x32x16_bf16 v[112:127], v[230:233], v[238:241], v[112:127]
	v_mfma_f32_32x32x16_bf16 v[96:111], v[230:233], v[242:245], v[96:111]
	ds_read_b64_tr_b16 v[238:239], v249 offset:5120
	ds_read_b64_tr_b16 v[240:241], v249 offset:7168
	ds_read_b64_tr_b16 v[242:243], v249 offset:5632
	ds_read_b64_tr_b16 v[244:245], v249 offset:7680
	v_lshl_add_u64 v[246:247], v[200:201], 0, s[26:27]
	s_add_i32 s30, s86, s34
	s_add_i32 m0, s30, 0x8000
	v_lshl_add_u64 v[246:247], v[246:247], 0, s[12:13]
	global_load_lds_dwordx4 v[246:247], off
	s_waitcnt lgkmcnt(8)
	v_mfma_f32_32x32x16_bf16 v[112:127], v[234:237], v[128:131], v[112:127]
	v_mfma_f32_32x32x16_bf16 v[96:111], v[234:237], v[132:135], v[96:111]
	ds_read_b64_tr_b16 v[128:129], v249 offset:16384
	ds_read_b64_tr_b16 v[130:131], v249 offset:18432
	ds_read_b64_tr_b16 v[132:133], v249 offset:16896
	ds_read_b64_tr_b16 v[134:135], v249 offset:18944
	v_lshl_add_u64 v[246:247], v[202:203], 0, s[26:27]
	s_add_i32 s30, s86, s34
	s_add_i32 m0, s30, 0xa000
	v_lshl_add_u64 v[246:247], v[246:247], 0, s[12:13]
	global_load_lds_dwordx4 v[246:247], off
	s_waitcnt lgkmcnt(8)
	v_mfma_f32_32x32x16_bf16 v[80:95], v[230:233], v[136:139], v[80:95]
	v_mfma_f32_32x32x16_bf16 v[64:79], v[230:233], v[140:143], v[64:79]
	ds_read_b64_tr_b16 v[136:137], v249 offset:20480
	ds_read_b64_tr_b16 v[138:139], v249 offset:22528
	ds_read_b64_tr_b16 v[140:141], v249 offset:20992
	ds_read_b64_tr_b16 v[142:143], v249 offset:23040
	v_lshl_add_u64 v[246:247], v[200:201], 0, s[26:27]
	s_add_i32 s30, s86, s34
	s_add_i32 m0, s30, 0xc000
	v_lshl_add_u64 v[246:247], v[246:247], 0, s[14:15]
	global_load_lds_dwordx4 v[246:247], off
	s_waitcnt lgkmcnt(8)
	v_mfma_f32_32x32x16_bf16 v[80:95], v[234:237], v[238:241], v[80:95]
	v_mfma_f32_32x32x16_bf16 v[64:79], v[234:237], v[242:245], v[64:79]
	ds_read_b64_tr_b16 v[238:239], v249 offset:17408
	ds_read_b64_tr_b16 v[240:241], v249 offset:19456
	ds_read_b64_tr_b16 v[242:243], v249 offset:17920
	ds_read_b64_tr_b16 v[244:245], v249 offset:19968
	v_lshl_add_u64 v[246:247], v[202:203], 0, s[26:27]
	s_add_i32 s30, s86, s34
	s_add_i32 m0, s30, 0xe000
	v_lshl_add_u64 v[246:247], v[246:247], 0, s[14:15]
	global_load_lds_dwordx4 v[246:247], off
	s_waitcnt lgkmcnt(8)
	v_mfma_f32_32x32x16_bf16 v[32:47], v[230:233], v[128:131], v[32:47]
	v_mfma_f32_32x32x16_bf16 v[16:31], v[230:233], v[132:135], v[16:31]
	ds_read_b64_tr_b16 v[128:129], v249 offset:21504
	ds_read_b64_tr_b16 v[130:131], v249 offset:23552
	ds_read_b64_tr_b16 v[132:133], v249 offset:22016
	ds_read_b64_tr_b16 v[134:135], v249 offset:24064
	s_waitcnt lgkmcnt(8)
	v_mfma_f32_32x32x16_bf16 v[32:47], v[234:237], v[136:139], v[32:47]
	v_mfma_f32_32x32x16_bf16 v[16:31], v[234:237], v[140:143], v[16:31]
	s_waitcnt lgkmcnt(0)
	v_mfma_f32_32x32x16_bf16 v[48:63], v[230:233], v[238:241], v[48:63]
	v_mfma_f32_32x32x16_bf16 v[0:15], v[230:233], v[242:245], v[0:15]
	v_mfma_f32_32x32x16_bf16 v[48:63], v[234:237], v[128:131], v[48:63]
	v_mfma_f32_32x32x16_bf16 v[0:15], v[234:237], v[132:135], v[0:15]
	s_mov_b32 s87, s84
	s_mov_b32 s84, s85
	s_mov_b32 s85, s86
	s_mov_b32 s86, s87
	s_add_i32 s40, s40, 1
	s_cmpk_eq_i32 s40, 0x82
	s_cbranch_scc0 .LattnB_m1
	s_waitcnt vmcnt(0)
	s_barrier
; #define XS_WRITE(OV, BASE) do { float* xs_ = (float*)(lds + (BASE)) + ((g * 4) * 64 + lane) * 16; \
;     _Pragma("unroll") for (int d0 = 0; d0 < 4; ++d0) { float* xp = xs_ + d0 * 64 * 16; \
;       _Pragma("unroll") for (int q4 = 0; q4 < 4; ++q4) *(f32x4v*)(xp + 4 * q4) = (f32x4v){OV[d0][4 * q4], OV[d0][4 * q4 + 1], OV[d0][4 * q4 + 2], OV[d0][4 * q4 + 3]}; } } while (0)
; #define XS_WRITE(OV, BASE) do { float* xs_ = (float*)(lds + (BASE)) + ((g * 4) * 64 + lane) * 16; \
;     _Pragma("unroll") for (int d0 = 0; d0 < 4; ++d0) { float* xp = xs_ + d0 * 64 * 16; \
;       _Pragma("unroll") for (int q4 = 0; q4 < 4; ++q4) *(f32x4v*)(xp + 4 * q4) = (f32x4v){OV[d0][4 * q4], OV[d0][4 * q4 + 1], OV[d0][4 * q4 + 2], OV[d0][4 * q4 + 3]}; } } while (0)
; template <int MODE> ...
;     ...
;   __builtin_amdgcn_s_setprio(0);
;   L_lds[(wid * 2 + hi) * 32 + r32] = lsum;
;     ...
;   f32x16* olo = o; f32x16* ohi = o + 4;
;   if (kh) { XS_WRITE(olo, 0); } else { XS_WRITE(ohi, 65536); }
;   __syncthreads();
;   if (kh) { XS_ADD(ohi, 65536);
; #pragma unroll
;     for (int d0 = 0; d0 < 4; ++d0) o[d0] = o[4 + d0]; }
;   else { XS_ADD(olo, 0); }
.Lattn_join_m1:
	v_mov_b32_e32 v172, v219
	s_setprio 0
	v_lshl_add_u32 v128, v194, 2, 0
	v_add_u32_e32 v128, 0x20000, v128
	v_mov_b32_e32 v129, s65
	v_cmp_eq_u32_e32 vcc, 0, v216
	ds_write_b32 v128, v172
	v_lshlrev_b32_e32 v128, 14, v217
	v_cndmask_b32_e32 v131, 0, v129, vcc
	v_lshlrev_b32_e32 v130, 2, v197
	v_cndmask_b32_e32 v147, v115, v35, vcc
	v_cndmask_b32_e32 v146, v114, v34, vcc
	v_cndmask_b32_e32 v145, v113, v33, vcc
	v_cndmask_b32_e32 v144, v112, v32, vcc
	v_add3_u32 v131, v131, v128, v130
	v_cndmask_b32_e32 v135, v127, v47, vcc
	v_cndmask_b32_e32 v134, v126, v46, vcc
	v_cndmask_b32_e32 v133, v125, v45, vcc
	v_cndmask_b32_e32 v132, v124, v44, vcc
	v_cndmask_b32_e32 v139, v123, v43, vcc
	v_cndmask_b32_e32 v138, v122, v42, vcc
	v_cndmask_b32_e32 v137, v121, v41, vcc
	v_cndmask_b32_e32 v136, v120, v40, vcc
	v_cndmask_b32_e32 v143, v119, v39, vcc
	v_cndmask_b32_e32 v142, v118, v38, vcc
	v_cndmask_b32_e32 v141, v117, v37, vcc
	v_cndmask_b32_e32 v140, v116, v36, vcc
	v_cndmask_b32_e32 v151, v111, v31, vcc
	v_cndmask_b32_e32 v150, v110, v30, vcc
	v_cndmask_b32_e32 v149, v109, v29, vcc
	v_cndmask_b32_e32 v148, v108, v28, vcc
	v_cndmask_b32_e32 v155, v107, v27, vcc
	v_cndmask_b32_e32 v154, v106, v26, vcc
	v_cndmask_b32_e32 v153, v105, v25, vcc
	v_cndmask_b32_e32 v152, v104, v24, vcc
	v_cndmask_b32_e32 v159, v103, v23, vcc
	v_cndmask_b32_e32 v158, v102, v22, vcc
	v_cndmask_b32_e32 v157, v101, v21, vcc
	v_cndmask_b32_e32 v156, v100, v20, vcc
	v_cndmask_b32_e32 v163, v99, v19, vcc
	v_cndmask_b32_e32 v162, v98, v18, vcc
	v_cndmask_b32_e32 v161, v97, v17, vcc
	v_cndmask_b32_e32 v160, v96, v16, vcc
	v_cndmask_b32_e32 v167, v95, v63, vcc
	v_cndmask_b32_e32 v166, v94, v62, vcc
	v_cndmask_b32_e32 v165, v93, v61, vcc
	v_cndmask_b32_e32 v164, v92, v60, vcc
	v_cndmask_b32_e32 v171, v91, v59, vcc
	v_cndmask_b32_e32 v170, v90, v58, vcc
	v_cndmask_b32_e32 v169, v89, v57, vcc
	v_cndmask_b32_e32 v168, v88, v56, vcc
	v_cndmask_b32_e32 v175, v87, v55, vcc
	v_cndmask_b32_e32 v174, v86, v54, vcc
	v_cndmask_b32_e32 v173, v85, v53, vcc
	v_cndmask_b32_e32 v172, v84, v52, vcc
	v_cndmask_b32_e32 v179, v83, v51, vcc
	v_cndmask_b32_e32 v178, v82, v50, vcc
	v_cndmask_b32_e32 v177, v81, v49, vcc
	v_cndmask_b32_e32 v176, v80, v48, vcc
	v_cndmask_b32_e32 v183, v79, v15, vcc
	v_cndmask_b32_e32 v182, v78, v14, vcc
	v_cndmask_b32_e32 v181, v77, v13, vcc
	v_cndmask_b32_e32 v180, v76, v12, vcc
	v_cndmask_b32_e32 v187, v75, v11, vcc
	v_cndmask_b32_e32 v186, v74, v10, vcc
	v_cndmask_b32_e32 v185, v73, v9, vcc
	v_cndmask_b32_e32 v184, v72, v8, vcc
	v_cndmask_b32_e32 v191, v71, v7, vcc
	v_cndmask_b32_e32 v190, v70, v6, vcc
	v_cndmask_b32_e32 v189, v69, v5, vcc
	v_cndmask_b32_e32 v188, v68, v4, vcc
	v_cndmask_b32_e32 v203, v67, v3, vcc
	v_cndmask_b32_e32 v202, v66, v2, vcc
	v_cndmask_b32_e32 v201, v65, v1, vcc
	v_cndmask_b32_e32 v200, v64, v0, vcc
	ds_write_b128 v131, v[144:147]
	ds_write_b128 v131, v[140:143] offset:16
	ds_write_b128 v131, v[136:139] offset:32
	ds_write_b128 v131, v[132:135] offset:48
	ds_write_b128 v131, v[160:163] offset:4096
	ds_write_b128 v131, v[156:159] offset:4112
	ds_write_b128 v131, v[152:155] offset:4128
	ds_write_b128 v131, v[148:151] offset:4144
	ds_write_b128 v131, v[176:179] offset:8192
	ds_write_b128 v131, v[172:175] offset:8208
	ds_write_b128 v131, v[168:171] offset:8224
	ds_write_b128 v131, v[164:167] offset:8240
	ds_write_b128 v131, v[200:203] offset:12288
	ds_write_b128 v131, v[188:191] offset:12304
	ds_write_b128 v131, v[184:187] offset:12320
	ds_write_b128 v131, v[180:183] offset:12336
	s_waitcnt vmcnt(0) lgkmcnt(0)
	s_barrier
	s_and_saveexec_b64 s[26:27], vcc
	s_cbranch_execz .LBB0_1026
	v_mov_b64_e32 v[32:33], v[112:113]
	v_mov_b64_e32 v[16:17], v[96:97]
	v_mov_b64_e32 v[48:49], v[80:81]
	v_mov_b64_e32 v[0:1], v[64:65]
	v_mov_b32_e32 v129, 0
	v_mov_b64_e32 v[34:35], v[114:115]
	v_mov_b64_e32 v[36:37], v[116:117]
	v_mov_b64_e32 v[38:39], v[118:119]
	v_mov_b64_e32 v[40:41], v[120:121]
	v_mov_b64_e32 v[42:43], v[122:123]
	v_mov_b64_e32 v[44:45], v[124:125]
	v_mov_b64_e32 v[46:47], v[126:127]
	v_mov_b64_e32 v[18:19], v[98:99]
	v_mov_b64_e32 v[20:21], v[100:101]
	v_mov_b64_e32 v[22:23], v[102:103]
	v_mov_b64_e32 v[24:25], v[104:105]
	v_mov_b64_e32 v[26:27], v[106:107]
	v_mov_b64_e32 v[28:29], v[108:109]
	v_mov_b64_e32 v[30:31], v[110:111]
	v_mov_b64_e32 v[50:51], v[82:83]
	v_mov_b64_e32 v[52:53], v[84:85]
	v_mov_b64_e32 v[54:55], v[86:87]
	v_mov_b64_e32 v[56:57], v[88:89]
	v_mov_b64_e32 v[58:59], v[90:91]
	v_mov_b64_e32 v[60:61], v[92:93]
	v_mov_b64_e32 v[62:63], v[94:95]
	v_mov_b64_e32 v[2:3], v[66:67]
	v_mov_b64_e32 v[4:5], v[68:69]
	v_mov_b64_e32 v[6:7], v[70:71]
	v_mov_b64_e32 v[8:9], v[72:73]
	v_mov_b64_e32 v[10:11], v[74:75]
	v_mov_b64_e32 v[12:13], v[76:77]
	v_mov_b64_e32 v[14:15], v[78:79]
